# phase 3 (conformer conv + q/k prep): 702 v_pk_fma/mul_f32 split into scalar v_fma/v_mul (bit-identical), 502 op_sel hazard nops dropped; on top of v5
# speedup vs baseline: 1.0043x; 1.0034x over previous
; template <int PH>
; __device__ __forceinline__ void run_phase(const Args& args, LAS unsigned char* lds) {
;     ...
;                 for (int grp = gw; grp < MT / 4; grp += NGW) {
;                     const int row = grp * 4 + gq;
;                     const bool lat = row < ML; const int b = lat ? (row >> 11) : ((row - ML) >> 8); const int t = lat ? (row & 2047) : ((row - ML) & 255);
;                     const int Tpos = lat ? CTXL + t : t;
;                     float cs[8], sn[8];
; #pragma unroll
;                     for (int k = 0; k < 8; ++k) { cs[k] = 1.f; sn[k] = 0.f; }
;                     if (lat) { const int pos = l16 < 8 ? (t >> 6) : (t & 63); const f32x4* tp = (const f32x4*)((const float*)(ws + OFF_ROPE32) + (pos * 32 + 8 * (l16 & 3)) * 2);
; #pragma unroll
;                         for (int k2 = 0; k2 < 4; ++k2) { const f32x4 tv = tp[k2]; cs[2 * k2] = tv.x; sn[2 * k2] = tv.y; cs[2 * k2 + 1] = tv.z; sn[2 * k2 + 1] = tv.w; } }
;                     const bf16_t* zr = Zb + (size_t)row * INE + 2048 + 8 * l16;
;                     u32x4 raw[12];
; #pragma unroll
;                     for (int h = 0; h < 12; ++h) raw[h] = *(const u32x4*)(zr + h * 128);
; #pragma unroll
;                     for (int h = 0; h < 10; ++h) {
;                         float x[8] = {bflo(raw[h].x), bfhi(raw[h].x), bflo(raw[h].y), bfhi(raw[h].y), bflo(raw[h].z), bfhi(raw[h].z), bflo(raw[h].w), bfhi(raw[h].w)};
;                         float ss = 0.f;
; #pragma unroll
;                         for (int k = 0; k < 8; ++k) ss += x[k] * x[k];
;                         ss += __shfl_xor(ss, 1); ss += __shfl_xor(ss, 2); ss += __shfl_xor(ss, 4); ss += __shfl_xor(ss, 8);
;                         const float rs = 1.0f / sqrtf(ss * (1.0f / 128.0f) + NEPS);
;                         float o[8];
; #pragma unroll
;                         for (int k = 0; k < 8; ++k) { const float y = x[k] * rs * (h < 8 ? qgv[k] : kgv[k]); const float yo = __shfl_xor(y, 4);
;                             o[k] = first ? (y * cs[k] - yo * sn[k]) : (yo * sn[k] + y * cs[k]); if (h < 8) o[k] *= QS; }
.LBB0_293:
	s_or_b64 exec, exec, s[0:1]
	v_mov_b64_e32 v[30:31], s[6:7]
	v_mad_i64_i32 v[30:31], s[0:1], v32, s29, v[30:31]
	v_lshlrev_b32_e32 v68, 1, v66
	v_lshl_add_u64 v[30:31], v[30:31], 0, v[68:69]
	v_add_co_u32_e64 v34, s[0:1], s30, v30
	v_lshl_add_u64 v[80:81], v[30:31], 0, s[14:15]
	s_nop 0
	v_addc_co_u32_e64 v35, s[0:1], 0, v31, s[0:1]
	global_load_dwordx4 v[50:53], v[34:35], off
	global_load_dwordx4 v[46:49], v[80:81], off offset:256
	s_add_i32 s0, s26, 0xffffc000
	v_add_u32_e32 v30, 0x100, v33
	s_ashr_i32 s1, s24, 9
	v_and_b32_e32 v31, 0xff, v32
	v_ashrrev_i32_e32 v33, 31, v32
	s_lshr_b32 s0, s0, 8
	v_mov_b32_e32 v34, s1
	v_cndmask_b32_e32 v74, v31, v30, vcc
	v_lshlrev_b64 v[30:31], 11, v[32:33]
	v_mov_b32_e32 v32, s0
	v_lshl_add_u64 v[76:77], v[70:71], 0, v[30:31]
	v_cndmask_b32_e32 v89, v32, v34, vcc
	global_load_dwordx4 v[38:41], v[80:81], off offset:512
	global_load_dwordx4 v[62:65], v[80:81], off offset:768
	s_waitcnt lgkmcnt(0)
	global_load_dwordx4 v[54:57], v[80:81], off offset:1024
	global_load_dwordx4 v[42:45], v[80:81], off offset:1280
	global_load_dwordx4 v[34:37], v[80:81], off offset:1536
	global_load_dwordx4 v[30:33], v[80:81], off offset:2816
	s_add_i32 s24, s24, s25
	s_add_i32 s26, s26, s27
	s_cmpk_gt_i32 s24, 0x11ff
	s_waitcnt vmcnt(0)
	v_lshlrev_b32_e32 v94, 16, v50
	v_and_b32_e32 v95, 0xffff0000, v50
	v_lshlrev_b32_e32 v90, 16, v53
	v_and_b32_e32 v91, 0xffff0000, v53
	v_lshlrev_b32_e32 v92, 16, v52
	v_and_b32_e32 v93, 0xffff0000, v52
	v_lshlrev_b32_e32 v52, 16, v51
	v_and_b32_e32 v53, 0xffff0000, v51
	v_mul_f32_e32 v58, v94, v94
	v_mul_f32_e32 v59, v95, v95
	v_mul_f32_e32 v50, v52, v52
	v_mul_f32_e32 v51, v53, v53
	v_add_f32_e32 v58, v58, v59
	v_add_f32_e32 v50, v50, v58
	v_lshlrev_b32_e32 v96, 16, v49
	v_and_b32_e32 v97, 0xffff0000, v49
	v_lshlrev_b32_e32 v98, 16, v48
	v_and_b32_e32 v99, 0xffff0000, v48
	v_mul_f32_e32 v48, v92, v92
	v_mul_f32_e32 v49, v93, v93
	v_add_f32_e32 v50, v51, v50
	v_add_f32_e32 v48, v48, v50
	v_lshlrev_b32_e32 v100, 16, v47
	v_and_b32_e32 v101, 0xffff0000, v47
	v_lshlrev_b32_e32 v102, 16, v46
	v_and_b32_e32 v103, 0xffff0000, v46
	v_mul_f32_e32 v46, v90, v90
	v_mul_f32_e32 v47, v91, v91
	v_add_f32_e32 v48, v49, v48
	v_add_f32_e32 v46, v46, v48
	v_mul_f32_e32 v106, v102, v102
	v_mul_f32_e32 v107, v103, v103
	v_add_f32_e32 v46, v47, v46
	v_mul_f32_e32 v104, v100, v100
	v_mul_f32_e32 v105, v101, v101
	v_add_f32_e32 v59, v106, v107
	ds_bpermute_b32 v47, v82, v46
	v_add_f32_e32 v58, v104, v59
	v_mul_f32_e32 v78, v98, v98
	v_mul_f32_e32 v79, v99, v99
	v_add_f32_e32 v51, v105, v58
	v_add_f32_e32 v50, v78, v51
	v_mul_f32_e32 v60, v96, v96
	v_mul_f32_e32 v61, v97, v97
	v_add_f32_e32 v48, v79, v50
	v_add_f32_e32 v48, v60, v48
	s_waitcnt lgkmcnt(0)
	v_add_f32_e32 v78, v46, v47
	v_add_f32_e32 v50, v61, v48
	ds_bpermute_b32 v79, v83, v78
	ds_bpermute_b32 v51, v82, v50
	global_load_dwordx4 v[58:61], v[80:81], off offset:1792
	global_load_dwordx4 v[46:49], v[80:81], off offset:2048
	s_waitcnt lgkmcnt(1)
	v_add_f32_e32 v78, v78, v79
	s_waitcnt lgkmcnt(0)
	v_add_f32_e32 v104, v50, v51
	ds_bpermute_b32 v79, v84, v78
	ds_bpermute_b32 v105, v83, v104
	v_mad_u64_u32 v[50:51], s[0:1], v89, s31, v[74:75]
	v_ashrrev_i32_e32 v51, 31, v50
	s_waitcnt lgkmcnt(1)
	v_add_f32_e32 v78, v78, v79
	s_waitcnt lgkmcnt(0)
	v_add_f32_e32 v104, v104, v105
	ds_bpermute_b32 v79, v85, v78
	ds_bpermute_b32 v105, v84, v104
	v_lshlrev_b64 v[50:51], 9, v[50:51]
	s_waitcnt lgkmcnt(1)
	v_add_f32_e32 v78, v78, v79
	s_waitcnt lgkmcnt(0)
	v_add_f32_e32 v104, v104, v105
	v_fmamk_f32 v78, v78, 0x3c000000, v87
	ds_bpermute_b32 v105, v85, v104
	v_mul_f32_e32 v79, 0x4f800000, v78
	v_cmp_gt_f32_e32 vcc, s34, v78
	s_nop 1
	v_cndmask_b32_e32 v106, v78, v79, vcc
	v_sqrt_f32_e32 v107, v106
	v_lshl_add_u64 v[78:79], s[84:85], 0, v[50:51]
	s_waitcnt lgkmcnt(0)
	v_add_f32_e32 v50, v104, v105
	v_fmamk_f32 v110, v50, 0x3c000000, v87
	v_add_u32_e32 v50, -1, v107
	v_add_u32_e32 v51, 1, v107
	v_fma_f32 v104, -v50, v107, v106
	v_fma_f32 v105, -v51, v107, v106
	v_cmp_ge_f32_e64 s[0:1], 0, v104
	v_mul_f32_e32 v111, 0x4f800000, v110
	s_nop 0
	v_cndmask_b32_e64 v50, v107, v50, s[0:1]
	v_cmp_lt_f32_e64 s[0:1], 0, v105
	s_nop 1
	v_cndmask_b32_e64 v50, v50, v51, s[0:1]
	v_mul_f32_e32 v51, 0x37800000, v50
	v_cndmask_b32_e32 v50, v50, v51, vcc
	v_cmp_class_f32_e32 vcc, v106, v88
	s_nop 1
	v_cndmask_b32_e32 v50, v50, v106, vcc
	v_div_scale_f32 v51, s[0:1], v50, v50, 1.0
	v_rcp_f32_e32 v104, v51
	v_div_scale_f32 v105, vcc, 1.0, v50, 1.0
	v_fma_f32 v106, -v51, v104, 1.0
	v_fmac_f32_e32 v104, v106, v104
	v_mul_f32_e32 v106, v105, v104
	v_fma_f32 v107, -v51, v106, v105
	v_fmac_f32_e32 v106, v107, v104
	v_fma_f32 v51, -v51, v106, v105
	v_div_fmas_f32 v51, v51, v104, v106
	v_div_fixup_f32 v50, v51, v50, 1.0
	v_pk_mul_f32 v[52:53], v[50:51], v[52:53] op_sel_hi:[0,1]
	v_mul_f32_e32 v52, v6, v52
	v_mul_f32_e32 v53, v7, v53
	ds_bpermute_b32 v104, v84, v52
	ds_bpermute_b32 v105, v84, v53
	v_pk_mul_f32 v[92:93], v[50:51], v[92:93] op_sel_hi:[0,1]
	v_mul_f32_e32 v92, v12, v92
	v_mul_f32_e32 v93, v13, v93
	ds_bpermute_b32 v106, v84, v92
	ds_bpermute_b32 v107, v84, v93
	s_waitcnt lgkmcnt(2)
	v_mul_f32_e32 v104, v22, v104
	v_mul_f32_e32 v105, v23, v105
	v_cmp_gt_f32_e32 vcc, s34, v110
	v_cndmask_b32_e64 v105, v105, -v105, s[2:3]
	v_cndmask_b32_e64 v104, v104, -v104, s[2:3]
	v_fma_f32 v52, v24, v52, v104
	v_fma_f32 v53, v25, v53, v105
	v_cndmask_b32_e32 v104, v110, v111, vcc
	v_sqrt_f32_e32 v105, v104
	s_waitcnt lgkmcnt(0)
; __device__ __forceinline__ unsigned cvtpk(float lo, float hi) { const f32x2 v = {lo, hi}; const hbf16x2_t b = __builtin_convertvector(v, hbf16x2_t); return __builtin_bit_cast(unsigned, b); }
; template <int PH>
; __device__ __forceinline__ void run_phase(const Args& args, LAS unsigned char* lds) {
;     ...
;                     for (int h = 0; h < 10; ++h) {
;                         float x[8] = {bflo(raw[h].x), bfhi(raw[h].x), bflo(raw[h].y), bfhi(raw[h].y), bflo(raw[h].z), bfhi(raw[h].z), bflo(raw[h].w), bfhi(raw[h].w)};
;                         float ss = 0.f;
; #pragma unroll
;                         for (int k = 0; k < 8; ++k) ss += x[k] * x[k];
;                         ss += __shfl_xor(ss, 1); ss += __shfl_xor(ss, 2); ss += __shfl_xor(ss, 4); ss += __shfl_xor(ss, 8);
;                         const float rs = 1.0f / sqrtf(ss * (1.0f / 128.0f) + NEPS);
;                         float o[8];
; #pragma unroll
;                         for (int k = 0; k < 8; ++k) { const float y = x[k] * rs * (h < 8 ? qgv[k] : kgv[k]); const float yo = __shfl_xor(y, 4);
;                             o[k] = first ? (y * cs[k] - yo * sn[k]) : (yo * sn[k] + y * cs[k]); if (h < 8) o[k] *= QS; }
;                         u32x4 w; w.x = cvtpk(o[0], o[1]); w.y = cvtpk(o[2], o[3]); w.z = cvtpk(o[4], o[5]); w.w = cvtpk(o[6], o[7]);
;                         if (h < 8) *(u32x4*)(Qb + (size_t)row * 1024 + h * 128 + 8 * l16) = w;
;                         else *(u32x4*)(Kb + (size_t)(b * TK + Tpos) * 256 + (h - 8) * 128 + 8 * l16) = w;
	v_mul_f32_e32 v106, v16, v106
	v_mul_f32_e32 v107, v17, v107
	v_pk_mul_f32 v[94:95], v[50:51], v[94:95] op_sel_hi:[0,1]
	v_cndmask_b32_e64 v107, v107, -v107, s[2:3]
	v_cndmask_b32_e64 v106, v106, -v106, s[2:3]
	v_fma_f32 v92, v20, v92, v106
	v_fma_f32 v93, v21, v93, v107
	v_add_u32_e32 v106, -1, v105
	v_fma_f32 v107, -v106, v105, v104
	v_cmp_ge_f32_e64 s[0:1], 0, v107
	v_add_u32_e32 v107, 1, v105
	v_pk_mul_f32 v[50:51], v[50:51], v[90:91] op_sel_hi:[0,1]
	v_mul_f32_e32 v90, v4, v94
	v_mul_f32_e32 v91, v5, v95
	v_cndmask_b32_e64 v106, v105, v106, s[0:1]
	v_fma_f32 v105, -v107, v105, v104
	ds_bpermute_b32 v94, v84, v90
	ds_bpermute_b32 v95, v84, v91
	v_cmp_lt_f32_e64 s[0:1], 0, v105
	v_mul_f32_e32 v50, v14, v50
	v_mul_f32_e32 v51, v15, v51
	ds_bpermute_b32 v108, v84, v50
	v_cndmask_b32_e64 v105, v106, v107, s[0:1]
	ds_bpermute_b32 v109, v84, v51
	v_mul_f32_e32 v106, 0x37800000, v105
	v_cndmask_b32_e32 v105, v105, v106, vcc
	v_cmp_class_f32_e32 vcc, v104, v88
	s_waitcnt lgkmcnt(2)
	v_mul_f32_e32 v94, v26, v94
	v_mul_f32_e32 v95, v27, v95
	v_pk_mul_f32 v[52:53], v[52:53], s[22:23] op_sel_hi:[1,0]
	v_cndmask_b32_e32 v104, v105, v104, vcc
	v_div_scale_f32 v105, s[0:1], v104, v104, 1.0
	v_cndmask_b32_e64 v95, v95, -v95, s[2:3]
	v_cndmask_b32_e64 v94, v94, -v94, s[2:3]
	v_rcp_f32_e32 v106, v105
	v_fma_f32 v90, v28, v90, v94
	v_fma_f32 v91, v29, v91, v95
	s_waitcnt lgkmcnt(0)
	v_mul_f32_e32 v94, v18, v108
	v_mul_f32_e32 v95, v19, v109
	v_pk_mul_f32 v[90:91], v[90:91], s[22:23] op_sel_hi:[1,0]
	v_cndmask_b32_e64 v95, v95, -v95, s[2:3]
	v_cndmask_b32_e64 v94, v94, -v94, s[2:3]
	v_fma_f32 v50, v72, v50, v94
	v_fma_f32 v51, v73, v51, v95
	v_pk_mul_f32 v[92:93], v[92:93], s[22:23] op_sel_hi:[1,0]
	v_pk_mul_f32 v[94:95], v[50:51], s[22:23] op_sel_hi:[1,0]
	v_fma_f32 v51, -v105, v106, 1.0
	v_fmac_f32_e32 v106, v51, v106
	v_div_scale_f32 v51, vcc, 1.0, v104, 1.0
	v_cvt_pk_bf16_f32 v50, v90, v91
	v_mul_f32_e32 v90, v51, v106
	v_fma_f32 v91, -v105, v90, v51
	v_fmac_f32_e32 v90, v91, v106
	v_fma_f32 v51, -v105, v90, v51
	v_div_fmas_f32 v51, v51, v106, v90
	v_div_fixup_f32 v90, v51, v104, 1.0
	v_pk_mul_f32 v[102:103], v[90:91], v[102:103] op_sel_hi:[0,1]
	v_mul_f32_e32 v102, v4, v102
	v_mul_f32_e32 v103, v5, v103
	ds_bpermute_b32 v104, v84, v102
	ds_bpermute_b32 v105, v84, v103
	v_cvt_pk_bf16_f32 v51, v52, v53
	v_cvt_pk_bf16_f32 v52, v92, v93
	v_cvt_pk_bf16_f32 v53, v94, v95
	v_lshlrev_b32_e32 v108, 16, v38
	v_and_b32_e32 v109, 0xffff0000, v38
	global_store_dwordx4 v[76:77], v[50:53], off
	v_pk_mul_f32 v[94:95], v[90:91], v[98:99] op_sel_hi:[0,1]
	v_lshlrev_b32_e32 v98, 16, v41
	s_waitcnt lgkmcnt(0)
	v_mul_f32_e32 v50, v26, v104
	v_mul_f32_e32 v51, v27, v105
	v_lshlrev_b32_e32 v104, 16, v39
	v_and_b32_e32 v105, 0xffff0000, v39
	v_mul_f32_e32 v38, v108, v108
	v_mul_f32_e32 v39, v109, v109
	v_cndmask_b32_e64 v51, v51, -v51, s[2:3]
	v_cndmask_b32_e64 v50, v50, -v50, s[2:3]
	v_mul_f32_e32 v106, v104, v104
	v_mul_f32_e32 v107, v105, v105
	v_add_f32_e32 v38, v38, v39
	v_fma_f32 v50, v28, v102, v50
	v_fma_f32 v51, v29, v103, v51
	v_lshlrev_b32_e32 v102, 16, v40
	v_and_b32_e32 v103, 0xffff0000, v40
	v_add_f32_e32 v38, v106, v38
	v_and_b32_e32 v99, 0xffff0000, v41
	v_mul_f32_e32 v40, v102, v102
	v_mul_f32_e32 v41, v103, v103
	v_add_f32_e32 v38, v107, v38
	v_add_f32_e32 v38, v40, v38
	v_pk_mul_f32 v[52:53], v[90:91], v[100:101] op_sel_hi:[0,1]
	v_mul_f32_e32 v100, v98, v98
	v_mul_f32_e32 v101, v99, v99
	v_add_f32_e32 v38, v41, v38
	v_mul_f32_e32 v52, v6, v52
	v_mul_f32_e32 v53, v7, v53
	v_add_f32_e32 v38, v100, v38
	ds_bpermute_b32 v92, v84, v52
	ds_bpermute_b32 v93, v84, v53
	v_add_f32_e32 v91, v101, v38
	ds_bpermute_b32 v100, v82, v91
	v_mul_f32_e32 v38, v12, v94
	v_mul_f32_e32 v39, v13, v95
	ds_bpermute_b32 v40, v84, v38
	s_waitcnt lgkmcnt(2)
	v_mul_f32_e32 v92, v22, v92
	v_mul_f32_e32 v93, v23, v93
	ds_bpermute_b32 v41, v84, v39
	v_cndmask_b32_e64 v93, v93, -v93, s[2:3]
	v_cndmask_b32_e64 v92, v92, -v92, s[2:3]
	s_waitcnt lgkmcnt(2)
	v_add_f32_e32 v91, v91, v100
	v_fma_f32 v52, v24, v52, v92
	v_fma_f32 v53, v25, v53, v93
	ds_bpermute_b32 v92, v83, v91
	s_waitcnt lgkmcnt(1)
	v_mul_f32_e32 v40, v16, v40
	v_mul_f32_e32 v41, v17, v41
	v_pk_mul_f32 v[50:51], v[50:51], s[22:23] op_sel_hi:[1,0]
	v_cndmask_b32_e64 v41, v41, -v41, s[2:3]
	v_cndmask_b32_e64 v40, v40, -v40, s[2:3]
	s_waitcnt lgkmcnt(0)
	v_add_f32_e32 v94, v91, v92
	ds_bpermute_b32 v95, v84, v94
	v_pk_mul_f32 v[90:91], v[90:91], v[96:97] op_sel_hi:[0,1]
	v_mul_f32_e32 v90, v14, v90
	v_mul_f32_e32 v91, v15, v91
	ds_bpermute_b32 v92, v84, v90
	ds_bpermute_b32 v93, v84, v91
	s_waitcnt lgkmcnt(2)
	v_add_f32_e32 v94, v94, v95
	ds_bpermute_b32 v95, v85, v94
	v_fma_f32 v38, v20, v38, v40
	v_fma_f32 v39, v21, v39, v41
	v_lshlrev_b32_e32 v110, 16, v62
	s_waitcnt lgkmcnt(1)
	v_mul_f32_e32 v40, v18, v92
	v_mul_f32_e32 v41, v19, v93
	v_pk_mul_f32 v[38:39], v[38:39], s[22:23] op_sel_hi:[1,0]
	s_waitcnt lgkmcnt(0)
; __device__ __forceinline__ unsigned cvtpk(float lo, float hi) { const f32x2 v = {lo, hi}; const hbf16x2_t b = __builtin_convertvector(v, hbf16x2_t); return __builtin_bit_cast(unsigned, b); }
; template <int PH>
; __device__ __forceinline__ void run_phase(const Args& args, LAS unsigned char* lds) {
;     ...
;                     for (int h = 0; h < 10; ++h) {
;                         float x[8] = {bflo(raw[h].x), bfhi(raw[h].x), bflo(raw[h].y), bfhi(raw[h].y), bflo(raw[h].z), bfhi(raw[h].z), bflo(raw[h].w), bfhi(raw[h].w)};
;                         float ss = 0.f;
; #pragma unroll
;                         for (int k = 0; k < 8; ++k) ss += x[k] * x[k];
;                         ss += __shfl_xor(ss, 1); ss += __shfl_xor(ss, 2); ss += __shfl_xor(ss, 4); ss += __shfl_xor(ss, 8);
;                         const float rs = 1.0f / sqrtf(ss * (1.0f / 128.0f) + NEPS);
;                         float o[8];
; #pragma unroll
;                         for (int k = 0; k < 8; ++k) { const float y = x[k] * rs * (h < 8 ? qgv[k] : kgv[k]); const float yo = __shfl_xor(y, 4);
;                             o[k] = first ? (y * cs[k] - yo * sn[k]) : (yo * sn[k] + y * cs[k]); if (h < 8) o[k] *= QS; }
;                         u32x4 w; w.x = cvtpk(o[0], o[1]); w.y = cvtpk(o[2], o[3]); w.z = cvtpk(o[4], o[5]); w.w = cvtpk(o[6], o[7]);
;                         if (h < 8) *(u32x4*)(Qb + (size_t)row * 1024 + h * 128 + 8 * l16) = w;
;                         else *(u32x4*)(Kb + (size_t)(b * TK + Tpos) * 256 + (h - 8) * 128 + 8 * l16) = w;
	v_add_f32_e32 v92, v94, v95
	v_fmamk_f32 v92, v92, 0x3c000000, v87
	v_mul_f32_e32 v93, 0x4f800000, v92
	v_cmp_gt_f32_e32 vcc, s34, v92
	v_cndmask_b32_e64 v41, v41, -v41, s[2:3]
	v_cndmask_b32_e64 v40, v40, -v40, s[2:3]
	v_cndmask_b32_e32 v92, v92, v93, vcc
	v_sqrt_f32_e32 v93, v92
	v_fma_f32 v40, v72, v90, v40
	v_fma_f32 v41, v73, v91, v41
	v_and_b32_e32 v111, 0xffff0000, v62
	v_pk_mul_f32 v[52:53], v[52:53], s[22:23] op_sel_hi:[1,0]
	v_add_u32_e32 v90, -1, v93
	v_fma_f32 v91, -v90, v93, v92
	v_cmp_ge_f32_e64 s[0:1], 0, v91
	v_add_u32_e32 v91, 1, v93
	v_pk_mul_f32 v[40:41], v[40:41], s[22:23] op_sel_hi:[1,0]
	v_cndmask_b32_e64 v90, v93, v90, s[0:1]
	v_fma_f32 v93, -v91, v93, v92
	v_cmp_lt_f32_e64 s[0:1], 0, v93
	v_lshlrev_b32_e32 v106, 16, v63
	v_and_b32_e32 v107, 0xffff0000, v63
	v_cndmask_b32_e64 v90, v90, v91, s[0:1]
	v_mul_f32_e32 v91, 0x37800000, v90
	v_cndmask_b32_e32 v90, v90, v91, vcc
	v_cmp_class_f32_e32 vcc, v92, v88
	v_mul_f32_e32 v62, v110, v110
	v_mul_f32_e32 v63, v111, v111
	v_cvt_pk_bf16_f32 v91, v52, v53
	v_cndmask_b32_e32 v93, v90, v92, vcc
	v_div_scale_f32 v94, s[0:1], v93, v93, 1.0
	v_rcp_f32_e32 v95, v94
	v_cvt_pk_bf16_f32 v92, v38, v39
	v_cvt_pk_bf16_f32 v90, v50, v51
	v_add_f32_e32 v62, v62, v63
	v_fma_f32 v38, -v94, v95, 1.0
	v_fmac_f32_e32 v95, v38, v95
	v_div_scale_f32 v38, vcc, 1.0, v93, 1.0
	v_mul_f32_e32 v39, v38, v95
	v_fma_f32 v50, -v94, v39, v38
	v_fmac_f32_e32 v39, v50, v95
	v_fma_f32 v38, -v94, v39, v38
	v_div_fmas_f32 v38, v38, v95, v39
	v_div_fixup_f32 v94, v38, v93, 1.0
	v_pk_mul_f32 v[38:39], v[94:95], v[108:109] op_sel_hi:[0,1]
	v_mul_f32_e32 v96, v4, v38
	v_mul_f32_e32 v97, v5, v39
	ds_bpermute_b32 v100, v84, v96
	ds_bpermute_b32 v101, v84, v97
	v_cvt_pk_bf16_f32 v93, v40, v41
	global_load_dwordx4 v[50:53], v[80:81], off offset:2304
	global_load_dwordx4 v[38:41], v[80:81], off offset:2560
	v_mul_f32_e32 v108, v106, v106
	v_mul_f32_e32 v109, v107, v107
	global_store_dwordx4 v[76:77], v[90:93], off offset:256
	s_waitcnt lgkmcnt(0)
	v_mul_f32_e32 v80, v26, v100
	v_mul_f32_e32 v81, v27, v101
	v_add_f32_e32 v62, v108, v62
	v_pk_mul_f32 v[90:91], v[94:95], v[104:105] op_sel_hi:[0,1]
	v_cndmask_b32_e64 v81, v81, -v81, s[2:3]
	v_cndmask_b32_e64 v80, v80, -v80, s[2:3]
	v_lshlrev_b32_e32 v104, 16, v64
	v_and_b32_e32 v105, 0xffff0000, v64
	v_fma_f32 v80, v28, v96, v80
	v_fma_f32 v81, v29, v97, v81
	v_lshlrev_b32_e32 v96, 16, v65
	v_and_b32_e32 v97, 0xffff0000, v65
	v_mul_f32_e32 v64, v104, v104
	v_mul_f32_e32 v65, v105, v105
	v_add_f32_e32 v62, v109, v62
	v_add_f32_e32 v62, v64, v62
	v_mul_f32_e32 v100, v96, v96
	v_mul_f32_e32 v101, v97, v97
	v_add_f32_e32 v62, v65, v62
	v_add_f32_e32 v62, v100, v62
	v_add_f32_e32 v95, v101, v62
	ds_bpermute_b32 v100, v82, v95
	v_mul_f32_e32 v90, v6, v90
	v_mul_f32_e32 v91, v7, v91
	ds_bpermute_b32 v92, v84, v90
	ds_bpermute_b32 v93, v84, v91
	v_pk_mul_f32 v[62:63], v[94:95], v[102:103] op_sel_hi:[0,1]
	s_waitcnt lgkmcnt(2)
	v_add_f32_e32 v95, v95, v100
	ds_bpermute_b32 v100, v83, v95
	v_mul_f32_e32 v62, v12, v62
	v_mul_f32_e32 v63, v13, v63
	s_waitcnt lgkmcnt(1)
	v_mul_f32_e32 v92, v22, v92
	v_mul_f32_e32 v93, v23, v93
	ds_bpermute_b32 v64, v84, v62
	v_cndmask_b32_e64 v93, v93, -v93, s[2:3]
	v_cndmask_b32_e64 v92, v92, -v92, s[2:3]
	v_fma_f32 v90, v24, v90, v92
	v_fma_f32 v91, v25, v91, v93
	s_waitcnt lgkmcnt(1)
	v_add_f32_e32 v92, v95, v100
	ds_bpermute_b32 v93, v84, v92
	ds_bpermute_b32 v65, v84, v63
	v_pk_mul_f32 v[80:81], v[80:81], s[22:23] op_sel_hi:[1,0]
	v_pk_mul_f32 v[90:91], v[90:91], s[22:23] op_sel_hi:[1,0]
	v_and_b32_e32 v101, 0xffff0000, v55
	s_waitcnt lgkmcnt(1)
	v_add_f32_e32 v95, v92, v93
	ds_bpermute_b32 v100, v85, v95
	s_waitcnt lgkmcnt(1)
	v_mul_f32_e32 v64, v16, v64
	v_mul_f32_e32 v65, v17, v65
	v_cndmask_b32_e64 v65, v65, -v65, s[2:3]
	v_cndmask_b32_e64 v64, v64, -v64, s[2:3]
	v_fma_f32 v62, v20, v62, v64
	v_fma_f32 v63, v21, v63, v65
	v_pk_mul_f32 v[64:65], v[62:63], s[22:23] op_sel_hi:[1,0]
	v_pk_mul_f32 v[62:63], v[94:95], v[98:99] op_sel_hi:[0,1]
	s_waitcnt lgkmcnt(0)
	v_add_f32_e32 v94, v95, v100
	v_fmamk_f32 v94, v94, 0x3c000000, v87
	v_mul_f32_e32 v95, 0x4f800000, v94
	v_cmp_gt_f32_e32 vcc, s34, v94
	v_mul_f32_e32 v62, v14, v62
	v_mul_f32_e32 v63, v15, v63
	ds_bpermute_b32 v92, v84, v62
	v_cndmask_b32_e32 v94, v94, v95, vcc
	v_sqrt_f32_e32 v95, v94
	ds_bpermute_b32 v93, v84, v63
	v_cvt_pk_bf16_f32 v64, v64, v65
	v_lshlrev_b32_e32 v100, 16, v55
	v_add_u32_e32 v98, -1, v95
	v_fma_f32 v99, -v98, v95, v94
	v_cmp_ge_f32_e64 s[0:1], 0, v99
	v_add_u32_e32 v99, 1, v95
	s_waitcnt lgkmcnt(0)
	v_mul_f32_e32 v92, v18, v92
	v_mul_f32_e32 v93, v19, v93
	v_cndmask_b32_e64 v98, v95, v98, s[0:1]
	v_fma_f32 v95, -v99, v95, v94
	v_cmp_lt_f32_e64 s[0:1], 0, v95
	v_cndmask_b32_e64 v93, v93, -v93, s[2:3]
	v_cndmask_b32_e64 v92, v92, -v92, s[2:3]
	v_cndmask_b32_e64 v95, v98, v99, s[0:1]
	v_mul_f32_e32 v98, 0x37800000, v95
	v_cndmask_b32_e32 v95, v95, v98, vcc
	v_cmp_class_f32_e32 vcc, v94, v88
	v_fma_f32 v62, v72, v62, v92
	v_fma_f32 v63, v73, v63, v93
	v_mul_f32_e32 v102, v100, v100
	v_mul_f32_e32 v103, v101, v101
	v_cndmask_b32_e32 v94, v95, v94, vcc
	v_div_scale_f32 v95, s[0:1], v94, v94, 1.0
	v_rcp_f32_e32 v98, v95
	v_pk_mul_f32 v[92:93], v[62:63], s[22:23] op_sel_hi:[1,0]
	v_cvt_pk_bf16_f32 v62, v80, v81
	v_cvt_pk_bf16_f32 v65, v92, v93
	v_fma_f32 v63, -v95, v98, 1.0
	v_fmac_f32_e32 v98, v63, v98
	v_div_scale_f32 v63, vcc, 1.0, v94, 1.0
	v_mul_f32_e32 v80, v63, v98
	v_fma_f32 v81, -v95, v80, v63
	v_fmac_f32_e32 v80, v81, v98
	v_fma_f32 v63, -v95, v80, v63
	v_div_fmas_f32 v63, v63, v98, v80
	v_div_fixup_f32 v80, v63, v94, 1.0
	v_pk_mul_f32 v[94:95], v[80:81], v[110:111] op_sel_hi:[0,1]
	v_mul_f32_e32 v94, v4, v94
	v_mul_f32_e32 v95, v5, v95
	ds_bpermute_b32 v98, v84, v94
	ds_bpermute_b32 v99, v84, v95
	v_cvt_pk_bf16_f32 v63, v90, v91
	global_store_dwordx4 v[76:77], v[62:65], off offset:512
	v_lshlrev_b32_e32 v92, 16, v57
	v_and_b32_e32 v93, 0xffff0000, v57
	v_pk_mul_f32 v[64:65], v[80:81], v[106:107] op_sel_hi:[0,1]
	v_lshlrev_b32_e32 v106, 16, v54
	v_and_b32_e32 v107, 0xffff0000, v54
	v_mul_f32_e32 v54, v106, v106
	v_mul_f32_e32 v55, v107, v107
	s_waitcnt lgkmcnt(0)
; __device__ __forceinline__ unsigned cvtpk(float lo, float hi) { const f32x2 v = {lo, hi}; const hbf16x2_t b = __builtin_convertvector(v, hbf16x2_t); return __builtin_bit_cast(unsigned, b); }
; template <int PH>
; __device__ __forceinline__ void run_phase(const Args& args, LAS unsigned char* lds) {
;     ...
;                     for (int h = 0; h < 10; ++h) {
;                         float x[8] = {bflo(raw[h].x), bfhi(raw[h].x), bflo(raw[h].y), bfhi(raw[h].y), bflo(raw[h].z), bfhi(raw[h].z), bflo(raw[h].w), bfhi(raw[h].w)};
;                         float ss = 0.f;
; #pragma unroll
;                         for (int k = 0; k < 8; ++k) ss += x[k] * x[k];
;                         ss += __shfl_xor(ss, 1); ss += __shfl_xor(ss, 2); ss += __shfl_xor(ss, 4); ss += __shfl_xor(ss, 8);
;                         const float rs = 1.0f / sqrtf(ss * (1.0f / 128.0f) + NEPS);
;                         float o[8];
; #pragma unroll
;                         for (int k = 0; k < 8; ++k) { const float y = x[k] * rs * (h < 8 ? qgv[k] : kgv[k]); const float yo = __shfl_xor(y, 4);
;                             o[k] = first ? (y * cs[k] - yo * sn[k]) : (yo * sn[k] + y * cs[k]); if (h < 8) o[k] *= QS; }
;                         u32x4 w; w.x = cvtpk(o[0], o[1]); w.y = cvtpk(o[2], o[3]); w.z = cvtpk(o[4], o[5]); w.w = cvtpk(o[6], o[7]);
;                         if (h < 8) *(u32x4*)(Qb + (size_t)row * 1024 + h * 128 + 8 * l16) = w;
;                         else *(u32x4*)(Kb + (size_t)(b * TK + Tpos) * 256 + (h - 8) * 128 + 8 * l16) = w;
	v_mul_f32_e32 v62, v26, v98
	v_mul_f32_e32 v63, v27, v99
	v_add_f32_e32 v54, v54, v55
	v_lshlrev_b32_e32 v98, 16, v56
	v_and_b32_e32 v99, 0xffff0000, v56
	v_add_f32_e32 v54, v102, v54
	v_mul_f32_e32 v56, v98, v98
	v_mul_f32_e32 v57, v99, v99
	v_add_f32_e32 v54, v103, v54
	v_cndmask_b32_e64 v63, v63, -v63, s[2:3]
	v_cndmask_b32_e64 v62, v62, -v62, s[2:3]
	v_add_f32_e32 v54, v56, v54
	v_fma_f32 v62, v28, v94, v62
	v_fma_f32 v63, v29, v95, v63
	v_mul_f32_e32 v94, v92, v92
	v_mul_f32_e32 v95, v93, v93
	v_add_f32_e32 v54, v57, v54
	v_add_f32_e32 v54, v94, v54
	v_add_f32_e32 v81, v95, v54
	ds_bpermute_b32 v94, v82, v81
	v_mul_f32_e32 v64, v6, v64
	v_mul_f32_e32 v65, v7, v65
	ds_bpermute_b32 v90, v84, v64
	ds_bpermute_b32 v91, v84, v65
	v_pk_mul_f32 v[54:55], v[80:81], v[104:105] op_sel_hi:[0,1]
	s_waitcnt lgkmcnt(2)
	v_add_f32_e32 v81, v81, v94
	ds_bpermute_b32 v94, v83, v81
	v_mul_f32_e32 v54, v12, v54
	v_mul_f32_e32 v55, v13, v55
	s_waitcnt lgkmcnt(1)
	v_mul_f32_e32 v90, v22, v90
	v_mul_f32_e32 v91, v23, v91
	ds_bpermute_b32 v56, v84, v54
	v_cndmask_b32_e64 v91, v91, -v91, s[2:3]
	v_cndmask_b32_e64 v90, v90, -v90, s[2:3]
	s_waitcnt lgkmcnt(1)
	v_add_f32_e32 v81, v81, v94
	v_fma_f32 v64, v24, v64, v90
	v_fma_f32 v65, v25, v65, v91
	ds_bpermute_b32 v90, v84, v81
	ds_bpermute_b32 v57, v84, v55
	v_pk_mul_f32 v[62:63], v[62:63], s[22:23] op_sel_hi:[1,0]
	v_pk_mul_f32 v[64:65], v[64:65], s[22:23] op_sel_hi:[1,0]
	v_lshlrev_b32_e32 v102, 16, v42
	s_waitcnt lgkmcnt(1)
	v_add_f32_e32 v90, v81, v90
	ds_bpermute_b32 v91, v85, v90
	s_waitcnt lgkmcnt(1)
	v_mul_f32_e32 v56, v16, v56
	v_mul_f32_e32 v57, v17, v57
	v_and_b32_e32 v103, 0xffff0000, v42
	v_cndmask_b32_e64 v57, v57, -v57, s[2:3]
	v_cndmask_b32_e64 v56, v56, -v56, s[2:3]
	s_waitcnt lgkmcnt(0)
	v_add_f32_e32 v90, v90, v91
	v_fmamk_f32 v90, v90, 0x3c000000, v87
	v_mul_f32_e32 v91, 0x4f800000, v90
	v_cmp_gt_f32_e32 vcc, s34, v90
	v_fma_f32 v54, v20, v54, v56
	v_fma_f32 v55, v21, v55, v57
	v_cndmask_b32_e32 v90, v90, v91, vcc
	v_sqrt_f32_e32 v91, v90
	v_pk_mul_f32 v[56:57], v[54:55], s[22:23] op_sel_hi:[1,0]
	v_pk_mul_f32 v[54:55], v[80:81], v[96:97] op_sel_hi:[0,1]
	v_mul_f32_e32 v54, v14, v54
	v_mul_f32_e32 v55, v15, v55
	v_add_u32_e32 v94, -1, v91
	v_fma_f32 v95, -v94, v91, v90
	v_cmp_ge_f32_e64 s[0:1], 0, v95
	v_add_u32_e32 v95, 1, v91
	ds_bpermute_b32 v80, v84, v54
	v_cndmask_b32_e64 v94, v91, v94, s[0:1]
	v_fma_f32 v91, -v95, v91, v90
	v_cmp_lt_f32_e64 s[0:1], 0, v91
	ds_bpermute_b32 v81, v84, v55
	v_cvt_pk_bf16_f32 v56, v56, v57
	v_cndmask_b32_e64 v91, v94, v95, s[0:1]
	v_mul_f32_e32 v94, 0x37800000, v91
	v_cndmask_b32_e32 v91, v91, v94, vcc
	v_cmp_class_f32_e32 vcc, v90, v88
	s_waitcnt lgkmcnt(0)
	v_mul_f32_e32 v80, v18, v80
	v_mul_f32_e32 v81, v19, v81
	v_lshlrev_b32_e32 v96, 16, v43
	v_cndmask_b32_e32 v90, v91, v90, vcc
	v_div_scale_f32 v91, s[0:1], v90, v90, 1.0
	v_rcp_f32_e32 v94, v91
	v_cndmask_b32_e64 v81, v81, -v81, s[2:3]
	v_cndmask_b32_e64 v80, v80, -v80, s[2:3]
	v_fma_f32 v54, v72, v54, v80
	v_fma_f32 v55, v73, v55, v81
	v_and_b32_e32 v97, 0xffff0000, v43
	v_pk_mul_f32 v[80:81], v[54:55], s[22:23] op_sel_hi:[1,0]
	v_fma_f32 v55, -v91, v94, 1.0
	v_fmac_f32_e32 v94, v55, v94
	v_div_scale_f32 v55, vcc, 1.0, v90, 1.0
	v_cvt_pk_bf16_f32 v54, v62, v63
	v_mul_f32_e32 v62, v55, v94
	v_fma_f32 v63, -v91, v62, v55
	v_fmac_f32_e32 v62, v63, v94
	v_fma_f32 v55, -v91, v62, v55
	v_div_fmas_f32 v55, v55, v94, v62
	v_div_fixup_f32 v62, v55, v90, 1.0
	v_pk_mul_f32 v[90:91], v[62:63], v[106:107] op_sel_hi:[0,1]
	v_mul_f32_e32 v90, v4, v90
	v_mul_f32_e32 v91, v5, v91
	ds_bpermute_b32 v94, v84, v90
	ds_bpermute_b32 v95, v84, v91
	v_cvt_pk_bf16_f32 v55, v64, v65
	v_cvt_pk_bf16_f32 v57, v80, v81
	v_mul_f32_e32 v42, v102, v102
	v_mul_f32_e32 v43, v103, v103
	global_store_dwordx4 v[76:77], v[54:57], off offset:768
	v_add_f32_e32 v42, v42, v43
	v_lshlrev_b32_e32 v80, 16, v45
	v_pk_mul_f32 v[56:57], v[62:63], v[100:101] op_sel_hi:[0,1]
	v_mul_f32_e32 v100, v96, v96
	v_mul_f32_e32 v101, v97, v97
	s_waitcnt lgkmcnt(0)
	v_mul_f32_e32 v54, v26, v94
	v_mul_f32_e32 v55, v27, v95
	v_lshlrev_b32_e32 v94, 16, v44
	v_and_b32_e32 v95, 0xffff0000, v44
	v_add_f32_e32 v42, v100, v42
	v_and_b32_e32 v81, 0xffff0000, v45
	v_mul_f32_e32 v44, v94, v94
	v_mul_f32_e32 v45, v95, v95
	v_add_f32_e32 v42, v101, v42
	v_cndmask_b32_e64 v55, v55, -v55, s[2:3]
	v_cndmask_b32_e64 v54, v54, -v54, s[2:3]
	v_add_f32_e32 v42, v44, v42
	v_fma_f32 v54, v28, v90, v54
	v_fma_f32 v55, v29, v91, v55
	v_mul_f32_e32 v90, v80, v80
	v_mul_f32_e32 v91, v81, v81
	v_add_f32_e32 v42, v45, v42
	v_add_f32_e32 v42, v90, v42
	v_add_f32_e32 v63, v91, v42
	ds_bpermute_b32 v90, v82, v63
	v_mul_f32_e32 v56, v6, v56
	v_mul_f32_e32 v57, v7, v57
	ds_bpermute_b32 v64, v84, v56
	ds_bpermute_b32 v65, v84, v57
	v_pk_mul_f32 v[42:43], v[62:63], v[98:99] op_sel_hi:[0,1]
	s_waitcnt lgkmcnt(2)
	v_add_f32_e32 v63, v63, v90
	ds_bpermute_b32 v90, v83, v63
	v_mul_f32_e32 v42, v12, v42
	v_mul_f32_e32 v43, v13, v43
	s_waitcnt lgkmcnt(1)
	v_mul_f32_e32 v64, v22, v64
	v_mul_f32_e32 v65, v23, v65
	ds_bpermute_b32 v44, v84, v42
	v_cndmask_b32_e64 v65, v65, -v65, s[2:3]
	v_cndmask_b32_e64 v64, v64, -v64, s[2:3]
	s_waitcnt lgkmcnt(1)
	v_add_f32_e32 v63, v63, v90
	v_fma_f32 v56, v24, v56, v64
	v_fma_f32 v57, v25, v57, v65
	ds_bpermute_b32 v64, v84, v63
	ds_bpermute_b32 v45, v84, v43
	v_pk_mul_f32 v[54:55], v[54:55], s[22:23] op_sel_hi:[1,0]
	v_pk_mul_f32 v[56:57], v[56:57], s[22:23] op_sel_hi:[1,0]
	v_lshlrev_b32_e32 v98, 16, v34
	s_waitcnt lgkmcnt(1)
	v_add_f32_e32 v64, v63, v64
	ds_bpermute_b32 v65, v85, v64
	s_waitcnt lgkmcnt(1)
; __device__ __forceinline__ unsigned cvtpk(float lo, float hi) { const f32x2 v = {lo, hi}; const hbf16x2_t b = __builtin_convertvector(v, hbf16x2_t); return __builtin_bit_cast(unsigned, b); }
; template <int PH>
; __device__ __forceinline__ void run_phase(const Args& args, LAS unsigned char* lds) {
;     ...
;                     for (int h = 0; h < 10; ++h) {
;                         float x[8] = {bflo(raw[h].x), bfhi(raw[h].x), bflo(raw[h].y), bfhi(raw[h].y), bflo(raw[h].z), bfhi(raw[h].z), bflo(raw[h].w), bfhi(raw[h].w)};
;                         float ss = 0.f;
; #pragma unroll
;                         for (int k = 0; k < 8; ++k) ss += x[k] * x[k];
;                         ss += __shfl_xor(ss, 1); ss += __shfl_xor(ss, 2); ss += __shfl_xor(ss, 4); ss += __shfl_xor(ss, 8);
;                         const float rs = 1.0f / sqrtf(ss * (1.0f / 128.0f) + NEPS);
;                         float o[8];
; #pragma unroll
;                         for (int k = 0; k < 8; ++k) { const float y = x[k] * rs * (h < 8 ? qgv[k] : kgv[k]); const float yo = __shfl_xor(y, 4);
;                             o[k] = first ? (y * cs[k] - yo * sn[k]) : (yo * sn[k] + y * cs[k]); if (h < 8) o[k] *= QS; }
;                         u32x4 w; w.x = cvtpk(o[0], o[1]); w.y = cvtpk(o[2], o[3]); w.z = cvtpk(o[4], o[5]); w.w = cvtpk(o[6], o[7]);
;                         if (h < 8) *(u32x4*)(Qb + (size_t)row * 1024 + h * 128 + 8 * l16) = w;
;                         else *(u32x4*)(Kb + (size_t)(b * TK + Tpos) * 256 + (h - 8) * 128 + 8 * l16) = w;
	v_mul_f32_e32 v44, v16, v44
	v_mul_f32_e32 v45, v17, v45
	v_and_b32_e32 v99, 0xffff0000, v34
	v_cndmask_b32_e64 v45, v45, -v45, s[2:3]
	v_cndmask_b32_e64 v44, v44, -v44, s[2:3]
	s_waitcnt lgkmcnt(0)
	v_add_f32_e32 v64, v64, v65
	v_fmamk_f32 v64, v64, 0x3c000000, v87
	v_mul_f32_e32 v65, 0x4f800000, v64
	v_cmp_gt_f32_e32 vcc, s34, v64
	v_fma_f32 v42, v20, v42, v44
	v_fma_f32 v43, v21, v43, v45
	v_cndmask_b32_e32 v64, v64, v65, vcc
	v_sqrt_f32_e32 v65, v64
	v_pk_mul_f32 v[44:45], v[42:43], s[22:23] op_sel_hi:[1,0]
	v_pk_mul_f32 v[42:43], v[62:63], v[92:93] op_sel_hi:[0,1]
	v_mul_f32_e32 v42, v14, v42
	v_mul_f32_e32 v43, v15, v43
	v_add_u32_e32 v90, -1, v65
	v_fma_f32 v91, -v90, v65, v64
	v_cmp_ge_f32_e64 s[0:1], 0, v91
	v_add_u32_e32 v91, 1, v65
	ds_bpermute_b32 v62, v84, v42
	v_cndmask_b32_e64 v90, v65, v90, s[0:1]
	v_fma_f32 v65, -v91, v65, v64
	v_cmp_lt_f32_e64 s[0:1], 0, v65
	ds_bpermute_b32 v63, v84, v43
	v_cvt_pk_bf16_f32 v44, v44, v45
	v_cndmask_b32_e64 v65, v90, v91, s[0:1]
	v_mul_f32_e32 v90, 0x37800000, v65
	v_cndmask_b32_e32 v65, v65, v90, vcc
	v_cmp_class_f32_e32 vcc, v64, v88
	s_waitcnt lgkmcnt(0)
	v_mul_f32_e32 v62, v18, v62
	v_mul_f32_e32 v63, v19, v63
	v_lshlrev_b32_e32 v92, 16, v35
	v_cndmask_b32_e32 v64, v65, v64, vcc
	v_div_scale_f32 v65, s[0:1], v64, v64, 1.0
	v_rcp_f32_e32 v90, v65
	v_cndmask_b32_e64 v63, v63, -v63, s[2:3]
	v_cndmask_b32_e64 v62, v62, -v62, s[2:3]
	v_fma_f32 v42, v72, v42, v62
	v_fma_f32 v43, v73, v43, v63
	v_and_b32_e32 v93, 0xffff0000, v35
	v_pk_mul_f32 v[62:63], v[42:43], s[22:23] op_sel_hi:[1,0]
	v_fma_f32 v43, -v65, v90, 1.0
	v_fmac_f32_e32 v90, v43, v90
	v_div_scale_f32 v43, vcc, 1.0, v64, 1.0
	v_cvt_pk_bf16_f32 v42, v54, v55
	v_mul_f32_e32 v54, v43, v90
	v_fma_f32 v55, -v65, v54, v43
	v_fmac_f32_e32 v54, v55, v90
	v_fma_f32 v43, -v65, v54, v43
	v_div_fmas_f32 v43, v43, v90, v54
	v_div_fixup_f32 v54, v43, v64, 1.0
	v_pk_mul_f32 v[64:65], v[54:55], v[102:103] op_sel_hi:[0,1]
	v_mul_f32_e32 v64, v4, v64
	v_mul_f32_e32 v65, v5, v65
	ds_bpermute_b32 v90, v84, v64
	ds_bpermute_b32 v91, v84, v65
	v_cvt_pk_bf16_f32 v43, v56, v57
	v_cvt_pk_bf16_f32 v45, v62, v63
	v_mul_f32_e32 v34, v98, v98
	v_mul_f32_e32 v35, v99, v99
	global_store_dwordx4 v[76:77], v[42:45], off offset:1024
	v_add_f32_e32 v34, v34, v35
	v_lshlrev_b32_e32 v62, 16, v37
	v_pk_mul_f32 v[44:45], v[54:55], v[96:97] op_sel_hi:[0,1]
	v_mul_f32_e32 v96, v92, v92
	v_mul_f32_e32 v97, v93, v93
	s_waitcnt lgkmcnt(0)
	v_mul_f32_e32 v42, v26, v90
	v_mul_f32_e32 v43, v27, v91
	v_lshlrev_b32_e32 v90, 16, v36
	v_and_b32_e32 v91, 0xffff0000, v36
	v_add_f32_e32 v34, v96, v34
	v_and_b32_e32 v63, 0xffff0000, v37
	v_mul_f32_e32 v36, v90, v90
	v_mul_f32_e32 v37, v91, v91
	v_add_f32_e32 v34, v97, v34
	v_cndmask_b32_e64 v43, v43, -v43, s[2:3]
	v_cndmask_b32_e64 v42, v42, -v42, s[2:3]
	v_add_f32_e32 v34, v36, v34
	v_fma_f32 v42, v28, v64, v42
	v_fma_f32 v43, v29, v65, v43
	v_mul_f32_e32 v64, v62, v62
	v_mul_f32_e32 v65, v63, v63
	v_add_f32_e32 v34, v37, v34
	v_add_f32_e32 v34, v64, v34
	v_add_f32_e32 v55, v65, v34
	ds_bpermute_b32 v64, v82, v55
	v_mul_f32_e32 v44, v6, v44
	v_mul_f32_e32 v45, v7, v45
	ds_bpermute_b32 v56, v84, v44
	ds_bpermute_b32 v57, v84, v45
	v_pk_mul_f32 v[34:35], v[54:55], v[94:95] op_sel_hi:[0,1]
	s_waitcnt lgkmcnt(2)
	v_add_f32_e32 v55, v55, v64
	ds_bpermute_b32 v64, v83, v55
	v_mul_f32_e32 v34, v12, v34
	v_mul_f32_e32 v35, v13, v35
	s_waitcnt lgkmcnt(1)
	v_mul_f32_e32 v56, v22, v56
	v_mul_f32_e32 v57, v23, v57
	ds_bpermute_b32 v36, v84, v34
	v_cndmask_b32_e64 v57, v57, -v57, s[2:3]
	v_cndmask_b32_e64 v56, v56, -v56, s[2:3]
	s_waitcnt lgkmcnt(1)
	v_add_f32_e32 v55, v55, v64
	v_fma_f32 v44, v24, v44, v56
	v_fma_f32 v45, v25, v45, v57
	ds_bpermute_b32 v56, v84, v55
	ds_bpermute_b32 v37, v84, v35
	v_pk_mul_f32 v[42:43], v[42:43], s[22:23] op_sel_hi:[1,0]
	v_pk_mul_f32 v[44:45], v[44:45], s[22:23] op_sel_hi:[1,0]
	s_waitcnt vmcnt(8)
	v_lshlrev_b32_e32 v94, 16, v58
	s_waitcnt lgkmcnt(1)
	v_add_f32_e32 v56, v55, v56
	ds_bpermute_b32 v57, v85, v56
	s_waitcnt lgkmcnt(1)
	v_mul_f32_e32 v36, v16, v36
	v_mul_f32_e32 v37, v17, v37
	v_and_b32_e32 v95, 0xffff0000, v58
	v_cndmask_b32_e64 v37, v37, -v37, s[2:3]
	v_cndmask_b32_e64 v36, v36, -v36, s[2:3]
	s_waitcnt lgkmcnt(0)
	v_add_f32_e32 v56, v56, v57
	v_fmamk_f32 v56, v56, 0x3c000000, v87
	v_mul_f32_e32 v57, 0x4f800000, v56
	v_cmp_gt_f32_e32 vcc, s34, v56
	v_fma_f32 v34, v20, v34, v36
	v_fma_f32 v35, v21, v35, v37
	v_cndmask_b32_e32 v56, v56, v57, vcc
	v_sqrt_f32_e32 v57, v56
	v_pk_mul_f32 v[36:37], v[34:35], s[22:23] op_sel_hi:[1,0]
	v_pk_mul_f32 v[34:35], v[54:55], v[80:81] op_sel_hi:[0,1]
	v_mul_f32_e32 v34, v14, v34
	v_mul_f32_e32 v35, v15, v35
	v_add_u32_e32 v64, -1, v57
	v_fma_f32 v65, -v64, v57, v56
	v_cmp_ge_f32_e64 s[0:1], 0, v65
	v_add_u32_e32 v65, 1, v57
	ds_bpermute_b32 v54, v84, v34
	v_cndmask_b32_e64 v64, v57, v64, s[0:1]
	v_fma_f32 v57, -v65, v57, v56
	v_cmp_lt_f32_e64 s[0:1], 0, v57
	ds_bpermute_b32 v55, v84, v35
	v_cvt_pk_bf16_f32 v36, v36, v37
	v_cndmask_b32_e64 v57, v64, v65, s[0:1]
	v_mul_f32_e32 v64, 0x37800000, v57
	v_cndmask_b32_e32 v57, v57, v64, vcc
	v_cmp_class_f32_e32 vcc, v56, v88
	s_waitcnt lgkmcnt(0)
; __device__ __forceinline__ unsigned cvtpk(float lo, float hi) { const f32x2 v = {lo, hi}; const hbf16x2_t b = __builtin_convertvector(v, hbf16x2_t); return __builtin_bit_cast(unsigned, b); }
; template <int PH>
; __device__ __forceinline__ void run_phase(const Args& args, LAS unsigned char* lds) {
;     ...
;                     for (int h = 0; h < 10; ++h) {
;                         float x[8] = {bflo(raw[h].x), bfhi(raw[h].x), bflo(raw[h].y), bfhi(raw[h].y), bflo(raw[h].z), bfhi(raw[h].z), bflo(raw[h].w), bfhi(raw[h].w)};
;                         float ss = 0.f;
; #pragma unroll
;                         for (int k = 0; k < 8; ++k) ss += x[k] * x[k];
;                         ss += __shfl_xor(ss, 1); ss += __shfl_xor(ss, 2); ss += __shfl_xor(ss, 4); ss += __shfl_xor(ss, 8);
;                         const float rs = 1.0f / sqrtf(ss * (1.0f / 128.0f) + NEPS);
;                         float o[8];
; #pragma unroll
;                         for (int k = 0; k < 8; ++k) { const float y = x[k] * rs * (h < 8 ? qgv[k] : kgv[k]); const float yo = __shfl_xor(y, 4);
;                             o[k] = first ? (y * cs[k] - yo * sn[k]) : (yo * sn[k] + y * cs[k]); if (h < 8) o[k] *= QS; }
;                         u32x4 w; w.x = cvtpk(o[0], o[1]); w.y = cvtpk(o[2], o[3]); w.z = cvtpk(o[4], o[5]); w.w = cvtpk(o[6], o[7]);
;                         if (h < 8) *(u32x4*)(Qb + (size_t)row * 1024 + h * 128 + 8 * l16) = w;
;                         else *(u32x4*)(Kb + (size_t)(b * TK + Tpos) * 256 + (h - 8) * 128 + 8 * l16) = w;
	v_mul_f32_e32 v54, v18, v54
	v_mul_f32_e32 v55, v19, v55
	v_lshlrev_b32_e32 v80, 16, v59
	v_cndmask_b32_e32 v56, v57, v56, vcc
	v_div_scale_f32 v57, s[0:1], v56, v56, 1.0
	v_rcp_f32_e32 v64, v57
	v_cndmask_b32_e64 v55, v55, -v55, s[2:3]
	v_cndmask_b32_e64 v54, v54, -v54, s[2:3]
	v_fma_f32 v34, v72, v34, v54
	v_fma_f32 v35, v73, v35, v55
	v_and_b32_e32 v81, 0xffff0000, v59
	v_pk_mul_f32 v[54:55], v[34:35], s[22:23] op_sel_hi:[1,0]
	v_fma_f32 v35, -v57, v64, 1.0
	v_fmac_f32_e32 v64, v35, v64
	v_div_scale_f32 v35, vcc, 1.0, v56, 1.0
	v_cvt_pk_bf16_f32 v34, v42, v43
	v_mul_f32_e32 v42, v35, v64
	v_fma_f32 v43, -v57, v42, v35
	v_fmac_f32_e32 v42, v43, v64
	v_fma_f32 v35, -v57, v42, v35
	v_div_fmas_f32 v35, v35, v64, v42
	v_div_fixup_f32 v42, v35, v56, 1.0
	v_pk_mul_f32 v[56:57], v[42:43], v[98:99] op_sel_hi:[0,1]
	v_mul_f32_e32 v56, v4, v56
	v_mul_f32_e32 v57, v5, v57
	ds_bpermute_b32 v64, v84, v56
	ds_bpermute_b32 v65, v84, v57
	v_cvt_pk_bf16_f32 v35, v44, v45
	v_cvt_pk_bf16_f32 v37, v54, v55
	v_mul_f32_e32 v58, v94, v94
	v_mul_f32_e32 v59, v95, v95
	global_store_dwordx4 v[76:77], v[34:37], off offset:1280
	v_lshlrev_b32_e32 v54, 16, v61
	v_and_b32_e32 v55, 0xffff0000, v61
	v_pk_mul_f32 v[36:37], v[42:43], v[92:93] op_sel_hi:[0,1]
	v_mul_f32_e32 v92, v80, v80
	v_mul_f32_e32 v93, v81, v81
	v_add_f32_e32 v43, v58, v59
	s_waitcnt lgkmcnt(0)
	v_mul_f32_e32 v34, v26, v64
	v_mul_f32_e32 v35, v27, v65
	v_lshlrev_b32_e32 v64, 16, v60
	v_and_b32_e32 v65, 0xffff0000, v60
	v_add_f32_e32 v43, v92, v43
	v_mul_f32_e32 v60, v64, v64
	v_mul_f32_e32 v61, v65, v65
	v_add_f32_e32 v43, v93, v43
	v_cndmask_b32_e64 v35, v35, -v35, s[2:3]
	v_cndmask_b32_e64 v34, v34, -v34, s[2:3]
	v_add_f32_e32 v43, v60, v43
	v_fma_f32 v34, v28, v56, v34
	v_fma_f32 v35, v29, v57, v35
	v_mul_f32_e32 v56, v54, v54
	v_mul_f32_e32 v57, v55, v55
	v_add_f32_e32 v43, v61, v43
	v_add_f32_e32 v43, v56, v43
	v_add_f32_e32 v43, v57, v43
	ds_bpermute_b32 v60, v82, v43
	v_mul_f32_e32 v36, v6, v36
	v_mul_f32_e32 v37, v7, v37
	ds_bpermute_b32 v44, v84, v36
	ds_bpermute_b32 v45, v84, v37
	v_pk_mul_f32 v[56:57], v[42:43], v[90:91] op_sel_hi:[0,1]
	s_waitcnt lgkmcnt(2)
	v_add_f32_e32 v43, v43, v60
	v_mul_f32_e32 v56, v12, v56
	v_mul_f32_e32 v57, v13, v57
	ds_bpermute_b32 v60, v83, v43
	ds_bpermute_b32 v58, v84, v56
	ds_bpermute_b32 v59, v84, v57
	s_waitcnt lgkmcnt(3)
	v_mul_f32_e32 v44, v22, v44
	v_mul_f32_e32 v45, v23, v45
	v_pk_mul_f32 v[34:35], v[34:35], s[22:23] op_sel_hi:[1,0]
	v_cndmask_b32_e64 v45, v45, -v45, s[2:3]
	v_cndmask_b32_e64 v44, v44, -v44, s[2:3]
	s_waitcnt lgkmcnt(2)
	v_add_f32_e32 v43, v43, v60
	v_fma_f32 v36, v24, v36, v44
	v_fma_f32 v37, v25, v37, v45
	s_waitcnt lgkmcnt(0)
	v_mul_f32_e32 v44, v16, v58
	v_mul_f32_e32 v45, v17, v59
	ds_bpermute_b32 v58, v84, v43
	v_cndmask_b32_e64 v45, v45, -v45, s[2:3]
	v_cndmask_b32_e64 v44, v44, -v44, s[2:3]
	v_fma_f32 v44, v20, v56, v44
	v_fma_f32 v45, v21, v57, v45
	v_cvt_pk_bf16_f32 v34, v34, v35
	s_waitcnt lgkmcnt(0)
	v_add_f32_e32 v58, v43, v58
	ds_bpermute_b32 v59, v85, v58
	v_pk_mul_f32 v[42:43], v[42:43], v[62:63] op_sel_hi:[0,1]
	v_mul_f32_e32 v42, v14, v42
	v_mul_f32_e32 v43, v15, v43
	ds_bpermute_b32 v56, v84, v42
	ds_bpermute_b32 v57, v84, v43
	s_waitcnt lgkmcnt(2)
	v_add_f32_e32 v58, v58, v59
	v_fmamk_f32 v58, v58, 0x3c000000, v87
	v_mul_f32_e32 v59, 0x4f800000, v58
	v_cmp_gt_f32_e32 vcc, s34, v58
	s_waitcnt lgkmcnt(0)
	v_mul_f32_e32 v56, v18, v56
	v_mul_f32_e32 v57, v19, v57
	v_pk_mul_f32 v[36:37], v[36:37], s[22:23] op_sel_hi:[1,0]
	v_cndmask_b32_e32 v58, v58, v59, vcc
	v_sqrt_f32_e32 v59, v58
	v_cndmask_b32_e64 v57, v57, -v57, s[2:3]
	v_cndmask_b32_e64 v56, v56, -v56, s[2:3]
	v_fma_f32 v42, v72, v42, v56
	v_fma_f32 v43, v73, v43, v57
	v_add_u32_e32 v60, -1, v59
	v_fma_f32 v61, -v60, v59, v58
	v_cmp_ge_f32_e64 s[0:1], 0, v61
	v_add_u32_e32 v61, 1, v59
	v_pk_mul_f32 v[44:45], v[44:45], s[22:23] op_sel_hi:[1,0]
	v_cndmask_b32_e64 v60, v59, v60, s[0:1]
	v_fma_f32 v59, -v61, v59, v58
	v_cmp_lt_f32_e64 s[0:1], 0, v59
	v_pk_mul_f32 v[42:43], v[42:43], s[22:23] op_sel_hi:[1,0]
	s_waitcnt vmcnt(8)
	v_lshlrev_b32_e32 v92, 16, v46
	v_cndmask_b32_e64 v59, v60, v61, s[0:1]
	v_mul_f32_e32 v60, 0x37800000, v59
	v_cndmask_b32_e32 v59, v59, v60, vcc
	v_cmp_class_f32_e32 vcc, v58, v88
	v_and_b32_e32 v93, 0xffff0000, v46
	s_nop 0
	v_cndmask_b32_e32 v58, v59, v58, vcc
	v_div_scale_f32 v59, s[0:1], v58, v58, 1.0
	v_rcp_f32_e32 v60, v59
	s_nop 0
	v_fma_f32 v35, -v59, v60, 1.0
	v_fmac_f32_e32 v60, v35, v60
	v_div_scale_f32 v35, vcc, 1.0, v58, 1.0
	v_mul_f32_e32 v56, v35, v60
	v_fma_f32 v57, -v59, v56, v35
	v_fmac_f32_e32 v56, v57, v60
	v_fma_f32 v35, -v59, v56, v35
	v_div_fmas_f32 v35, v35, v60, v56
	v_div_fixup_f32 v56, v35, v58, 1.0
	v_pk_mul_f32 v[58:59], v[56:57], v[94:95] op_sel_hi:[0,1]
	v_mul_f32_e32 v58, v4, v58
	v_mul_f32_e32 v59, v5, v59
	ds_bpermute_b32 v60, v84, v58
	ds_bpermute_b32 v61, v84, v59
	v_cvt_pk_bf16_f32 v35, v36, v37
	v_cvt_pk_bf16_f32 v36, v44, v45
	v_cvt_pk_bf16_f32 v37, v42, v43
	global_store_dwordx4 v[76:77], v[34:37], off offset:1536
	v_pk_mul_f32 v[44:45], v[56:57], v[64:65] op_sel_hi:[0,1]
	v_lshlrev_b32_e32 v64, 16, v48
	v_pk_mul_f32 v[36:37], v[56:57], v[80:81] op_sel_hi:[0,1]
	v_lshlrev_b32_e32 v80, 16, v47
	v_and_b32_e32 v81, 0xffff0000, v47
	v_mul_f32_e32 v46, v92, v92
	v_mul_f32_e32 v47, v93, v93
	v_mul_f32_e32 v90, v80, v80
	v_mul_f32_e32 v91, v81, v81
	v_add_f32_e32 v46, v46, v47
	v_and_b32_e32 v65, 0xffff0000, v48
	v_add_f32_e32 v46, v90, v46
	s_waitcnt lgkmcnt(0)
; __device__ __forceinline__ unsigned cvtpk(float lo, float hi) { const f32x2 v = {lo, hi}; const hbf16x2_t b = __builtin_convertvector(v, hbf16x2_t); return __builtin_bit_cast(unsigned, b); }
; template <int PH>
; __device__ __forceinline__ void run_phase(const Args& args, LAS unsigned char* lds) {
;     ...
;                     for (int h = 0; h < 10; ++h) {
;                         float x[8] = {bflo(raw[h].x), bfhi(raw[h].x), bflo(raw[h].y), bfhi(raw[h].y), bflo(raw[h].z), bfhi(raw[h].z), bflo(raw[h].w), bfhi(raw[h].w)};
;                         float ss = 0.f;
; #pragma unroll
;                         for (int k = 0; k < 8; ++k) ss += x[k] * x[k];
;                         ss += __shfl_xor(ss, 1); ss += __shfl_xor(ss, 2); ss += __shfl_xor(ss, 4); ss += __shfl_xor(ss, 8);
;                         const float rs = 1.0f / sqrtf(ss * (1.0f / 128.0f) + NEPS);
;                         float o[8];
; #pragma unroll
;                         for (int k = 0; k < 8; ++k) { const float y = x[k] * rs * (h < 8 ? qgv[k] : kgv[k]); const float yo = __shfl_xor(y, 4);
;                             o[k] = first ? (y * cs[k] - yo * sn[k]) : (yo * sn[k] + y * cs[k]); if (h < 8) o[k] *= QS; }
;                         u32x4 w; w.x = cvtpk(o[0], o[1]); w.y = cvtpk(o[2], o[3]); w.z = cvtpk(o[4], o[5]); w.w = cvtpk(o[6], o[7]);
;                         if (h < 8) *(u32x4*)(Qb + (size_t)row * 1024 + h * 128 + 8 * l16) = w;
;                         else *(u32x4*)(Kb + (size_t)(b * TK + Tpos) * 256 + (h - 8) * 128 + 8 * l16) = w;
	v_mul_f32_e32 v34, v26, v60
	v_mul_f32_e32 v35, v27, v61
	v_lshlrev_b32_e32 v60, 16, v49
	v_and_b32_e32 v61, 0xffff0000, v49
	v_mul_f32_e32 v48, v64, v64
	v_mul_f32_e32 v49, v65, v65
	v_add_f32_e32 v46, v91, v46
	v_add_f32_e32 v46, v48, v46
	v_mul_f32_e32 v62, v60, v60
	v_mul_f32_e32 v63, v61, v61
	v_add_f32_e32 v46, v49, v46
	v_add_f32_e32 v46, v62, v46
	v_add_f32_e32 v46, v63, v46
	ds_bpermute_b32 v47, v82, v46
	v_mul_f32_e32 v36, v6, v36
	v_mul_f32_e32 v37, v7, v37
	ds_bpermute_b32 v42, v84, v36
	ds_bpermute_b32 v43, v84, v37
	v_cndmask_b32_e64 v35, v35, -v35, s[2:3]
	s_waitcnt lgkmcnt(2)
	v_add_f32_e32 v48, v46, v47
	ds_bpermute_b32 v49, v83, v48
	v_pk_mul_f32 v[46:47], v[56:57], v[54:55] op_sel_hi:[0,1]
	v_cndmask_b32_e64 v34, v34, -v34, s[2:3]
	v_mul_f32_e32 v44, v12, v44
	v_mul_f32_e32 v45, v13, v45
	v_fma_f32 v34, v28, v58, v34
	v_fma_f32 v35, v29, v59, v35
	s_waitcnt lgkmcnt(0)
	v_add_f32_e32 v54, v48, v49
	ds_bpermute_b32 v55, v84, v54
	ds_bpermute_b32 v58, v84, v44
	ds_bpermute_b32 v59, v84, v45
	v_mul_f32_e32 v46, v14, v46
	v_mul_f32_e32 v47, v15, v47
	ds_bpermute_b32 v48, v84, v46
	ds_bpermute_b32 v49, v84, v47
	v_mul_f32_e32 v42, v22, v42
	v_mul_f32_e32 v43, v23, v43
	s_waitcnt lgkmcnt(4)
	v_add_f32_e32 v54, v54, v55
	v_cndmask_b32_e64 v43, v43, -v43, s[2:3]
	v_cndmask_b32_e64 v42, v42, -v42, s[2:3]
	ds_bpermute_b32 v55, v85, v54
	v_fma_f32 v36, v24, v36, v42
	v_fma_f32 v37, v25, v37, v43
	s_waitcnt lgkmcnt(3)
	v_mul_f32_e32 v42, v16, v58
	v_mul_f32_e32 v43, v17, v59
	v_pk_mul_f32 v[34:35], v[34:35], s[22:23] op_sel_hi:[1,0]
	v_cndmask_b32_e64 v43, v43, -v43, s[2:3]
	v_cndmask_b32_e64 v42, v42, -v42, s[2:3]
	v_fma_f32 v42, v20, v44, v42
	v_fma_f32 v43, v21, v45, v43
	s_waitcnt lgkmcnt(1)
	v_mul_f32_e32 v44, v18, v48
	v_mul_f32_e32 v45, v19, v49
	v_pk_mul_f32 v[36:37], v[36:37], s[22:23] op_sel_hi:[1,0]
	v_cndmask_b32_e64 v45, v45, -v45, s[2:3]
	v_cndmask_b32_e64 v44, v44, -v44, s[2:3]
	v_fma_f32 v44, v72, v46, v44
	v_fma_f32 v45, v73, v47, v45
	s_waitcnt lgkmcnt(0)
	v_add_f32_e32 v46, v54, v55
	v_fmamk_f32 v46, v46, 0x3c000000, v87
	v_mul_f32_e32 v47, 0x4f800000, v46
	v_cmp_gt_f32_e32 vcc, s34, v46
	v_cvt_pk_bf16_f32 v34, v34, v35
	v_cvt_pk_bf16_f32 v35, v36, v37
	v_cndmask_b32_e32 v46, v46, v47, vcc
	v_sqrt_f32_e32 v47, v46
	v_pk_mul_f32 v[42:43], v[42:43], s[22:23] op_sel_hi:[1,0]
	v_pk_mul_f32 v[44:45], v[44:45], s[22:23] op_sel_hi:[1,0]
	s_waitcnt vmcnt(7)
	v_lshlrev_b32_e32 v62, 16, v51
	v_add_u32_e32 v36, -1, v47
	v_fma_f32 v37, -v36, v47, v46
	v_cmp_ge_f32_e64 s[0:1], 0, v37
	v_add_u32_e32 v37, 1, v47
	v_and_b32_e32 v63, 0xffff0000, v51
	v_cndmask_b32_e64 v36, v47, v36, s[0:1]
	v_fma_f32 v47, -v37, v47, v46
	v_cmp_lt_f32_e64 s[0:1], 0, v47
	v_lshlrev_b32_e32 v58, 16, v52
	v_and_b32_e32 v59, 0xffff0000, v52
	v_cndmask_b32_e64 v36, v36, v37, s[0:1]
	v_mul_f32_e32 v37, 0x37800000, v36
	v_cndmask_b32_e32 v36, v36, v37, vcc
	v_cmp_class_f32_e32 vcc, v46, v88
	v_cvt_pk_bf16_f32 v37, v44, v45
	v_lshlrev_b32_e32 v54, 16, v53
	v_cndmask_b32_e32 v46, v36, v46, vcc
	v_div_scale_f32 v47, s[0:1], v46, v46, 1.0
	v_rcp_f32_e32 v48, v47
	v_cvt_pk_bf16_f32 v36, v42, v43
	global_store_dwordx4 v[76:77], v[34:37], off offset:1792
	v_lshlrev_b32_e32 v76, 16, v50
	v_and_b32_e32 v77, 0xffff0000, v50
	v_fma_f32 v34, -v47, v48, 1.0
	v_fmac_f32_e32 v48, v34, v48
	v_div_scale_f32 v34, vcc, 1.0, v46, 1.0
	v_mul_f32_e32 v35, v34, v48
	v_fma_f32 v36, -v47, v35, v34
	v_fmac_f32_e32 v35, v36, v48
	v_fma_f32 v34, -v47, v35, v34
	v_div_fmas_f32 v34, v34, v48, v35
	v_div_fixup_f32 v34, v34, v46, 1.0
	v_pk_mul_f32 v[36:37], v[34:35], v[92:93] op_sel_hi:[0,1]
	v_mul_f32_e32 v36, v0, v36
	v_mul_f32_e32 v37, v1, v37
	ds_bpermute_b32 v42, v84, v36
	ds_bpermute_b32 v43, v84, v37
	v_pk_mul_f32 v[44:45], v[34:35], v[80:81] op_sel_hi:[0,1]
	v_mul_f32_e32 v44, v2, v44
	v_mul_f32_e32 v45, v3, v45
	ds_bpermute_b32 v46, v84, v44
	ds_bpermute_b32 v47, v84, v45
	s_waitcnt lgkmcnt(2)
	v_mul_f32_e32 v42, v26, v42
	v_mul_f32_e32 v43, v27, v43
	v_mul_f32_e32 v50, v76, v76
	v_mul_f32_e32 v51, v77, v77
	v_cndmask_b32_e64 v43, v43, -v43, s[2:3]
	v_cndmask_b32_e64 v42, v42, -v42, s[2:3]
	v_fma_f32 v36, v28, v36, v42
	v_fma_f32 v37, v29, v37, v43
	s_waitcnt lgkmcnt(0)
	v_mul_f32_e32 v42, v22, v46
	v_mul_f32_e32 v43, v23, v47
	v_pk_mul_f32 v[46:47], v[34:35], v[64:65] op_sel_hi:[0,1]
	v_mul_f32_e32 v64, v62, v62
	v_mul_f32_e32 v65, v63, v63
	v_add_f32_e32 v35, v50, v51
	v_add_f32_e32 v35, v64, v35
	v_and_b32_e32 v55, 0xffff0000, v53
	v_mul_f32_e32 v52, v58, v58
	v_mul_f32_e32 v53, v59, v59
	v_add_f32_e32 v35, v65, v35
	v_add_f32_e32 v35, v52, v35
	v_mul_f32_e32 v56, v54, v54
	v_mul_f32_e32 v57, v55, v55
	v_add_f32_e32 v35, v53, v35
	v_mul_f32_e32 v46, v8, v46
	v_mul_f32_e32 v47, v9, v47
	v_add_f32_e32 v35, v56, v35
	ds_bpermute_b32 v48, v84, v46
	ds_bpermute_b32 v49, v84, v47
	v_add_f32_e32 v50, v57, v35
	ds_bpermute_b32 v51, v82, v50
	v_cndmask_b32_e64 v43, v43, -v43, s[2:3]
	v_cndmask_b32_e64 v42, v42, -v42, s[2:3]
	v_fma_f32 v42, v24, v44, v42
	v_fma_f32 v43, v25, v45, v43
	s_waitcnt lgkmcnt(1)
	v_mul_f32_e32 v44, v16, v48
	v_mul_f32_e32 v45, v17, v49
	v_cndmask_b32_e64 v35, v45, -v45, s[2:3]
	s_waitcnt lgkmcnt(0)
	v_add_f32_e32 v45, v50, v51
	ds_bpermute_b32 v52, v83, v45
	v_pk_mul_f32 v[48:49], v[34:35], v[60:61] op_sel_hi:[0,1]
	v_mul_f32_e32 v48, v10, v48
	v_mul_f32_e32 v49, v11, v49
	ds_bpermute_b32 v50, v84, v48
	ds_bpermute_b32 v51, v84, v49
	s_waitcnt lgkmcnt(2)
	v_add_f32_e32 v52, v45, v52
	ds_bpermute_b32 v53, v84, v52
	v_cndmask_b32_e64 v34, v44, -v44, s[2:3]
	v_fma_f32 v44, v20, v46, v34
	v_fma_f32 v45, v21, v47, v35
	s_waitcnt lgkmcnt(1)
; __device__ __forceinline__ unsigned cvtpk(float lo, float hi) { const f32x2 v = {lo, hi}; const hbf16x2_t b = __builtin_convertvector(v, hbf16x2_t); return __builtin_bit_cast(unsigned, b); }
; template <int PH>
; __device__ __forceinline__ void run_phase(const Args& args, LAS unsigned char* lds) {
;     ...
;                     for (int h = 0; h < 10; ++h) {
;                         float x[8] = {bflo(raw[h].x), bfhi(raw[h].x), bflo(raw[h].y), bfhi(raw[h].y), bflo(raw[h].z), bfhi(raw[h].z), bflo(raw[h].w), bfhi(raw[h].w)};
;                         float ss = 0.f;
; #pragma unroll
;                         for (int k = 0; k < 8; ++k) ss += x[k] * x[k];
;                         ss += __shfl_xor(ss, 1); ss += __shfl_xor(ss, 2); ss += __shfl_xor(ss, 4); ss += __shfl_xor(ss, 8);
;                         const float rs = 1.0f / sqrtf(ss * (1.0f / 128.0f) + NEPS);
;                         float o[8];
; #pragma unroll
;                         for (int k = 0; k < 8; ++k) { const float y = x[k] * rs * (h < 8 ? qgv[k] : kgv[k]); const float yo = __shfl_xor(y, 4);
;                             o[k] = first ? (y * cs[k] - yo * sn[k]) : (yo * sn[k] + y * cs[k]); if (h < 8) o[k] *= QS; }
;                         u32x4 w; w.x = cvtpk(o[0], o[1]); w.y = cvtpk(o[2], o[3]); w.z = cvtpk(o[4], o[5]); w.w = cvtpk(o[6], o[7]);
;                         if (h < 8) *(u32x4*)(Qb + (size_t)row * 1024 + h * 128 + 8 * l16) = w;
;                         else *(u32x4*)(Kb + (size_t)(b * TK + Tpos) * 256 + (h - 8) * 128 + 8 * l16) = w;
;                     }
; #pragma unroll
;                     for (int h = 0; h < 2; ++h) { bf16_t* vp = VTb + (size_t)((b * 2 + h) * 128 + 8 * l16) * TK + Tpos; const u32x4 r = raw[10 + h];
;                         vp[0] = (bf16_t)(r.x & 0xffffu); vp[TK] = (bf16_t)(r.x >> 16); vp[2 * TK] = (bf16_t)(r.y & 0xffffu); vp[3 * TK] = (bf16_t)(r.y >> 16);
;                         vp[4 * TK] = (bf16_t)(r.z & 0xffffu); vp[5 * TK] = (bf16_t)(r.z >> 16); vp[6 * TK] = (bf16_t)(r.w & 0xffffu); vp[7 * TK] = (bf16_t)(r.w >> 16); }
	v_mul_f32_e32 v34, v18, v50
	v_mul_f32_e32 v35, v19, v51
	s_waitcnt lgkmcnt(0)
	v_add_f32_e32 v50, v52, v53
	ds_bpermute_b32 v51, v85, v50
	v_cndmask_b32_e64 v35, v35, -v35, s[2:3]
	v_cndmask_b32_e64 v34, v34, -v34, s[2:3]
	v_fma_f32 v46, v72, v48, v34
	v_fma_f32 v47, v73, v49, v35
	v_cvt_pk_bf16_f32 v34, v36, v37
	s_waitcnt lgkmcnt(0)
	v_add_f32_e32 v36, v50, v51
	v_fmamk_f32 v36, v36, 0x3c000000, v87
	v_mul_f32_e32 v37, 0x4f800000, v36
	v_cmp_gt_f32_e32 vcc, s34, v36
	v_cvt_pk_bf16_f32 v35, v42, v43
	v_lshl_add_u64 v[42:43], v[78:79], 0, v[68:69]
	v_cndmask_b32_e32 v48, v36, v37, vcc
	v_sqrt_f32_e32 v49, v48
	v_cvt_pk_bf16_f32 v36, v44, v45
	v_cvt_pk_bf16_f32 v37, v46, v47
	v_lshlrev_b32_e32 v68, 1, v74
	v_add_u32_e32 v44, -1, v49
	v_fma_f32 v45, -v44, v49, v48
	v_cmp_ge_f32_e64 s[0:1], 0, v45
	v_add_u32_e32 v45, 1, v49
	v_fma_f32 v46, -v45, v49, v48
	v_cndmask_b32_e64 v44, v49, v44, s[0:1]
	v_cmp_lt_f32_e64 s[0:1], 0, v46
	s_nop 1
	v_cndmask_b32_e64 v44, v44, v45, s[0:1]
	v_mul_f32_e32 v45, 0x37800000, v44
	v_cndmask_b32_e32 v44, v44, v45, vcc
	v_cmp_class_f32_e32 vcc, v48, v88
	s_nop 1
	v_cndmask_b32_e32 v44, v44, v48, vcc
	v_div_scale_f32 v45, s[0:1], v44, v44, 1.0
	v_rcp_f32_e32 v46, v45
	v_add_co_u32_e32 v42, vcc, s35, v42
	s_nop 1
	v_addc_co_u32_e32 v43, vcc, 0, v43, vcc
	global_store_dwordx4 v[42:43], v[34:37], off
	s_nop 1
	v_fma_f32 v34, -v45, v46, 1.0
	v_fmac_f32_e32 v46, v34, v46
	v_div_scale_f32 v34, vcc, 1.0, v44, 1.0
	v_mul_f32_e32 v35, v34, v46
	v_fma_f32 v36, -v45, v35, v34
	v_fmac_f32_e32 v35, v36, v46
	v_fma_f32 v34, -v45, v35, v34
	v_div_fmas_f32 v34, v34, v46, v35
	v_div_fixup_f32 v34, v34, v44, 1.0
	v_pk_mul_f32 v[46:47], v[34:35], v[62:63] op_sel_hi:[0,1]
	v_mul_f32_e32 v46, v2, v46
	v_mul_f32_e32 v47, v3, v47
	v_pk_mul_f32 v[36:37], v[34:35], v[76:77] op_sel_hi:[0,1]
	ds_bpermute_b32 v48, v84, v46
	ds_bpermute_b32 v49, v84, v47
	v_mul_f32_e32 v36, v0, v36
	v_mul_f32_e32 v37, v1, v37
	ds_bpermute_b32 v44, v84, v36
	ds_bpermute_b32 v45, v84, v37
	s_waitcnt lgkmcnt(2)
	v_mul_f32_e32 v22, v22, v48
	v_mul_f32_e32 v23, v23, v49
	v_cndmask_b32_e64 v23, v23, -v23, s[2:3]
	v_cndmask_b32_e64 v22, v22, -v22, s[2:3]
	s_waitcnt lgkmcnt(0)
	v_mul_f32_e32 v26, v26, v44
	v_mul_f32_e32 v27, v27, v45
	v_fma_f32 v22, v24, v46, v22
	v_fma_f32 v23, v25, v47, v23
	v_pk_mul_f32 v[24:25], v[34:35], v[58:59] op_sel_hi:[0,1]
	v_cndmask_b32_e64 v27, v27, -v27, s[2:3]
	v_cndmask_b32_e64 v26, v26, -v26, s[2:3]
	v_mul_f32_e32 v24, v8, v24
	v_mul_f32_e32 v25, v9, v25
	v_fma_f32 v26, v28, v36, v26
	v_fma_f32 v27, v29, v37, v27
	ds_bpermute_b32 v28, v84, v24
	ds_bpermute_b32 v29, v84, v25
	v_pk_mul_f32 v[34:35], v[34:35], v[54:55] op_sel_hi:[0,1]
	v_mul_f32_e32 v34, v10, v34
	v_mul_f32_e32 v35, v11, v35
	ds_bpermute_b32 v36, v84, v34
	ds_bpermute_b32 v37, v84, v35
	s_waitcnt lgkmcnt(2)
	v_mul_f32_e32 v16, v16, v28
	v_mul_f32_e32 v17, v17, v29
	v_cndmask_b32_e64 v17, v17, -v17, s[2:3]
	v_cndmask_b32_e64 v16, v16, -v16, s[2:3]
	v_fma_f32 v20, v20, v24, v16
	v_fma_f32 v21, v21, v25, v17
	s_waitcnt lgkmcnt(0)
	v_mul_f32_e32 v16, v18, v36
	v_mul_f32_e32 v17, v19, v37
	v_cvt_pk_bf16_f32 v18, v20, v21
	v_cndmask_b32_e64 v17, v17, -v17, s[2:3]
	v_cndmask_b32_e64 v16, v16, -v16, s[2:3]
	v_fma_f32 v24, v72, v34, v16
	v_fma_f32 v25, v73, v35, v17
	v_cvt_pk_bf16_f32 v16, v26, v27
	v_cvt_pk_bf16_f32 v17, v22, v23
	v_cvt_pk_bf16_f32 v19, v24, v25
	global_store_dwordx4 v[42:43], v[16:19], off offset:256
	v_lshl_or_b32 v22, v89, 8, v66
	s_nop 0
	v_lshl_add_u64 v[16:17], s[8:9], 0, v[68:69]
	v_mad_i64_i32 v[18:19], s[0:1], v22, s36, v[16:17]
	v_add_co_u32_e32 v20, vcc, s30, v18
	s_waitcnt vmcnt(9)
	global_store_short v[18:19], v38, off
	v_addc_co_u32_e32 v21, vcc, 0, v19, vcc
	global_store_short_d16_hi v[20:21], v38, off offset:512
	v_add_co_u32_e32 v20, vcc, s37, v18
	s_nop 1
	v_addc_co_u32_e32 v21, vcc, 0, v19, vcc
	global_store_short v[20:21], v39, off offset:1024
	v_add_co_u32_e32 v20, vcc, s38, v18
	s_nop 1
	v_addc_co_u32_e32 v21, vcc, 0, v19, vcc
	global_store_short_d16_hi v[20:21], v39, off offset:1536
	v_add_co_u32_e32 v20, vcc, s28, v18
	s_nop 1
	v_addc_co_u32_e32 v21, vcc, 0, v19, vcc
	global_store_short v[20:21], v40, off offset:2048
	v_add_co_u32_e32 v20, vcc, s39, v18
	s_nop 1
	v_addc_co_u32_e32 v21, vcc, 0, v19, vcc
	global_store_short_d16_hi v[20:21], v40, off offset:2560
	v_add_co_u32_e32 v20, vcc, s44, v18
	s_nop 1
	v_addc_co_u32_e32 v21, vcc, 0, v19, vcc
	v_add_co_u32_e32 v18, vcc, s45, v18
	global_store_short v[20:21], v41, off offset:3072
	s_nop 0
	v_addc_co_u32_e32 v19, vcc, 0, v19, vcc
	global_store_short_d16_hi v[18:19], v41, off offset:3584
	v_or_b32_e32 v18, 0x80, v22
	v_mad_i64_i32 v[16:17], s[0:1], v18, s36, v[16:17]
	v_add_co_u32_e32 v18, vcc, s30, v16
	global_store_short v[16:17], v30, off
	s_nop 0
	v_addc_co_u32_e32 v19, vcc, 0, v17, vcc
	global_store_short_d16_hi v[18:19], v30, off offset:512
	v_add_co_u32_e32 v18, vcc, s37, v16
	s_nop 1
	v_addc_co_u32_e32 v19, vcc, 0, v17, vcc
	global_store_short v[18:19], v31, off offset:1024
	v_add_co_u32_e32 v18, vcc, s38, v16
	s_nop 1
	v_addc_co_u32_e32 v19, vcc, 0, v17, vcc
	global_store_short_d16_hi v[18:19], v31, off offset:1536
	v_add_co_u32_e32 v18, vcc, s28, v16
	s_nop 1
	v_addc_co_u32_e32 v19, vcc, 0, v17, vcc
	global_store_short v[18:19], v32, off offset:2048
	v_add_co_u32_e32 v18, vcc, s39, v16
	s_nop 1
	v_addc_co_u32_e32 v19, vcc, 0, v17, vcc
	global_store_short_d16_hi v[18:19], v32, off offset:2560
	v_add_co_u32_e32 v18, vcc, 0x6000, v16
	s_nop 1
	v_addc_co_u32_e32 v19, vcc, 0, v17, vcc
	v_add_co_u32_e32 v16, vcc, 0x7000, v16
	global_store_short v[18:19], v33, off offset:3072
	s_nop 0
	v_addc_co_u32_e32 v17, vcc, 0, v17, vcc
	global_store_short_d16_hi v[16:17], v33, off offset:3584
	s_cbranch_scc1 .LBB0_296

; #define CONF_LOAD(DA, DG, CH) _Pragma("unroll") for (int k = 0; k < 8; ++k) { const int q = p0 - 15 + 8 * (CH) + k; const int qc = q < 0 ? 0 : (q >= L ? L - 1 : q); \
;                         const bf16_t* rowp = Zb + (size_t)(seq0 + qc) * INE; DA[k] = *(const unsigned*)(rowp + (unsigned)c0); DG[k] = *(const unsigned*)(rowp + 1024 + (unsigned)c0); }
; template <int PH>
; __device__ __forceinline__ void run_phase(const Args& args, LAS unsigned char* lds) {
;     ...
;                     CONF_LOAD(ca, cgt, 0)
; #pragma unroll
;                     for (int ch = 0; ch < 6; ++ch) {
;                         if (ch < 5) { CONF_LOAD(na, ng, ch + 1) }
;                         asm volatile("" ::: "memory");
; #pragma unroll
;                         for (int k = 0; k < 8; ++k) { const int i = 8 * ch + k; if (i < 46) { const int q = p0 - 15 + i; float u0 = 0.f, u1 = 0.f;
;                             if (q >= 0 && q < L) { u0 = bflo(ca[k]) * __builtin_amdgcn_rcpf(1.0f + __expf(-bflo(cgt[k]))); u1 = bfhi(ca[k]) * __builtin_amdgcn_rcpf(1.0f + __expf(-bfhi(cgt[k]))); }
.LBB0_299:
	s_add_i32 s8, s6, -15
	s_cmpk_lt_i32 s25, 0x400
	s_cselect_b32 s0, s14, 0xf0
	s_cselect_b32 s4, s15, 0x100
	s_and_b32 s5, s0, s8
	s_add_i32 s46, s5, -15
	s_add_i32 s7, s4, -1
	v_sub_co_u32_e64 v1, s[0:1], s5, 1
	s_min_i32 s9, s46, s7
	s_and_b64 s[26:27], s[0:1], exec
	s_cselect_b32 s9, 0, s9
	s_sub_i32 s9, s9, s5
	s_add_i32 s9, s8, s9
	s_add_i32 s39, s5, -14
	v_mad_i64_i32 v[2:3], s[26:27], s9, v236, v[202:203]
	s_min_i32 s9, s39, s7
	s_and_b64 s[26:27], s[0:1], exec
	s_cselect_b32 s9, 0, s9
	s_sub_i32 s9, s9, s5
	s_add_i32 s9, s8, s9
	s_add_i32 s37, s5, -13
	v_mad_i64_i32 v[4:5], s[26:27], s9, v236, v[202:203]
	s_min_i32 s9, s37, s7
	s_and_b64 s[26:27], s[0:1], exec
	s_cselect_b32 s9, 0, s9
	s_sub_i32 s9, s9, s5
	s_add_i32 s9, s8, s9
	s_add_i32 s35, s5, -12
	v_mad_i64_i32 v[6:7], s[26:27], s9, v236, v[202:203]
	s_min_i32 s9, s35, s7
	s_and_b64 s[26:27], s[0:1], exec
	s_cselect_b32 s9, 0, s9
	s_sub_i32 s9, s9, s5
	s_add_i32 s9, s8, s9
	s_add_i32 s31, s5, -11
	v_mad_i64_i32 v[8:9], s[26:27], s9, v236, v[202:203]
	s_min_i32 s9, s31, s7
	s_and_b64 s[26:27], s[0:1], exec
	s_cselect_b32 s9, 0, s9
	s_sub_i32 s9, s9, s5
	s_add_i32 s9, s8, s9
	s_add_i32 s29, s5, -10
	global_load_dword v30, v[2:3], off
	global_load_dword v32, v[2:3], off offset:2048
	global_load_dword v29, v[4:5], off
	global_load_dword v31, v[4:5], off offset:2048
	global_load_dword v20, v[6:7], off
	global_load_dword v28, v[6:7], off offset:2048
	global_load_dword v14, v[8:9], off
	global_load_dword v21, v[8:9], off offset:2048
	v_mad_i64_i32 v[2:3], s[26:27], s9, v236, v[202:203]
	s_min_i32 s9, s29, s7
	s_and_b64 s[26:27], s[0:1], exec
	s_cselect_b32 s9, 0, s9
	s_sub_i32 s9, s9, s5
	s_add_i32 s9, s8, s9
	v_mad_i64_i32 v[4:5], s[26:27], s9, v236, v[202:203]
	s_add_i32 s27, s5, -9
	s_min_i32 s9, s27, s7
	s_and_b64 s[44:45], s[0:1], exec
	s_cselect_b32 s9, 0, s9
	s_sub_i32 s9, s9, s5
	s_add_i32 s9, s8, s9
	v_mad_i64_i32 v[6:7], s[44:45], s9, v236, v[202:203]
	s_add_i32 s9, s5, -8
	s_min_i32 s26, s9, s7
	s_and_b64 s[44:45], s[0:1], exec
	s_cselect_b32 s26, 0, s26
	s_sub_i32 s26, s26, s5
	s_add_i32 s26, s8, s26
	s_add_i32 s38, s5, -7
	v_mad_i64_i32 v[10:11], s[44:45], s26, v236, v[202:203]
	s_min_i32 s26, s38, s7
	s_and_b64 s[44:45], s[0:1], exec
	s_cselect_b32 s26, 0, s26
	s_sub_i32 s26, s26, s5
	s_add_i32 s26, s8, s26
	s_add_i32 s36, s5, -6
	global_load_dword v26, v[2:3], off
	global_load_dword v27, v[2:3], off offset:2048
	global_load_dword v15, v[4:5], off
	global_load_dword v19, v[4:5], off offset:2048
	global_load_dword v8, v[6:7], off
	global_load_dword v18, v[6:7], off offset:2048
	global_load_dword v9, v[10:11], off
	global_load_dword v23, v[10:11], off offset:2048
	v_mad_i64_i32 v[2:3], s[44:45], s26, v236, v[202:203]
	s_min_i32 s26, s36, s7
	s_and_b64 s[44:45], s[0:1], exec
	s_cselect_b32 s26, 0, s26
	s_sub_i32 s26, s26, s5
	s_add_i32 s26, s8, s26
	s_add_i32 s34, s5, -5
	v_mad_i64_i32 v[4:5], s[44:45], s26, v236, v[202:203]
	s_min_i32 s26, s34, s7
	s_and_b64 s[44:45], s[0:1], exec
	s_cselect_b32 s26, 0, s26
	s_sub_i32 s26, s26, s5
	s_add_i32 s26, s8, s26
	s_add_i32 s30, s5, -4
	v_mad_i64_i32 v[10:11], s[44:45], s26, v236, v[202:203]
	s_min_i32 s26, s30, s7
	s_and_b64 s[44:45], s[0:1], exec
	s_cselect_b32 s26, 0, s26
	s_sub_i32 s26, s26, s5
	s_add_i32 s26, s8, s26
	s_add_i32 s28, s5, -3
	v_mad_i64_i32 v[24:25], s[44:45], s26, v236, v[202:203]
	s_min_i32 s26, s28, s7
	s_and_b64 s[44:45], s[0:1], exec
	s_cselect_b32 s26, 0, s26
	s_sub_i32 s26, s26, s5
	s_add_i32 s26, s8, s26
	global_load_dword v12, v[2:3], off
	global_load_dword v22, v[2:3], off offset:2048
	global_load_dword v13, v[4:5], off
	global_load_dword v17, v[4:5], off offset:2048
	global_load_dword v6, v[10:11], off
	global_load_dword v16, v[10:11], off offset:2048
	global_load_dword v7, v[24:25], off
	s_nop 0
	global_load_dword v11, v[24:25], off offset:2048
	v_mad_i64_i32 v[2:3], s[44:45], s26, v236, v[202:203]
	s_add_i32 s26, s5, -2
	s_min_i32 s47, s26, s7
	s_and_b64 s[44:45], s[0:1], exec
	s_cselect_b32 s44, 0, s47
	s_sub_i32 s44, s44, s5
	s_add_i32 s44, s8, s44
	v_mad_i64_i32 v[24:25], s[44:45], s44, v236, v[202:203]
	v_readfirstlane_b32 s44, v1
	s_min_i32 s44, s44, s7
	s_and_b64 s[0:1], s[0:1], exec
	s_cselect_b32 s0, 0, s44
	s_sub_i32 s0, s0, s5
	s_add_i32 s0, s8, s0
	v_mad_i64_i32 v[34:35], s[0:1], s0, v236, v[202:203]
	s_min_u32 s0, s5, s7
	s_sub_i32 s0, s0, s5
	s_add_i32 s0, s8, s0
	v_mad_i64_i32 v[36:37], s[0:1], s0, v236, v[202:203]
	global_load_dword v0, v[2:3], off
	global_load_dword v10, v[2:3], off offset:2048
	global_load_dword v5, v[24:25], off
	s_nop 0
	global_load_dword v25, v[24:25], off offset:2048
	s_nop 0
	global_load_dword v2, v[34:35], off
	global_load_dword v4, v[34:35], off offset:2048
	global_load_dword v3, v[36:37], off
	global_load_dword v24, v[36:37], off offset:2048
	s_cmp_ge_u32 s46, s4
	v_mov_b32_e32 v44, 0
	v_mov_b32_e32 v45, 0
	s_cbranch_scc1 .LBB0_301
	s_waitcnt vmcnt(0)
	v_lshlrev_b32_e32 v33, 16, v32
	v_and_b32_e32 v32, 0xffff0000, v32
	v_mul_f32_e32 v33, 0xbfb8aa3b, v33
	v_mul_f32_e32 v32, 0xbfb8aa3b, v32
	v_exp_f32_e32 v33, v33
	v_exp_f32_e32 v34, v32
	v_and_b32_e32 v35, 0xffff0000, v30
	v_add_f32_e32 v32, 1.0, v33
	v_add_f32_e32 v33, 1.0, v34
	v_rcp_f32_e32 v32, v32
	v_rcp_f32_e32 v33, v33
	v_lshlrev_b32_e32 v34, 16, v30
	v_mul_f32_e32 v44, v32, v34
	v_mul_f32_e32 v45, v33, v35
; #define CONF_LOAD(DA, DG, CH) _Pragma("unroll") for (int k = 0; k < 8; ++k) { const int q = p0 - 15 + 8 * (CH) + k; const int qc = q < 0 ? 0 : (q >= L ? L - 1 : q); \
;                         const bf16_t* rowp = Zb + (size_t)(seq0 + qc) * INE; DA[k] = *(const unsigned*)(rowp + (unsigned)c0); DG[k] = *(const unsigned*)(rowp + 1024 + (unsigned)c0); }
; template <int PH>
; __device__ __forceinline__ void run_phase(const Args& args, LAS unsigned char* lds) {
;     ...
;                     CONF_LOAD(ca, cgt, 0)
; #pragma unroll
;                     for (int ch = 0; ch < 6; ++ch) {
;                         if (ch < 5) { CONF_LOAD(na, ng, ch + 1) }
;                         asm volatile("" ::: "memory");
; #pragma unroll
;                         for (int k = 0; k < 8; ++k) { const int i = 8 * ch + k; if (i < 46) { const int q = p0 - 15 + i; float u0 = 0.f, u1 = 0.f;
;                             if (q >= 0 && q < L) { u0 = bflo(ca[k]) * __builtin_amdgcn_rcpf(1.0f + __expf(-bflo(cgt[k]))); u1 = bfhi(ca[k]) * __builtin_amdgcn_rcpf(1.0f + __expf(-bfhi(cgt[k]))); }
.LBB0_301:
	s_waitcnt vmcnt(0)
	v_mov_b32_e32 v30, 0
	s_cmp_ge_u32 s39, s4
	v_mov_b32_e32 v38, 0
	v_mov_b32_e32 v39, 0
	s_cbranch_scc1 .LBB0_303
	v_lshlrev_b32_e32 v32, 16, v31
	v_and_b32_e32 v31, 0xffff0000, v31
	v_mul_f32_e32 v32, 0xbfb8aa3b, v32
	v_mul_f32_e32 v31, 0xbfb8aa3b, v31
	v_exp_f32_e32 v32, v32
	v_exp_f32_e32 v31, v31
	v_lshlrev_b32_e32 v34, 16, v29
	v_and_b32_e32 v35, 0xffff0000, v29
	v_add_f32_e32 v32, 1.0, v32
	v_add_f32_e32 v31, 1.0, v31
	v_rcp_f32_e32 v32, v32
	v_rcp_f32_e32 v33, v31
	s_nop 0
	v_mul_f32_e32 v38, v32, v34
	v_mul_f32_e32 v39, v33, v35
.LBB0_303:
	s_cmp_ge_u32 s37, s4
	v_mov_b32_e32 v31, 0
	s_cbranch_scc1 .LBB0_305
	v_lshlrev_b32_e32 v29, 16, v28
	v_and_b32_e32 v28, 0xffff0000, v28
	v_mul_f32_e32 v29, 0xbfb8aa3b, v29
	v_mul_f32_e32 v28, 0xbfb8aa3b, v28
	v_exp_f32_e32 v29, v29
	v_exp_f32_e32 v30, v28
	v_and_b32_e32 v31, 0xffff0000, v20
	v_add_f32_e32 v28, 1.0, v29
	v_add_f32_e32 v29, 1.0, v30
	v_rcp_f32_e32 v28, v28
	v_rcp_f32_e32 v29, v29
	v_lshlrev_b32_e32 v30, 16, v20
	v_mul_f32_e32 v30, v28, v30
	v_mul_f32_e32 v31, v29, v31
.LBB0_305:
	v_mov_b32_e32 v20, 0
	s_cmp_ge_u32 s35, s4
	v_mov_b32_e32 v32, 0
	v_mov_b32_e32 v33, 0
	s_cbranch_scc1 .LBB0_307
	v_lshlrev_b32_e32 v28, 16, v21
	v_and_b32_e32 v21, 0xffff0000, v21
	v_mul_f32_e32 v28, 0xbfb8aa3b, v28
	v_mul_f32_e32 v21, 0xbfb8aa3b, v21
	v_exp_f32_e32 v28, v28
	v_exp_f32_e32 v21, v21
	v_lshlrev_b32_e32 v32, 16, v14
	v_and_b32_e32 v33, 0xffff0000, v14
	v_add_f32_e32 v28, 1.0, v28
	v_add_f32_e32 v21, 1.0, v21
	v_rcp_f32_e32 v28, v28
	v_rcp_f32_e32 v29, v21
	s_nop 0
	v_mul_f32_e32 v32, v28, v32
	v_mul_f32_e32 v33, v29, v33
.LBB0_307:
	s_cmp_ge_u32 s31, s4
	v_mov_b32_e32 v21, 0
	s_cbranch_scc1 .LBB0_309
	v_lshlrev_b32_e32 v14, 16, v27
	v_mul_f32_e32 v14, 0xbfb8aa3b, v14
	v_and_b32_e32 v20, 0xffff0000, v27
	v_exp_f32_e32 v14, v14
	v_mul_f32_e32 v20, 0xbfb8aa3b, v20
	v_exp_f32_e32 v21, v20
	v_lshlrev_b32_e32 v28, 16, v26
	v_add_f32_e32 v14, 1.0, v14
	v_rcp_f32_e32 v20, v14
	v_add_f32_e32 v14, 1.0, v21
	v_rcp_f32_e32 v21, v14
	v_and_b32_e32 v29, 0xffff0000, v26
	v_mul_f32_e32 v20, v20, v28
	v_mul_f32_e32 v21, v21, v29
.LBB0_309:
	v_mov_b32_e32 v14, 0
	s_cmp_ge_u32 s29, s4
	v_mov_b32_e32 v28, 0
	v_mov_b32_e32 v29, 0
	s_cbranch_scc1 .LBB0_311
	v_lshlrev_b32_e32 v26, 16, v19
	v_and_b32_e32 v19, 0xffff0000, v19
	v_mul_f32_e32 v26, 0xbfb8aa3b, v26
	v_mul_f32_e32 v19, 0xbfb8aa3b, v19
	v_exp_f32_e32 v26, v26
	v_exp_f32_e32 v19, v19
	v_lshlrev_b32_e32 v28, 16, v15
	v_and_b32_e32 v29, 0xffff0000, v15
	v_add_f32_e32 v26, 1.0, v26
	v_add_f32_e32 v19, 1.0, v19
	v_rcp_f32_e32 v26, v26
	v_rcp_f32_e32 v27, v19
	s_nop 0
	v_mul_f32_e32 v28, v26, v28
	v_mul_f32_e32 v29, v27, v29
.LBB0_311:
	s_cmp_ge_u32 s27, s4
	v_mov_b32_e32 v15, 0
	s_cbranch_scc1 .LBB0_313
	v_lshlrev_b32_e32 v14, 16, v18
	v_and_b32_e32 v15, 0xffff0000, v18
	v_mul_f32_e32 v14, 0xbfb8aa3b, v14
	v_mul_f32_e32 v15, 0xbfb8aa3b, v15
	v_exp_f32_e32 v14, v14
	v_exp_f32_e32 v15, v15
	v_lshlrev_b32_e32 v18, 16, v8
	v_and_b32_e32 v19, 0xffff0000, v8
	v_add_f32_e32 v14, 1.0, v14
	v_add_f32_e32 v15, 1.0, v15
	v_rcp_f32_e32 v14, v14
	v_rcp_f32_e32 v15, v15
	s_nop 0
	v_mul_f32_e32 v14, v14, v18
	v_mul_f32_e32 v15, v15, v19
.LBB0_313:
	v_mov_b32_e32 v8, 0
	s_cmp_ge_u32 s9, s4
	v_mov_b32_e32 v18, 0
	v_mov_b32_e32 v19, 0
	s_cbranch_scc1 .LBB0_315
	v_lshlrev_b32_e32 v18, 16, v23
	v_and_b32_e32 v19, 0xffff0000, v23
	v_mul_f32_e32 v18, 0xbfb8aa3b, v18
	v_mul_f32_e32 v19, 0xbfb8aa3b, v19
	v_exp_f32_e32 v18, v18
	v_exp_f32_e32 v19, v19
	v_lshlrev_b32_e32 v26, 16, v9
	v_and_b32_e32 v27, 0xffff0000, v9
	v_add_f32_e32 v18, 1.0, v18
	v_add_f32_e32 v19, 1.0, v19
	v_rcp_f32_e32 v18, v18
	v_rcp_f32_e32 v19, v19
	s_nop 0
	v_mul_f32_e32 v18, v18, v26
	v_mul_f32_e32 v19, v19, v27
.LBB0_315:
	s_or_b32 s39, s5, 1
	s_min_u32 s0, s39, s7
	s_sub_i32 s0, s0, s5
	s_add_i32 s0, s6, s0
	s_add_i32 s0, s0, -15
	v_mad_i64_i32 v[34:35], s[0:1], s0, v236, v[202:203]
	s_or_b32 s37, s5, 2
	s_min_u32 s0, s37, s7
	s_sub_i32 s0, s0, s5
	s_add_i32 s0, s6, s0
	s_add_i32 s0, s0, -15
	v_mad_i64_i32 v[40:41], s[0:1], s0, v236, v[202:203]
	s_or_b32 s35, s5, 3
	s_min_u32 s0, s35, s7
	s_sub_i32 s0, s0, s5
	s_add_i32 s0, s6, s0
	s_add_i32 s0, s0, -15
	v_mad_i64_i32 v[42:43], s[0:1], s0, v236, v[202:203]
	s_or_b32 s31, s5, 4
	s_min_u32 s0, s31, s7
	s_sub_i32 s0, s0, s5
	s_add_i32 s0, s6, s0
	s_add_i32 s0, s0, -15
	v_mad_i64_i32 v[46:47], s[0:1], s0, v236, v[202:203]
	s_or_b32 s29, s5, 5
	s_min_u32 s0, s29, s7
	s_sub_i32 s0, s0, s5
	s_add_i32 s0, s6, s0
	s_add_i32 s0, s0, -15
	global_load_dword v26, v[34:35], off
	global_load_dword v27, v[34:35], off offset:2048
	global_load_dword v37, v[40:41], off
	global_load_dword v52, v[40:41], off offset:2048
	s_nop 0
	global_load_dword v34, v[42:43], off
	global_load_dword v36, v[42:43], off offset:2048
	global_load_dword v35, v[46:47], off
	s_nop 0
	global_load_dword v43, v[46:47], off offset:2048
	v_mad_i64_i32 v[46:47], s[0:1], s0, v236, v[202:203]
	s_or_b32 s27, s5, 6
	s_min_u32 s0, s27, s7
	s_sub_i32 s0, s0, s5
	s_add_i32 s0, s6, s0
	s_add_i32 s0, s0, -15
	v_mad_i64_i32 v[48:49], s[0:1], s0, v236, v[202:203]
	s_or_b32 s9, s5, 7
	s_min_u32 s0, s9, s7
	s_sub_i32 s0, s0, s5
	s_add_i32 s0, s6, s0
	s_add_i32 s0, s0, -15
	v_mad_i64_i32 v[50:51], s[0:1], s0, v236, v[202:203]
	s_or_b32 s0, s5, 8
	s_min_u32 s1, s0, s7
	s_sub_i32 s1, s1, s5
	s_add_i32 s1, s6, s1
	s_add_i32 s1, s1, -15
	v_mad_i64_i32 v[54:55], s[44:45], s1, v236, v[202:203]
	global_load_dword v40, v[46:47], off
	global_load_dword v42, v[46:47], off offset:2048
	global_load_dword v41, v[48:49], off
	s_nop 0
	global_load_dword v49, v[48:49], off offset:2048
	s_nop 0
	global_load_dword v46, v[50:51], off
	global_load_dword v48, v[50:51], off offset:2048
	global_load_dword v47, v[54:55], off
	s_nop 0
	global_load_dword v50, v[54:55], off offset:2048
	s_cmp_ge_u32 s38, s4
	v_mov_b32_e32 v9, 0
	s_cbranch_scc1 .LBB0_317
	v_lshlrev_b32_e32 v8, 16, v22
	v_and_b32_e32 v9, 0xffff0000, v22
	v_mul_f32_e32 v8, 0xbfb8aa3b, v8
	v_mul_f32_e32 v9, 0xbfb8aa3b, v9
	v_exp_f32_e32 v8, v8
	v_exp_f32_e32 v9, v9
	v_lshlrev_b32_e32 v22, 16, v12
	v_and_b32_e32 v23, 0xffff0000, v12
	v_add_f32_e32 v8, 1.0, v8
	v_add_f32_e32 v9, 1.0, v9
	v_rcp_f32_e32 v8, v8
	v_rcp_f32_e32 v9, v9
	s_nop 0
	v_mul_f32_e32 v8, v8, v22
	v_mul_f32_e32 v9, v9, v23
; #define CONF_LOAD(DA, DG, CH) _Pragma("unroll") for (int k = 0; k < 8; ++k) { const int q = p0 - 15 + 8 * (CH) + k; const int qc = q < 0 ? 0 : (q >= L ? L - 1 : q); \
;                         const bf16_t* rowp = Zb + (size_t)(seq0 + qc) * INE; DA[k] = *(const unsigned*)(rowp + (unsigned)c0); DG[k] = *(const unsigned*)(rowp + 1024 + (unsigned)c0); }
; template <int PH>
; __device__ __forceinline__ void run_phase(const Args& args, LAS unsigned char* lds) {
;     ...
;                     CONF_LOAD(ca, cgt, 0)
; #pragma unroll
;                     for (int ch = 0; ch < 6; ++ch) {
;                         if (ch < 5) { CONF_LOAD(na, ng, ch + 1) }
;                         asm volatile("" ::: "memory");
; #pragma unroll
;                         for (int k = 0; k < 8; ++k) { const int i = 8 * ch + k; if (i < 46) { const int q = p0 - 15 + i; float u0 = 0.f, u1 = 0.f;
;                             if (q >= 0 && q < L) { u0 = bflo(ca[k]) * __builtin_amdgcn_rcpf(1.0f + __expf(-bflo(cgt[k]))); u1 = bfhi(ca[k]) * __builtin_amdgcn_rcpf(1.0f + __expf(-bfhi(cgt[k]))); }
.LBB0_317:
	v_mov_b32_e32 v12, 0
	s_cmp_ge_u32 s36, s4
	v_mov_b32_e32 v22, 0
	v_mov_b32_e32 v23, 0
	s_cbranch_scc1 .LBB0_319
	v_lshlrev_b32_e32 v22, 16, v17
	v_and_b32_e32 v17, 0xffff0000, v17
	v_mul_f32_e32 v22, 0xbfb8aa3b, v22
	v_mul_f32_e32 v17, 0xbfb8aa3b, v17
	v_exp_f32_e32 v22, v22
	v_exp_f32_e32 v17, v17
	v_lshlrev_b32_e32 v54, 16, v13
	v_and_b32_e32 v55, 0xffff0000, v13
	v_add_f32_e32 v22, 1.0, v22
	v_add_f32_e32 v17, 1.0, v17
	v_rcp_f32_e32 v22, v22
	v_rcp_f32_e32 v23, v17
	s_nop 0
	v_mul_f32_e32 v22, v22, v54
	v_mul_f32_e32 v23, v23, v55
.LBB0_319:
	s_cmp_ge_u32 s34, s4
	v_mov_b32_e32 v13, 0
	s_cbranch_scc1 .LBB0_321
	v_lshlrev_b32_e32 v12, 16, v16
	v_and_b32_e32 v13, 0xffff0000, v16
	v_mul_f32_e32 v12, 0xbfb8aa3b, v12
	v_mul_f32_e32 v13, 0xbfb8aa3b, v13
	v_exp_f32_e32 v12, v12
	v_exp_f32_e32 v13, v13
	v_lshlrev_b32_e32 v16, 16, v6
	v_and_b32_e32 v17, 0xffff0000, v6
	v_add_f32_e32 v12, 1.0, v12
	v_add_f32_e32 v13, 1.0, v13
	v_rcp_f32_e32 v12, v12
	v_rcp_f32_e32 v13, v13
	s_nop 0
	v_mul_f32_e32 v12, v12, v16
	v_mul_f32_e32 v13, v13, v17
.LBB0_321:
	v_mov_b32_e32 v6, 0
	s_cmp_ge_u32 s30, s4
	v_mov_b32_e32 v16, 0
	v_mov_b32_e32 v17, 0
	s_cbranch_scc1 .LBB0_323
	v_lshlrev_b32_e32 v16, 16, v11
	v_and_b32_e32 v11, 0xffff0000, v11
	v_mul_f32_e32 v16, 0xbfb8aa3b, v16
	v_mul_f32_e32 v11, 0xbfb8aa3b, v11
	v_exp_f32_e32 v16, v16
	v_exp_f32_e32 v11, v11
	v_lshlrev_b32_e32 v54, 16, v7
	v_and_b32_e32 v55, 0xffff0000, v7
	v_add_f32_e32 v16, 1.0, v16
	v_add_f32_e32 v11, 1.0, v11
	v_rcp_f32_e32 v16, v16
	v_rcp_f32_e32 v17, v11
	s_nop 0
	v_mul_f32_e32 v16, v16, v54
	v_mul_f32_e32 v17, v17, v55
.LBB0_323:
	s_cmp_ge_u32 s28, s4
	v_mov_b32_e32 v7, 0
	s_cbranch_scc1 .LBB0_325
	v_lshlrev_b32_e32 v6, 16, v10
	v_and_b32_e32 v7, 0xffff0000, v10
	v_mul_f32_e32 v6, 0xbfb8aa3b, v6
	v_mul_f32_e32 v7, 0xbfb8aa3b, v7
	v_exp_f32_e32 v6, v6
	v_exp_f32_e32 v7, v7
	v_lshlrev_b32_e32 v10, 16, v0
	v_and_b32_e32 v11, 0xffff0000, v0
	v_add_f32_e32 v6, 1.0, v6
	v_add_f32_e32 v7, 1.0, v7
	v_rcp_f32_e32 v6, v6
	v_rcp_f32_e32 v7, v7
	s_nop 0
	v_mul_f32_e32 v6, v6, v10
	v_mul_f32_e32 v7, v7, v11
.LBB0_325:
	v_mov_b32_e32 v0, 0
	s_cmp_ge_u32 s26, s4
	v_mov_b32_e32 v10, 0
	v_mov_b32_e32 v11, 0
	s_cbranch_scc1 .LBB0_327
	v_lshlrev_b32_e32 v10, 16, v25
	v_and_b32_e32 v11, 0xffff0000, v25
	v_mul_f32_e32 v10, 0xbfb8aa3b, v10
	v_mul_f32_e32 v11, 0xbfb8aa3b, v11
	v_exp_f32_e32 v10, v10
	v_exp_f32_e32 v11, v11
	v_lshlrev_b32_e32 v54, 16, v5
	v_and_b32_e32 v55, 0xffff0000, v5
	v_add_f32_e32 v10, 1.0, v10
	v_add_f32_e32 v11, 1.0, v11
	v_rcp_f32_e32 v10, v10
	v_rcp_f32_e32 v11, v11
	s_nop 0
	v_mul_f32_e32 v10, v10, v54
	v_mul_f32_e32 v11, v11, v55
.LBB0_327:
	v_cmp_le_u32_e32 vcc, s4, v1
	v_mov_b32_e32 v1, 0
	s_cbranch_vccnz .LBB0_329
	v_lshlrev_b32_e32 v0, 16, v4
	v_and_b32_e32 v1, 0xffff0000, v4
	v_mul_f32_e32 v0, 0xbfb8aa3b, v0
	v_mul_f32_e32 v1, 0xbfb8aa3b, v1
	v_exp_f32_e32 v0, v0
	v_exp_f32_e32 v1, v1
	v_lshlrev_b32_e32 v4, 16, v2
	v_and_b32_e32 v5, 0xffff0000, v2
	v_add_f32_e32 v0, 1.0, v0
	v_add_f32_e32 v1, 1.0, v1
	v_rcp_f32_e32 v0, v0
	v_rcp_f32_e32 v1, v1
	s_nop 0
	v_mul_f32_e32 v0, v0, v4
	v_mul_f32_e32 v1, v1, v5
.LBB0_329:
	v_mov_b32_e32 v2, 0
	s_cmp_ge_u32 s5, s4
	v_mov_b32_e32 v4, 0
	v_mov_b32_e32 v5, 0
	s_cbranch_scc1 .LBB0_331
	v_lshlrev_b32_e32 v4, 16, v24
	v_and_b32_e32 v5, 0xffff0000, v24
	v_mul_f32_e32 v4, 0xbfb8aa3b, v4
	v_mul_f32_e32 v5, 0xbfb8aa3b, v5
	v_exp_f32_e32 v4, v4
	v_exp_f32_e32 v5, v5
	v_lshlrev_b32_e32 v24, 16, v3
	v_and_b32_e32 v25, 0xffff0000, v3
	v_add_f32_e32 v4, 1.0, v4
	v_add_f32_e32 v5, 1.0, v5
	v_rcp_f32_e32 v4, v4
	v_rcp_f32_e32 v5, v5
	s_nop 0
	v_mul_f32_e32 v4, v4, v24
	v_mul_f32_e32 v5, v5, v25
.LBB0_331:
	s_or_b32 s44, s5, 9
	s_min_u32 s1, s44, s7
	s_sub_i32 s1, s1, s5
	s_add_i32 s1, s6, s1
	s_add_i32 s1, s1, -15
	s_or_b32 s38, s5, 10
	v_mad_i64_i32 v[24:25], s[46:47], s1, v236, v[202:203]
	s_min_u32 s1, s38, s7
	s_sub_i32 s1, s1, s5
	s_add_i32 s1, s6, s1
	s_add_i32 s1, s1, -15
	s_or_b32 s36, s5, 11
	v_mad_i64_i32 v[54:55], s[46:47], s1, v236, v[202:203]
	s_min_u32 s1, s36, s7
	s_sub_i32 s1, s1, s5
	s_add_i32 s1, s6, s1
	s_add_i32 s1, s1, -15
	s_or_b32 s34, s5, 12
	v_mad_i64_i32 v[58:59], s[46:47], s1, v236, v[202:203]
	s_min_u32 s1, s34, s7
	s_sub_i32 s1, s1, s5
	s_add_i32 s1, s6, s1
	s_add_i32 s1, s1, -15
	s_or_b32 s30, s5, 13
	v_mad_i64_i32 v[60:61], s[46:47], s1, v236, v[202:203]
	s_min_u32 s1, s30, s7
	s_sub_i32 s1, s1, s5
	s_add_i32 s1, s6, s1
	s_add_i32 s1, s1, -15
	s_or_b32 s28, s5, 14
	global_load_dword v53, v[24:25], off
	global_load_dword v68, v[24:25], off offset:2048
	global_load_dword v51, v[54:55], off
	global_load_dword v57, v[54:55], off offset:2048
	s_nop 0
	global_load_dword v54, v[58:59], off
	s_waitcnt lgkmcnt(0)
	global_load_dword v56, v[58:59], off offset:2048
	global_load_dword v55, v[60:61], off
	s_nop 0
	global_load_dword v61, v[60:61], off offset:2048
	v_mad_i64_i32 v[24:25], s[46:47], s1, v236, v[202:203]
	s_min_u32 s1, s28, s7
	s_sub_i32 s1, s1, s5
	s_add_i32 s1, s6, s1
	s_add_i32 s1, s1, -15
	s_or_b32 s26, s5, 15
	v_mad_i64_i32 v[62:63], s[46:47], s1, v236, v[202:203]
	s_min_u32 s1, s26, s7
	s_sub_i32 s1, s1, s5
	s_add_i32 s1, s6, s1
	s_add_i32 s1, s1, -15
	v_mad_i64_i32 v[66:67], s[46:47], s1, v236, v[202:203]
	s_add_i32 s1, s5, 16
	s_min_u32 s45, s1, s7
	s_sub_i32 s45, s45, s5
	s_add_i32 s45, s6, s45
	s_add_i32 s45, s45, -15
	v_mad_i64_i32 v[70:71], s[46:47], s45, v236, v[202:203]
	global_load_dword v58, v[24:25], off
	global_load_dword v60, v[24:25], off offset:2048
	global_load_dword v59, v[62:63], off
	global_load_dword v65, v[62:63], off offset:2048
	s_nop 0
	global_load_dword v62, v[66:67], off
	global_load_dword v64, v[66:67], off offset:2048
	global_load_dword v63, v[70:71], off
	s_nop 0
	global_load_dword v66, v[70:71], off offset:2048
	s_cmp_ge_u32 s39, s4
	v_mov_b32_e32 v3, 0
	s_cbranch_scc1 .LBB0_333
	s_waitcnt vmcnt(30)
	v_lshlrev_b32_e32 v2, 16, v27
	v_and_b32_e32 v3, 0xffff0000, v27
	v_mul_f32_e32 v2, 0xbfb8aa3b, v2
	v_mul_f32_e32 v3, 0xbfb8aa3b, v3
	v_exp_f32_e32 v2, v2
	v_exp_f32_e32 v3, v3
	v_lshlrev_b32_e32 v24, 16, v26
	v_and_b32_e32 v25, 0xffff0000, v26
	v_add_f32_e32 v2, 1.0, v2
	v_add_f32_e32 v3, 1.0, v3
	v_rcp_f32_e32 v2, v2
	v_rcp_f32_e32 v3, v3
	s_nop 0
	v_mul_f32_e32 v2, v2, v24
	v_mul_f32_e32 v3, v3, v25
; #define CONF_LOAD(DA, DG, CH) _Pragma("unroll") for (int k = 0; k < 8; ++k) { const int q = p0 - 15 + 8 * (CH) + k; const int qc = q < 0 ? 0 : (q >= L ? L - 1 : q); \
;                         const bf16_t* rowp = Zb + (size_t)(seq0 + qc) * INE; DA[k] = *(const unsigned*)(rowp + (unsigned)c0); DG[k] = *(const unsigned*)(rowp + 1024 + (unsigned)c0); }
; template <int PH>
; __device__ __forceinline__ void run_phase(const Args& args, LAS unsigned char* lds) {
;     ...
;                     CONF_LOAD(ca, cgt, 0)
; #pragma unroll
;                     for (int ch = 0; ch < 6; ++ch) {
;                         if (ch < 5) { CONF_LOAD(na, ng, ch + 1) }
;                         asm volatile("" ::: "memory");
; #pragma unroll
;                         for (int k = 0; k < 8; ++k) { const int i = 8 * ch + k; if (i < 46) { const int q = p0 - 15 + i; float u0 = 0.f, u1 = 0.f;
;                             if (q >= 0 && q < L) { u0 = bflo(ca[k]) * __builtin_amdgcn_rcpf(1.0f + __expf(-bflo(cgt[k]))); u1 = bfhi(ca[k]) * __builtin_amdgcn_rcpf(1.0f + __expf(-bfhi(cgt[k]))); }
.LBB0_333:
	v_mov_b32_e32 v24, 0
	s_cmp_ge_u32 s37, s4
	s_waitcnt vmcnt(31)
	v_mov_b32_e32 v26, 0
	s_waitcnt vmcnt(30)
	v_mov_b32_e32 v27, 0
	s_cbranch_scc1 .LBB0_335
	s_waitcnt vmcnt(28)
	v_lshlrev_b32_e32 v25, 16, v52
	v_mul_f32_e32 v25, 0xbfb8aa3b, v25
	v_and_b32_e32 v26, 0xffff0000, v52
	v_exp_f32_e32 v25, v25
	v_mul_f32_e32 v26, 0xbfb8aa3b, v26
	v_exp_f32_e32 v27, v26
	v_lshlrev_b32_e32 v70, 16, v37
	v_add_f32_e32 v25, 1.0, v25
	v_rcp_f32_e32 v26, v25
	v_add_f32_e32 v25, 1.0, v27
	v_rcp_f32_e32 v27, v25
	v_and_b32_e32 v71, 0xffff0000, v37
	v_mul_f32_e32 v26, v26, v70
	v_mul_f32_e32 v27, v27, v71
.LBB0_335:
	s_cmp_ge_u32 s35, s4
	v_mov_b32_e32 v25, 0
	s_cbranch_scc1 .LBB0_337
	s_waitcnt vmcnt(26)
	v_lshlrev_b32_e32 v24, 16, v36
	v_and_b32_e32 v25, 0xffff0000, v36
	v_mul_f32_e32 v24, 0xbfb8aa3b, v24
	v_mul_f32_e32 v25, 0xbfb8aa3b, v25
	v_exp_f32_e32 v24, v24
	v_exp_f32_e32 v25, v25
	v_lshlrev_b32_e32 v36, 16, v34
	v_and_b32_e32 v37, 0xffff0000, v34
	v_add_f32_e32 v24, 1.0, v24
	v_add_f32_e32 v25, 1.0, v25
	v_rcp_f32_e32 v24, v24
	v_rcp_f32_e32 v25, v25
	s_nop 0
	v_mul_f32_e32 v24, v24, v36
	v_mul_f32_e32 v25, v25, v37
.LBB0_337:
	s_waitcnt vmcnt(27)
	v_mov_b32_e32 v34, 0
	s_cmp_ge_u32 s31, s4
	s_waitcnt vmcnt(26)
	v_mov_b32_e32 v36, 0
	v_mov_b32_e32 v37, 0
	s_cbranch_scc1 .LBB0_339
	s_waitcnt vmcnt(24)
	v_lshlrev_b32_e32 v36, 16, v43
	v_and_b32_e32 v37, 0xffff0000, v43
	v_mul_f32_e32 v36, 0xbfb8aa3b, v36
	v_mul_f32_e32 v37, 0xbfb8aa3b, v37
	v_exp_f32_e32 v36, v36
	v_exp_f32_e32 v37, v37
	v_lshlrev_b32_e32 v70, 16, v35
	v_and_b32_e32 v71, 0xffff0000, v35
	v_add_f32_e32 v36, 1.0, v36
	v_add_f32_e32 v37, 1.0, v37
	v_rcp_f32_e32 v36, v36
	v_rcp_f32_e32 v37, v37
	s_nop 0
	v_mul_f32_e32 v36, v36, v70
	v_mul_f32_e32 v37, v37, v71
.LBB0_339:
	s_cmp_ge_u32 s29, s4
	s_waitcnt vmcnt(25)
	v_mov_b32_e32 v35, 0
	s_cbranch_scc1 .LBB0_341
	s_waitcnt vmcnt(22)
	v_lshlrev_b32_e32 v34, 16, v42
	v_and_b32_e32 v35, 0xffff0000, v42
	v_mul_f32_e32 v34, 0xbfb8aa3b, v34
	v_mul_f32_e32 v35, 0xbfb8aa3b, v35
	v_exp_f32_e32 v34, v34
	v_exp_f32_e32 v35, v35
	v_lshlrev_b32_e32 v42, 16, v40
	v_and_b32_e32 v43, 0xffff0000, v40
	v_add_f32_e32 v34, 1.0, v34
	v_add_f32_e32 v35, 1.0, v35
	v_rcp_f32_e32 v34, v34
	v_rcp_f32_e32 v35, v35
	s_nop 0
	v_mul_f32_e32 v34, v34, v42
	v_mul_f32_e32 v35, v35, v43
.LBB0_341:
	s_waitcnt vmcnt(23)
	v_mov_b32_e32 v40, 0
	s_cmp_ge_u32 s27, s4
	s_waitcnt vmcnt(22)
	v_mov_b32_e32 v42, 0
	v_mov_b32_e32 v43, 0
	s_cbranch_scc1 .LBB0_343
	s_waitcnt vmcnt(20)
	v_lshlrev_b32_e32 v42, 16, v49
	v_and_b32_e32 v43, 0xffff0000, v49
	v_mul_f32_e32 v42, 0xbfb8aa3b, v42
	v_mul_f32_e32 v43, 0xbfb8aa3b, v43
	v_exp_f32_e32 v42, v42
	v_exp_f32_e32 v43, v43
	v_lshlrev_b32_e32 v70, 16, v41
	v_and_b32_e32 v71, 0xffff0000, v41
	v_add_f32_e32 v42, 1.0, v42
	v_add_f32_e32 v43, 1.0, v43
	v_rcp_f32_e32 v42, v42
	v_rcp_f32_e32 v43, v43
	s_nop 0
	v_mul_f32_e32 v42, v42, v70
	v_mul_f32_e32 v43, v43, v71
.LBB0_343:
	s_cmp_ge_u32 s9, s4
	s_waitcnt vmcnt(21)
	v_mov_b32_e32 v41, 0
	s_cbranch_scc1 .LBB0_345
	s_waitcnt vmcnt(18)
	v_lshlrev_b32_e32 v40, 16, v48
	v_and_b32_e32 v41, 0xffff0000, v48
	v_mul_f32_e32 v40, 0xbfb8aa3b, v40
	v_mul_f32_e32 v41, 0xbfb8aa3b, v41
	v_exp_f32_e32 v40, v40
	v_exp_f32_e32 v41, v41
	v_lshlrev_b32_e32 v48, 16, v46
	v_and_b32_e32 v49, 0xffff0000, v46
	v_add_f32_e32 v40, 1.0, v40
	v_add_f32_e32 v41, 1.0, v41
	v_rcp_f32_e32 v40, v40
	v_rcp_f32_e32 v41, v41
	s_nop 0
	v_mul_f32_e32 v40, v40, v48
	v_mul_f32_e32 v41, v41, v49
.LBB0_345:
	s_waitcnt vmcnt(19)
	v_mov_b32_e32 v46, 0
	s_cmp_ge_u32 s0, s4
	s_waitcnt vmcnt(18)
	v_mov_b32_e32 v48, 0
	v_mov_b32_e32 v49, 0
	s_cbranch_scc1 .LBB0_347
	s_waitcnt vmcnt(16)
	v_lshlrev_b32_e32 v48, 16, v50
	v_and_b32_e32 v49, 0xffff0000, v50
	v_mul_f32_e32 v48, 0xbfb8aa3b, v48
	v_mul_f32_e32 v49, 0xbfb8aa3b, v49
	v_exp_f32_e32 v48, v48
	v_exp_f32_e32 v49, v49
	v_lshlrev_b32_e32 v70, 16, v47
	v_and_b32_e32 v71, 0xffff0000, v47
	v_add_f32_e32 v48, 1.0, v48
	v_add_f32_e32 v49, 1.0, v49
	v_rcp_f32_e32 v48, v48
	v_rcp_f32_e32 v49, v49
	s_nop 0
	v_mul_f32_e32 v48, v48, v70
	v_mul_f32_e32 v49, v49, v71
.LBB0_347:
	s_add_i32 s39, s5, 17
	s_min_u32 s0, s39, s7
	s_sub_i32 s0, s0, s5
	s_add_i32 s0, s6, s0
	s_add_i32 s0, s0, -15
	s_add_i32 s37, s5, 18
	v_mad_i64_i32 v[70:71], s[46:47], s0, v236, v[202:203]
	s_min_u32 s0, s37, s7
	s_sub_i32 s0, s0, s5
	s_add_i32 s0, s6, s0
	s_add_i32 s0, s0, -15
	s_add_i32 s35, s5, 19
	v_mad_i64_i32 v[72:73], s[46:47], s0, v236, v[202:203]
	s_min_u32 s0, s35, s7
	s_sub_i32 s0, s0, s5
	s_add_i32 s0, s6, s0
	s_add_i32 s0, s0, -15
	s_add_i32 s31, s5, 20
	v_mad_i64_i32 v[74:75], s[46:47], s0, v236, v[202:203]
	s_min_u32 s0, s31, s7
	s_sub_i32 s0, s0, s5
	s_add_i32 s0, s6, s0
	s_add_i32 s0, s0, -15
	s_add_i32 s29, s5, 21
	v_mad_i64_i32 v[76:77], s[46:47], s0, v236, v[202:203]
	s_min_u32 s0, s29, s7
	s_sub_i32 s0, s0, s5
	s_add_i32 s0, s6, s0
	s_add_i32 s0, s0, -15
	s_add_i32 s27, s5, 22
	v_mad_i64_i32 v[78:79], s[46:47], s0, v236, v[202:203]
	s_min_u32 s0, s27, s7
	s_sub_i32 s0, s0, s5
	s_add_i32 s0, s6, s0
	s_add_i32 s0, s0, -15
	s_add_i32 s9, s5, 23
	v_mad_i64_i32 v[80:81], s[46:47], s0, v236, v[202:203]
	s_min_u32 s0, s9, s7
	s_sub_i32 s0, s0, s5
	s_add_i32 s0, s6, s0
	s_add_i32 s0, s0, -15
	v_mad_i64_i32 v[84:85], s[46:47], s0, v236, v[202:203]
	s_add_i32 s0, s5, 24
	s_min_u32 s45, s0, s7
	s_sub_i32 s45, s45, s5
	s_add_i32 s45, s6, s45
	s_add_i32 s45, s45, -15
	global_load_dword v69, v[70:71], off
	global_load_dword v83, v[70:71], off offset:2048
	global_load_dword v67, v[72:73], off
	s_nop 0
	global_load_dword v73, v[72:73], off offset:2048
	s_nop 0
	global_load_dword v70, v[74:75], off
	global_load_dword v72, v[74:75], off offset:2048
	global_load_dword v71, v[76:77], off
	s_nop 0
	global_load_dword v77, v[76:77], off offset:2048
	v_mad_i64_i32 v[86:87], s[46:47], s45, v236, v[202:203]
	global_load_dword v74, v[78:79], off
	global_load_dword v76, v[78:79], off offset:2048
	global_load_dword v75, v[80:81], off
	s_nop 0
	global_load_dword v81, v[80:81], off offset:2048
	s_nop 0
	global_load_dword v78, v[84:85], off
	global_load_dword v80, v[84:85], off offset:2048
	global_load_dword v79, v[86:87], off
	global_load_dword v82, v[86:87], off offset:2048
	s_cmp_ge_u32 s44, s4
	s_waitcnt vmcnt(33)
	v_mov_b32_e32 v47, 0
	s_cbranch_scc1 .LBB0_349
	s_waitcnt vmcnt(30)
	v_lshlrev_b32_e32 v46, 16, v68
	v_and_b32_e32 v47, 0xffff0000, v68
	v_mul_f32_e32 v46, 0xbfb8aa3b, v46
	v_mul_f32_e32 v47, 0xbfb8aa3b, v47
	v_exp_f32_e32 v46, v46
	v_exp_f32_e32 v47, v47
	v_lshlrev_b32_e32 v52, 16, v53
	v_and_b32_e32 v53, 0xffff0000, v53
	v_add_f32_e32 v46, 1.0, v46
	v_add_f32_e32 v47, 1.0, v47
	v_rcp_f32_e32 v46, v46
	v_rcp_f32_e32 v47, v47
	s_nop 0
	v_mul_f32_e32 v46, v46, v52
	v_mul_f32_e32 v47, v47, v53
; #define CONF_LOAD(DA, DG, CH) _Pragma("unroll") for (int k = 0; k < 8; ++k) { const int q = p0 - 15 + 8 * (CH) + k; const int qc = q < 0 ? 0 : (q >= L ? L - 1 : q); \
;                         const bf16_t* rowp = Zb + (size_t)(seq0 + qc) * INE; DA[k] = *(const unsigned*)(rowp + (unsigned)c0); DG[k] = *(const unsigned*)(rowp + 1024 + (unsigned)c0); }
; template <int PH>
; __device__ __forceinline__ void run_phase(const Args& args, LAS unsigned char* lds) {
;     ...
;                     CONF_LOAD(ca, cgt, 0)
; #pragma unroll
;                     for (int ch = 0; ch < 6; ++ch) {
;                         if (ch < 5) { CONF_LOAD(na, ng, ch + 1) }
;                         asm volatile("" ::: "memory");
; #pragma unroll
;                         for (int k = 0; k < 8; ++k) { const int i = 8 * ch + k; if (i < 46) { const int q = p0 - 15 + i; float u0 = 0.f, u1 = 0.f;
;                             if (q >= 0 && q < L) { u0 = bflo(ca[k]) * __builtin_amdgcn_rcpf(1.0f + __expf(-bflo(cgt[k]))); u1 = bfhi(ca[k]) * __builtin_amdgcn_rcpf(1.0f + __expf(-bfhi(cgt[k]))); }
.LBB0_349:
	s_waitcnt vmcnt(32)
	v_mov_b32_e32 v50, 0
	s_cmp_ge_u32 s38, s4
	v_mov_b32_e32 v52, 0
	s_waitcnt vmcnt(31)
	v_mov_b32_e32 v53, 0
	s_cbranch_scc1 .LBB0_351
	s_waitcnt vmcnt(28)
	v_lshlrev_b32_e32 v52, 16, v57
	v_and_b32_e32 v53, 0xffff0000, v57
	v_mul_f32_e32 v52, 0xbfb8aa3b, v52
	v_mul_f32_e32 v53, 0xbfb8aa3b, v53
	v_exp_f32_e32 v52, v52
	v_exp_f32_e32 v53, v53
	v_lshlrev_b32_e32 v84, 16, v51
	v_and_b32_e32 v85, 0xffff0000, v51
	v_add_f32_e32 v52, 1.0, v52
	v_add_f32_e32 v53, 1.0, v53
	v_rcp_f32_e32 v52, v52
	v_rcp_f32_e32 v53, v53
	s_nop 0
	v_mul_f32_e32 v52, v52, v84
	v_mul_f32_e32 v53, v53, v85
.LBB0_351:
	s_cmp_ge_u32 s36, s4
	s_waitcnt vmcnt(29)
	v_mov_b32_e32 v51, 0
	s_cbranch_scc1 .LBB0_353
	s_waitcnt vmcnt(26)
	v_lshlrev_b32_e32 v50, 16, v56
	v_and_b32_e32 v51, 0xffff0000, v56
	v_mul_f32_e32 v50, 0xbfb8aa3b, v50
	v_mul_f32_e32 v51, 0xbfb8aa3b, v51
	v_exp_f32_e32 v50, v50
	v_exp_f32_e32 v51, v51
	v_lshlrev_b32_e32 v56, 16, v54
	v_and_b32_e32 v57, 0xffff0000, v54
	v_add_f32_e32 v50, 1.0, v50
	v_add_f32_e32 v51, 1.0, v51
	v_rcp_f32_e32 v50, v50
	v_rcp_f32_e32 v51, v51
	s_nop 0
	v_mul_f32_e32 v50, v50, v56
	v_mul_f32_e32 v51, v51, v57
.LBB0_353:
	s_waitcnt vmcnt(27)
	v_mov_b32_e32 v54, 0
	s_cmp_ge_u32 s34, s4
	s_waitcnt vmcnt(26)
	v_mov_b32_e32 v56, 0
	v_mov_b32_e32 v57, 0
	s_cbranch_scc1 .LBB0_355
	s_waitcnt vmcnt(24)
	v_lshlrev_b32_e32 v56, 16, v61
	v_and_b32_e32 v57, 0xffff0000, v61
	v_mul_f32_e32 v56, 0xbfb8aa3b, v56
	v_mul_f32_e32 v57, 0xbfb8aa3b, v57
	v_exp_f32_e32 v56, v56
	v_exp_f32_e32 v57, v57
	v_lshlrev_b32_e32 v84, 16, v55
	v_and_b32_e32 v85, 0xffff0000, v55
	v_add_f32_e32 v56, 1.0, v56
	v_add_f32_e32 v57, 1.0, v57
	v_rcp_f32_e32 v56, v56
	v_rcp_f32_e32 v57, v57
	s_nop 0
	v_mul_f32_e32 v56, v56, v84
	v_mul_f32_e32 v57, v57, v85
.LBB0_355:
	s_cmp_ge_u32 s30, s4
	s_waitcnt vmcnt(25)
	v_mov_b32_e32 v55, 0
	s_cbranch_scc1 .LBB0_357
	s_waitcnt vmcnt(22)
	v_lshlrev_b32_e32 v54, 16, v60
	v_and_b32_e32 v55, 0xffff0000, v60
	v_mul_f32_e32 v54, 0xbfb8aa3b, v54
	v_mul_f32_e32 v55, 0xbfb8aa3b, v55
	v_exp_f32_e32 v54, v54
	v_exp_f32_e32 v55, v55
	v_lshlrev_b32_e32 v60, 16, v58
	v_and_b32_e32 v61, 0xffff0000, v58
	v_add_f32_e32 v54, 1.0, v54
	v_add_f32_e32 v55, 1.0, v55
	v_rcp_f32_e32 v54, v54
	v_rcp_f32_e32 v55, v55
	s_nop 0
	v_mul_f32_e32 v54, v54, v60
	v_mul_f32_e32 v55, v55, v61
.LBB0_357:
	s_waitcnt vmcnt(23)
	v_mov_b32_e32 v58, 0
	s_cmp_ge_u32 s28, s4
	s_waitcnt vmcnt(22)
	v_mov_b32_e32 v60, 0
	v_mov_b32_e32 v61, 0
	s_cbranch_scc1 .LBB0_359
	s_waitcnt vmcnt(20)
	v_lshlrev_b32_e32 v60, 16, v65
	v_and_b32_e32 v61, 0xffff0000, v65
	v_mul_f32_e32 v60, 0xbfb8aa3b, v60
	v_mul_f32_e32 v61, 0xbfb8aa3b, v61
	v_exp_f32_e32 v60, v60
	v_exp_f32_e32 v61, v61
	v_lshlrev_b32_e32 v84, 16, v59
	v_and_b32_e32 v85, 0xffff0000, v59
	v_add_f32_e32 v60, 1.0, v60
	v_add_f32_e32 v61, 1.0, v61
	v_rcp_f32_e32 v60, v60
	v_rcp_f32_e32 v61, v61
	s_nop 0
	v_mul_f32_e32 v60, v60, v84
	v_mul_f32_e32 v61, v61, v85
.LBB0_359:
	s_cmp_ge_u32 s26, s4
	s_waitcnt vmcnt(21)
	v_mov_b32_e32 v59, 0
	s_cbranch_scc1 .LBB0_361
	s_waitcnt vmcnt(18)
	v_lshlrev_b32_e32 v58, 16, v64
	v_and_b32_e32 v59, 0xffff0000, v64
	v_mul_f32_e32 v58, 0xbfb8aa3b, v58
	v_mul_f32_e32 v59, 0xbfb8aa3b, v59
	v_exp_f32_e32 v58, v58
	v_exp_f32_e32 v59, v59
	v_lshlrev_b32_e32 v64, 16, v62
	v_and_b32_e32 v65, 0xffff0000, v62
	v_add_f32_e32 v58, 1.0, v58
	v_add_f32_e32 v59, 1.0, v59
	v_rcp_f32_e32 v58, v58
	v_rcp_f32_e32 v59, v59
	s_nop 0
	v_mul_f32_e32 v58, v58, v64
	v_mul_f32_e32 v59, v59, v65
.LBB0_361:
	s_waitcnt vmcnt(19)
	v_mov_b32_e32 v62, 0
	s_cmp_ge_u32 s1, s4
	s_waitcnt vmcnt(18)
	v_mov_b32_e32 v64, 0
	v_mov_b32_e32 v65, 0
	s_cbranch_scc1 .LBB0_363
	s_waitcnt vmcnt(16)
	v_lshlrev_b32_e32 v64, 16, v66
	v_and_b32_e32 v65, 0xffff0000, v66
	v_mul_f32_e32 v64, 0xbfb8aa3b, v64
	v_mul_f32_e32 v65, 0xbfb8aa3b, v65
	v_exp_f32_e32 v64, v64
	v_exp_f32_e32 v65, v65
	v_lshlrev_b32_e32 v84, 16, v63
	v_and_b32_e32 v85, 0xffff0000, v63
	v_add_f32_e32 v64, 1.0, v64
	v_add_f32_e32 v65, 1.0, v65
	v_rcp_f32_e32 v64, v64
	v_rcp_f32_e32 v65, v65
	s_nop 0
	v_mul_f32_e32 v64, v64, v84
	v_mul_f32_e32 v65, v65, v85
.LBB0_363:
	s_add_i32 s36, s5, 25
	s_min_u32 s1, s36, s7
	s_sub_i32 s1, s1, s5
	s_add_i32 s1, s6, s1
	s_add_i32 s1, s1, -15
	s_add_i32 s34, s5, 26
	v_mad_i64_i32 v[86:87], s[44:45], s1, v236, v[202:203]
	s_min_u32 s1, s34, s7
	s_sub_i32 s1, s1, s5
	s_add_i32 s1, s6, s1
	s_add_i32 s1, s1, -15
	s_add_i32 s30, s5, 27
	v_mad_i64_i32 v[90:91], s[44:45], s1, v236, v[202:203]
	s_min_u32 s1, s30, s7
	s_sub_i32 s1, s1, s5
	s_add_i32 s1, s6, s1
	s_add_i32 s1, s1, -15
	s_add_i32 s28, s5, 28
	v_mad_i64_i32 v[92:93], s[44:45], s1, v236, v[202:203]
	s_min_u32 s1, s28, s7
	s_sub_i32 s1, s1, s5
	s_add_i32 s1, s6, s1
	s_add_i32 s1, s1, -15
	s_add_i32 s26, s5, 29
	v_mad_i64_i32 v[96:97], s[44:45], s1, v236, v[202:203]
	s_min_u32 s1, s26, s7
	s_sub_i32 s1, s1, s5
	s_add_i32 s1, s6, s1
	s_add_i32 s1, s1, -15
	global_load_dword v84, v[86:87], off
	global_load_dword v85, v[86:87], off offset:2048
	global_load_dword v89, v[90:91], off
	global_load_dword v95, v[90:91], off offset:2048
	s_nop 0
	global_load_dword v86, v[92:93], off
	global_load_dword v88, v[92:93], off offset:2048
	global_load_dword v87, v[96:97], off
	global_load_dword v94, v[96:97], off offset:2048
	v_mad_i64_i32 v[92:93], s[44:45], s1, v236, v[202:203]
	s_add_i32 s1, s5, 30
	s_min_u32 s7, s1, s7
	s_sub_i32 s5, s7, s5
	s_add_i32 s5, s6, s5
	s_add_i32 s5, s5, -15
	v_mad_i64_i32 v[96:97], s[44:45], s5, v236, v[202:203]
	global_load_dword v90, v[92:93], off
	global_load_dword v91, v[92:93], off offset:2048
	s_nop 0
	global_load_dword v92, v[96:97], off
	global_load_dword v93, v[96:97], off offset:2048
	s_cmp_ge_u32 s39, s4
	s_waitcnt vmcnt(29)
	v_mov_b32_e32 v63, 0
	s_cbranch_scc1 .LBB0_365
	s_waitcnt vmcnt(26)
	v_lshlrev_b32_e32 v62, 16, v83
	v_and_b32_e32 v63, 0xffff0000, v83
	v_mul_f32_e32 v62, 0xbfb8aa3b, v62
	v_mul_f32_e32 v63, 0xbfb8aa3b, v63
	v_exp_f32_e32 v62, v62
	v_exp_f32_e32 v63, v63
	v_lshlrev_b32_e32 v68, 16, v69
	v_and_b32_e32 v69, 0xffff0000, v69
	v_add_f32_e32 v62, 1.0, v62
	v_add_f32_e32 v63, 1.0, v63
	v_rcp_f32_e32 v62, v62
	v_rcp_f32_e32 v63, v63
	s_nop 0
	v_mul_f32_e32 v62, v62, v68
	v_mul_f32_e32 v63, v63, v69
; #define CONF_LOAD(DA, DG, CH) _Pragma("unroll") for (int k = 0; k < 8; ++k) { const int q = p0 - 15 + 8 * (CH) + k; const int qc = q < 0 ? 0 : (q >= L ? L - 1 : q); \
;                         const bf16_t* rowp = Zb + (size_t)(seq0 + qc) * INE; DA[k] = *(const unsigned*)(rowp + (unsigned)c0); DG[k] = *(const unsigned*)(rowp + 1024 + (unsigned)c0); }
; template <int PH>
; __device__ __forceinline__ void run_phase(const Args& args, LAS unsigned char* lds) {
;     ...
;                     CONF_LOAD(ca, cgt, 0)
; #pragma unroll
;                     for (int ch = 0; ch < 6; ++ch) {
;                         if (ch < 5) { CONF_LOAD(na, ng, ch + 1) }
;                         asm volatile("" ::: "memory");
; #pragma unroll
;                         for (int k = 0; k < 8; ++k) { const int i = 8 * ch + k; if (i < 46) { const int q = p0 - 15 + i; float u0 = 0.f, u1 = 0.f;
;                             if (q >= 0 && q < L) { u0 = bflo(ca[k]) * __builtin_amdgcn_rcpf(1.0f + __expf(-bflo(cgt[k]))); u1 = bfhi(ca[k]) * __builtin_amdgcn_rcpf(1.0f + __expf(-bfhi(cgt[k]))); }
.LBB0_365:
	s_waitcnt vmcnt(28)
	v_mov_b32_e32 v66, 0
	s_cmp_ge_u32 s37, s4
	v_mov_b32_e32 v68, 0
	s_waitcnt vmcnt(27)
	v_mov_b32_e32 v69, 0
	s_cbranch_scc1 .LBB0_367
	s_waitcnt vmcnt(24)
	v_lshlrev_b32_e32 v68, 16, v73
	v_and_b32_e32 v69, 0xffff0000, v73
	v_mul_f32_e32 v68, 0xbfb8aa3b, v68
	v_mul_f32_e32 v69, 0xbfb8aa3b, v69
	v_exp_f32_e32 v68, v68
	v_exp_f32_e32 v69, v69
	v_lshlrev_b32_e32 v96, 16, v67
	v_and_b32_e32 v97, 0xffff0000, v67
	v_add_f32_e32 v68, 1.0, v68
	v_add_f32_e32 v69, 1.0, v69
	v_rcp_f32_e32 v68, v68
	v_rcp_f32_e32 v69, v69
	s_nop 0
	v_mul_f32_e32 v68, v68, v96
	v_mul_f32_e32 v69, v69, v97
.LBB0_367:
	s_cmp_ge_u32 s35, s4
	s_waitcnt vmcnt(25)
	v_mov_b32_e32 v67, 0
	s_cbranch_scc1 .LBB0_369
	s_waitcnt vmcnt(22)
	v_lshlrev_b32_e32 v66, 16, v72
	v_and_b32_e32 v67, 0xffff0000, v72
	v_mul_f32_e32 v66, 0xbfb8aa3b, v66
	v_mul_f32_e32 v67, 0xbfb8aa3b, v67
	v_exp_f32_e32 v66, v66
	v_exp_f32_e32 v67, v67
	v_lshlrev_b32_e32 v72, 16, v70
	v_and_b32_e32 v73, 0xffff0000, v70
	v_add_f32_e32 v66, 1.0, v66
	v_add_f32_e32 v67, 1.0, v67
	v_rcp_f32_e32 v66, v66
	v_rcp_f32_e32 v67, v67
	s_nop 0
	v_mul_f32_e32 v66, v66, v72
	v_mul_f32_e32 v67, v67, v73
.LBB0_369:
	s_waitcnt vmcnt(23)
	v_mov_b32_e32 v70, 0
	s_cmp_ge_u32 s31, s4
	s_waitcnt vmcnt(22)
	v_mov_b32_e32 v72, 0
	v_mov_b32_e32 v73, 0
	s_cbranch_scc1 .LBB0_371
	s_waitcnt vmcnt(20)
	v_lshlrev_b32_e32 v72, 16, v77
	v_and_b32_e32 v73, 0xffff0000, v77
	v_mul_f32_e32 v72, 0xbfb8aa3b, v72
	v_mul_f32_e32 v73, 0xbfb8aa3b, v73
	v_exp_f32_e32 v72, v72
	v_exp_f32_e32 v73, v73
	v_lshlrev_b32_e32 v96, 16, v71
	v_and_b32_e32 v97, 0xffff0000, v71
	v_add_f32_e32 v72, 1.0, v72
	v_add_f32_e32 v73, 1.0, v73
	v_rcp_f32_e32 v72, v72
	v_rcp_f32_e32 v73, v73
	s_nop 0
	v_mul_f32_e32 v72, v72, v96
	v_mul_f32_e32 v73, v73, v97
.LBB0_371:
	s_cmp_ge_u32 s29, s4
	s_waitcnt vmcnt(21)
	v_mov_b32_e32 v71, 0
	s_cbranch_scc1 .LBB0_373
	s_waitcnt vmcnt(18)
	v_lshlrev_b32_e32 v70, 16, v76
	v_and_b32_e32 v71, 0xffff0000, v76
	v_mul_f32_e32 v70, 0xbfb8aa3b, v70
	v_mul_f32_e32 v71, 0xbfb8aa3b, v71
	v_exp_f32_e32 v70, v70
	v_exp_f32_e32 v71, v71
	v_lshlrev_b32_e32 v76, 16, v74
	v_and_b32_e32 v77, 0xffff0000, v74
	v_add_f32_e32 v70, 1.0, v70
	v_add_f32_e32 v71, 1.0, v71
	v_rcp_f32_e32 v70, v70
	v_rcp_f32_e32 v71, v71
	s_nop 0
	v_mul_f32_e32 v70, v70, v76
	v_mul_f32_e32 v71, v71, v77
.LBB0_373:
	s_waitcnt vmcnt(19)
	v_mov_b32_e32 v74, 0
	s_cmp_ge_u32 s27, s4
	s_waitcnt vmcnt(18)
	v_mov_b32_e32 v76, 0
	v_mov_b32_e32 v77, 0
	s_cbranch_scc1 .LBB0_375
	s_waitcnt vmcnt(16)
	v_lshlrev_b32_e32 v76, 16, v81
	v_and_b32_e32 v77, 0xffff0000, v81
	v_mul_f32_e32 v76, 0xbfb8aa3b, v76
	v_mul_f32_e32 v77, 0xbfb8aa3b, v77
	v_exp_f32_e32 v76, v76
	v_exp_f32_e32 v77, v77
	v_lshlrev_b32_e32 v96, 16, v75
	v_and_b32_e32 v97, 0xffff0000, v75
	v_add_f32_e32 v76, 1.0, v76
	v_add_f32_e32 v77, 1.0, v77
	v_rcp_f32_e32 v76, v76
	v_rcp_f32_e32 v77, v77
	s_nop 0
	v_mul_f32_e32 v76, v76, v96
	v_mul_f32_e32 v77, v77, v97
.LBB0_375:
	s_cmp_ge_u32 s9, s4
	s_waitcnt vmcnt(17)
	v_mov_b32_e32 v75, 0
	s_cbranch_scc1 .LBB0_377
	s_waitcnt vmcnt(14)
	v_lshlrev_b32_e32 v74, 16, v80
	v_and_b32_e32 v75, 0xffff0000, v80
	v_mul_f32_e32 v74, 0xbfb8aa3b, v74
	v_mul_f32_e32 v75, 0xbfb8aa3b, v75
	v_exp_f32_e32 v74, v74
	v_exp_f32_e32 v75, v75
	v_lshlrev_b32_e32 v80, 16, v78
	v_and_b32_e32 v81, 0xffff0000, v78
	v_add_f32_e32 v74, 1.0, v74
	v_add_f32_e32 v75, 1.0, v75
	v_rcp_f32_e32 v74, v74
	v_rcp_f32_e32 v75, v75
	s_nop 0
	v_mul_f32_e32 v74, v74, v80
	v_mul_f32_e32 v75, v75, v81
.LBB0_377:
	s_waitcnt vmcnt(15)
	v_mov_b32_e32 v78, 0
	s_cmp_ge_u32 s0, s4
	s_waitcnt vmcnt(14)
	v_mov_b32_e32 v80, 0
	v_mov_b32_e32 v81, 0
	s_cbranch_scc1 .LBB0_379
	s_waitcnt vmcnt(12)
	v_lshlrev_b32_e32 v80, 16, v82
	v_and_b32_e32 v81, 0xffff0000, v82
	v_mul_f32_e32 v80, 0xbfb8aa3b, v80
	v_mul_f32_e32 v81, 0xbfb8aa3b, v81
	v_exp_f32_e32 v80, v80
	v_exp_f32_e32 v81, v81
	v_lshlrev_b32_e32 v82, 16, v79
	v_and_b32_e32 v83, 0xffff0000, v79
	v_add_f32_e32 v80, 1.0, v80
	v_add_f32_e32 v81, 1.0, v81
	v_rcp_f32_e32 v80, v80
	v_rcp_f32_e32 v81, v81
	s_nop 0
	v_mul_f32_e32 v80, v80, v82
	v_mul_f32_e32 v81, v81, v83
.LBB0_379:
	s_cmp_ge_u32 s36, s4
	s_waitcnt vmcnt(13)
	v_mov_b32_e32 v79, 0
	s_cbranch_scc1 .LBB0_381
	s_waitcnt vmcnt(10)
	v_lshlrev_b32_e32 v78, 16, v85
	v_and_b32_e32 v79, 0xffff0000, v85
	v_mul_f32_e32 v78, 0xbfb8aa3b, v78
	v_mul_f32_e32 v79, 0xbfb8aa3b, v79
	v_exp_f32_e32 v78, v78
	v_exp_f32_e32 v79, v79
	v_lshlrev_b32_e32 v82, 16, v84
	v_and_b32_e32 v83, 0xffff0000, v84
	v_add_f32_e32 v78, 1.0, v78
	v_add_f32_e32 v79, 1.0, v79
	v_rcp_f32_e32 v78, v78
	v_rcp_f32_e32 v79, v79
	s_nop 0
	v_mul_f32_e32 v78, v78, v82
	v_mul_f32_e32 v79, v79, v83
.LBB0_381:
	s_waitcnt vmcnt(12)
	v_mov_b32_e32 v82, 0
	s_cmp_ge_u32 s34, s4
	s_waitcnt vmcnt(11)
	v_mov_b32_e32 v84, 0
	s_waitcnt vmcnt(10)
	v_mov_b32_e32 v85, 0
	s_cbranch_scc1 .LBB0_383
	s_waitcnt vmcnt(8)
	v_lshlrev_b32_e32 v83, 16, v95
	v_mul_f32_e32 v83, 0xbfb8aa3b, v83
	v_and_b32_e32 v84, 0xffff0000, v95
	v_exp_f32_e32 v83, v83
	v_mul_f32_e32 v84, 0xbfb8aa3b, v84
	v_exp_f32_e32 v85, v84
	v_lshlrev_b32_e32 v96, 16, v89
	v_add_f32_e32 v83, 1.0, v83
	v_rcp_f32_e32 v84, v83
	v_add_f32_e32 v83, 1.0, v85
	v_rcp_f32_e32 v85, v83
	v_and_b32_e32 v97, 0xffff0000, v89
	v_mul_f32_e32 v84, v84, v96
	v_mul_f32_e32 v85, v85, v97
.LBB0_383:
	s_cmp_ge_u32 s30, s4
	v_mov_b32_e32 v83, 0
	s_cbranch_scc1 .LBB0_385
	s_waitcnt vmcnt(6)
	v_lshlrev_b32_e32 v82, 16, v88
	v_and_b32_e32 v83, 0xffff0000, v88
	v_mul_f32_e32 v82, 0xbfb8aa3b, v82
	v_mul_f32_e32 v83, 0xbfb8aa3b, v83
	v_exp_f32_e32 v82, v82
	v_exp_f32_e32 v83, v83
	v_lshlrev_b32_e32 v88, 16, v86
	v_and_b32_e32 v89, 0xffff0000, v86
	v_add_f32_e32 v82, 1.0, v82
	v_add_f32_e32 v83, 1.0, v83
	v_rcp_f32_e32 v82, v82
	v_rcp_f32_e32 v83, v83
	s_nop 0
	v_mul_f32_e32 v82, v82, v88
	v_mul_f32_e32 v83, v83, v89
.LBB0_385:
	s_waitcnt vmcnt(7)
	v_mov_b32_e32 v86, 0
	s_cmp_ge_u32 s28, s4
	s_waitcnt vmcnt(6)
	v_mov_b32_e32 v88, 0
	v_mov_b32_e32 v89, 0
	s_cbranch_scc1 .LBB0_453
	s_waitcnt vmcnt(4)
	v_lshlrev_b32_e32 v88, 16, v94
	v_and_b32_e32 v89, 0xffff0000, v94
	v_mul_f32_e32 v88, 0xbfb8aa3b, v88
	v_mul_f32_e32 v89, 0xbfb8aa3b, v89
	v_exp_f32_e32 v88, v88
	v_exp_f32_e32 v89, v89
	v_lshlrev_b32_e32 v94, 16, v87
	v_and_b32_e32 v95, 0xffff0000, v87
	v_add_f32_e32 v88, 1.0, v88
	v_add_f32_e32 v89, 1.0, v89
	v_rcp_f32_e32 v88, v88
	v_rcp_f32_e32 v89, v89
	s_nop 0
	v_mul_f32_e32 v88, v88, v94
	v_mul_f32_e32 v89, v89, v95
	s_cmp_ge_u32 s26, s4
	v_mov_b32_e32 v87, 0
	s_cbranch_scc0 .LBB0_454

; template <int PH>
; __device__ __forceinline__ void run_phase(const Args& args, LAS unsigned char* lds) {
;     ...
;                         for (int k = 0; k < 8; ++k) { const int i = 8 * ch + k; if (i < 46) { const int q = p0 - 15 + i; float u0 = 0.f, u1 = 0.f;
;                             if (q >= 0 && q < L) { u0 = bflo(ca[k]) * __builtin_amdgcn_rcpf(1.0f + __expf(-bflo(cgt[k]))); u1 = bfhi(ca[k]) * __builtin_amdgcn_rcpf(1.0f + __expf(-bfhi(cgt[k]))); }
; #pragma unroll
;                             for (int o = 0; o < 16; ++o) { const int kk = i - o; if (kk >= 0 && kk <= 30) { a0[o] += w0[kk] * u0; a1[o] += w1[kk] * u1; } } } }
; #pragma unroll
;                         for (int k = 0; k < 8; ++k) { ca[k] = na[k]; cgt[k] = ng[k]; }
;                     }
;     ...
;                     float mean[16], rstd[16];
; #pragma unroll
;                     for (int o = 0; o < 16; ++o) { const float s = wave_sum(a0[o] + a1[o]); if (lane == 0) red[wave * 16 + o] = s; }
.LBB0_388:
	s_waitcnt vmcnt(0)
	v_lshlrev_b32_e32 v90, 16, v93
	v_and_b32_e32 v91, 0xffff0000, v93
	v_mul_f32_e32 v90, 0xbfb8aa3b, v90
	v_mul_f32_e32 v91, 0xbfb8aa3b, v91
	v_exp_f32_e32 v90, v90
	v_exp_f32_e32 v91, v91
	v_lshlrev_b32_e32 v94, 16, v92
	v_and_b32_e32 v95, 0xffff0000, v92
	v_add_f32_e32 v90, 1.0, v90
	v_add_f32_e32 v91, 1.0, v91
	v_rcp_f32_e32 v90, v90
	v_rcp_f32_e32 v91, v91
	s_nop 0
	v_mul_f32_e32 v90, v90, v94
	v_mul_f32_e32 v91, v91, v95
.LBB0_389:
	v_fma_f32 v44, v188, v44, v198
	v_fma_f32 v45, v189, v45, v199
	s_waitcnt vmcnt(0)
	v_xor_b32_e32 v93, 2, v237
	v_fma_f32 v44, v130, v38, v44
	v_fma_f32 v45, v131, v39, v45
	v_fma_f32 v44, v132, v30, v44
	v_fma_f32 v45, v133, v31, v45
	v_fma_f32 v44, v134, v32, v44
	v_fma_f32 v45, v135, v33, v45
	v_fma_f32 v44, v136, v20, v44
	v_fma_f32 v45, v137, v21, v45
	v_fma_f32 v44, v138, v28, v44
	v_fma_f32 v45, v139, v29, v45
	v_fma_f32 v44, v140, v14, v44
	v_fma_f32 v45, v141, v15, v45
	v_fma_f32 v44, v142, v18, v44
	v_fma_f32 v45, v143, v19, v45
	v_fma_f32 v44, v144, v8, v44
	v_fma_f32 v45, v145, v9, v45
	v_fma_f32 v44, v146, v22, v44
	v_fma_f32 v45, v147, v23, v45
	v_fma_f32 v44, v148, v12, v44
	v_fma_f32 v45, v149, v13, v45
	v_fma_f32 v44, v150, v16, v44
	v_fma_f32 v45, v151, v17, v45
	v_fma_f32 v44, v152, v6, v44
	v_fma_f32 v45, v153, v7, v45
	v_fma_f32 v44, v154, v10, v44
	v_fma_f32 v45, v155, v11, v45
	v_fma_f32 v44, v156, v0, v44
	v_fma_f32 v45, v157, v1, v45
	v_fma_f32 v44, v158, v4, v44
	v_fma_f32 v45, v159, v5, v45
	v_fma_f32 v44, v160, v2, v44
	v_fma_f32 v45, v161, v3, v45
	v_fma_f32 v44, v162, v26, v44
	v_fma_f32 v45, v163, v27, v45
	v_fma_f32 v44, v164, v24, v44
	v_fma_f32 v45, v165, v25, v45
	v_fma_f32 v44, v166, v36, v44
	v_fma_f32 v45, v167, v37, v45
	v_fma_f32 v44, v168, v34, v44
	v_fma_f32 v45, v169, v35, v45
	v_fma_f32 v44, v170, v42, v44
	v_fma_f32 v45, v171, v43, v45
	v_fma_f32 v44, v172, v40, v44
	v_fma_f32 v45, v173, v41, v45
	v_fma_f32 v44, v174, v48, v44
	v_fma_f32 v45, v175, v49, v45
	v_fma_f32 v44, v176, v46, v44
	v_fma_f32 v45, v177, v47, v45
	v_fma_f32 v44, v178, v52, v44
	v_fma_f32 v45, v179, v53, v45
	v_fma_f32 v44, v180, v50, v44
	v_fma_f32 v45, v181, v51, v45
	v_fma_f32 v44, v182, v56, v44
	v_fma_f32 v45, v183, v57, v45
	v_fma_f32 v44, v186, v54, v44
	v_fma_f32 v45, v187, v55, v45
	v_fma_f32 v44, v190, v60, v44
	v_fma_f32 v45, v191, v61, v45
	v_fma_f32 v204, v194, v58, v44
	v_fma_f32 v205, v195, v59, v45
	v_and_b32_e32 v44, 64, v237
	v_add_u32_e32 v44, 64, v44
	v_xor_b32_e32 v45, 1, v237
	v_cmp_lt_i32_e32 vcc, v45, v44
	s_nop 1
	v_cndmask_b32_e32 v45, v237, v45, vcc
	v_lshlrev_b32_e32 v238, 2, v45
	v_add_f32_e32 v45, v204, v205
	ds_bpermute_b32 v92, v238, v45
	v_cmp_lt_i32_e32 vcc, v93, v44
	s_waitcnt lgkmcnt(0)
	v_add_f32_e32 v45, v45, v92
	v_cndmask_b32_e32 v93, v237, v93, vcc
	v_lshlrev_b32_e32 v239, 2, v93
	ds_bpermute_b32 v92, v239, v45
	v_xor_b32_e32 v93, 4, v237
	v_cmp_lt_i32_e32 vcc, v93, v44
	s_waitcnt lgkmcnt(0)
	v_add_f32_e32 v45, v45, v92
	v_cndmask_b32_e32 v93, v237, v93, vcc
	v_lshlrev_b32_e32 v240, 2, v93
	ds_bpermute_b32 v92, v240, v45
	v_xor_b32_e32 v93, 8, v237
	v_cmp_lt_i32_e32 vcc, v93, v44
	s_waitcnt lgkmcnt(0)
	v_add_f32_e32 v45, v45, v92
	v_cndmask_b32_e32 v93, v237, v93, vcc
	v_lshlrev_b32_e32 v241, 2, v93
	ds_bpermute_b32 v92, v241, v45
	v_xor_b32_e32 v93, 16, v237
	v_cmp_lt_i32_e32 vcc, v93, v44
	s_waitcnt lgkmcnt(0)
	v_add_f32_e32 v45, v45, v92
	v_cndmask_b32_e32 v93, v237, v93, vcc
	v_lshlrev_b32_e32 v242, 2, v93
	ds_bpermute_b32 v92, v242, v45
	v_xor_b32_e32 v93, 32, v237
	v_cmp_lt_i32_e32 vcc, v93, v44
	s_nop 1
	v_cndmask_b32_e32 v44, v237, v93, vcc
	v_lshlrev_b32_e32 v243, 2, v44
	s_waitcnt lgkmcnt(0)
	v_add_f32_e32 v44, v45, v92
	ds_bpermute_b32 v45, v243, v44
	s_and_saveexec_b64 s[0:1], s[2:3]
	s_cbranch_execz .LBB0_391
	s_add_i32 s4, s10, 0
	s_waitcnt lgkmcnt(0)
	v_add_f32_e32 v44, v44, v45
	v_mov_b32_e32 v45, s4
	ds_write_b32 v45, v44
.LBB0_391:
	s_or_b64 exec, exec, s[0:1]
	v_fma_f32 v38, v188, v38, v198
	v_fma_f32 v39, v189, v39, v199
	v_fma_f32 v38, v130, v30, v38
	v_fma_f32 v39, v131, v31, v39
	v_fma_f32 v38, v132, v32, v38
	v_fma_f32 v39, v133, v33, v39
	v_fma_f32 v38, v134, v20, v38
	v_fma_f32 v39, v135, v21, v39
	v_fma_f32 v38, v136, v28, v38
	v_fma_f32 v39, v137, v29, v39
	v_fma_f32 v38, v138, v14, v38
	v_fma_f32 v39, v139, v15, v39
	v_fma_f32 v38, v140, v18, v38
	v_fma_f32 v39, v141, v19, v39
	v_fma_f32 v38, v142, v8, v38
	v_fma_f32 v39, v143, v9, v39
	v_fma_f32 v38, v144, v22, v38
	v_fma_f32 v39, v145, v23, v39
	v_fma_f32 v38, v146, v12, v38
	v_fma_f32 v39, v147, v13, v39
	v_fma_f32 v38, v148, v16, v38
	v_fma_f32 v39, v149, v17, v39
	v_fma_f32 v38, v150, v6, v38
	v_fma_f32 v39, v151, v7, v39
	v_fma_f32 v38, v152, v10, v38
	v_fma_f32 v39, v153, v11, v39
	v_fma_f32 v38, v154, v0, v38
	v_fma_f32 v39, v155, v1, v39
	v_fma_f32 v38, v156, v4, v38
	v_fma_f32 v39, v157, v5, v39
	v_fma_f32 v38, v158, v2, v38
	v_fma_f32 v39, v159, v3, v39
	v_fma_f32 v38, v160, v26, v38
	v_fma_f32 v39, v161, v27, v39
	v_fma_f32 v38, v162, v24, v38
	v_fma_f32 v39, v163, v25, v39
	v_fma_f32 v38, v164, v36, v38
	v_fma_f32 v39, v165, v37, v39
	v_fma_f32 v38, v166, v34, v38
	v_fma_f32 v39, v167, v35, v39
	v_fma_f32 v38, v168, v42, v38
	v_fma_f32 v39, v169, v43, v39
	v_fma_f32 v38, v170, v40, v38
	v_fma_f32 v39, v171, v41, v39
	v_fma_f32 v38, v172, v48, v38
	v_fma_f32 v39, v173, v49, v39
	v_fma_f32 v38, v174, v46, v38
	v_fma_f32 v39, v175, v47, v39
	v_fma_f32 v38, v176, v52, v38
	v_fma_f32 v39, v177, v53, v39
	v_fma_f32 v38, v178, v50, v38
	v_fma_f32 v39, v179, v51, v39
	v_fma_f32 v38, v180, v56, v38
	v_fma_f32 v39, v181, v57, v39
	v_fma_f32 v38, v182, v54, v38
	v_fma_f32 v39, v183, v55, v39
	v_fma_f32 v38, v186, v60, v38
	v_fma_f32 v39, v187, v61, v39
	v_fma_f32 v38, v190, v58, v38
	v_fma_f32 v39, v191, v59, v39
	v_fma_f32 v206, v194, v64, v38
	v_fma_f32 v207, v195, v65, v39
	v_add_f32_e32 v38, v206, v207
	ds_bpermute_b32 v39, v238, v38
	s_waitcnt lgkmcnt(0)
	v_add_f32_e32 v38, v38, v39
	ds_bpermute_b32 v39, v239, v38
	s_waitcnt lgkmcnt(0)
	v_add_f32_e32 v38, v38, v39
	ds_bpermute_b32 v39, v240, v38
	s_waitcnt lgkmcnt(0)
	v_add_f32_e32 v38, v38, v39
	ds_bpermute_b32 v39, v241, v38
	s_waitcnt lgkmcnt(0)
	v_add_f32_e32 v38, v38, v39
	ds_bpermute_b32 v39, v242, v38
	s_waitcnt lgkmcnt(0)
	v_add_f32_e32 v38, v38, v39
	ds_bpermute_b32 v39, v243, v38
	s_and_saveexec_b64 s[0:1], s[2:3]
	s_cbranch_execz .LBB0_393
	s_add_i32 s4, s10, 0
	s_waitcnt lgkmcnt(0)
	v_add_f32_e32 v38, v38, v39
	v_mov_b32_e32 v39, s4
	ds_write_b32 v39, v38 offset:4
; template <int PH>
; __device__ __forceinline__ void run_phase(const Args& args, LAS unsigned char* lds) {
;     ...
;                         for (int k = 0; k < 8; ++k) { const int i = 8 * ch + k; if (i < 46) { const int q = p0 - 15 + i; float u0 = 0.f, u1 = 0.f;
;                             if (q >= 0 && q < L) { u0 = bflo(ca[k]) * __builtin_amdgcn_rcpf(1.0f + __expf(-bflo(cgt[k]))); u1 = bfhi(ca[k]) * __builtin_amdgcn_rcpf(1.0f + __expf(-bfhi(cgt[k]))); }
; #pragma unroll
;                             for (int o = 0; o < 16; ++o) { const int kk = i - o; if (kk >= 0 && kk <= 30) { a0[o] += w0[kk] * u0; a1[o] += w1[kk] * u1; } } } }
; #pragma unroll
;                         for (int k = 0; k < 8; ++k) { ca[k] = na[k]; cgt[k] = ng[k]; }
;                     }
;     ...
;                     float mean[16], rstd[16];
; #pragma unroll
;                     for (int o = 0; o < 16; ++o) { const float s = wave_sum(a0[o] + a1[o]); if (lane == 0) red[wave * 16 + o] = s; }
.LBB0_393:
	s_or_b64 exec, exec, s[0:1]
	v_fma_f32 v30, v188, v30, v198
	v_fma_f32 v31, v189, v31, v199
	v_fma_f32 v30, v130, v32, v30
	v_fma_f32 v31, v131, v33, v31
	v_fma_f32 v30, v132, v20, v30
	v_fma_f32 v31, v133, v21, v31
	v_fma_f32 v30, v134, v28, v30
	v_fma_f32 v31, v135, v29, v31
	v_fma_f32 v30, v136, v14, v30
	v_fma_f32 v31, v137, v15, v31
	v_fma_f32 v30, v138, v18, v30
	v_fma_f32 v31, v139, v19, v31
	v_fma_f32 v30, v140, v8, v30
	v_fma_f32 v31, v141, v9, v31
	v_fma_f32 v30, v142, v22, v30
	v_fma_f32 v31, v143, v23, v31
	v_fma_f32 v30, v144, v12, v30
	v_fma_f32 v31, v145, v13, v31
	v_fma_f32 v30, v146, v16, v30
	v_fma_f32 v31, v147, v17, v31
	v_fma_f32 v30, v148, v6, v30
	v_fma_f32 v31, v149, v7, v31
	v_fma_f32 v30, v150, v10, v30
	v_fma_f32 v31, v151, v11, v31
	v_fma_f32 v30, v152, v0, v30
	v_fma_f32 v31, v153, v1, v31
	v_fma_f32 v30, v154, v4, v30
	v_fma_f32 v31, v155, v5, v31
	v_fma_f32 v30, v156, v2, v30
	v_fma_f32 v31, v157, v3, v31
	v_fma_f32 v30, v158, v26, v30
	v_fma_f32 v31, v159, v27, v31
	v_fma_f32 v30, v160, v24, v30
	v_fma_f32 v31, v161, v25, v31
	v_fma_f32 v30, v162, v36, v30
	v_fma_f32 v31, v163, v37, v31
	v_fma_f32 v30, v164, v34, v30
	v_fma_f32 v31, v165, v35, v31
	v_fma_f32 v30, v166, v42, v30
	v_fma_f32 v31, v167, v43, v31
	v_fma_f32 v30, v168, v40, v30
	v_fma_f32 v31, v169, v41, v31
	v_fma_f32 v30, v170, v48, v30
	v_fma_f32 v31, v171, v49, v31
	v_fma_f32 v30, v172, v46, v30
	v_fma_f32 v31, v173, v47, v31
	v_fma_f32 v30, v174, v52, v30
	v_fma_f32 v31, v175, v53, v31
	v_fma_f32 v30, v176, v50, v30
	v_fma_f32 v31, v177, v51, v31
	v_fma_f32 v30, v178, v56, v30
	v_fma_f32 v31, v179, v57, v31
	v_fma_f32 v30, v180, v54, v30
	v_fma_f32 v31, v181, v55, v31
	v_fma_f32 v30, v182, v60, v30
	v_fma_f32 v31, v183, v61, v31
	v_fma_f32 v30, v186, v58, v30
	v_fma_f32 v31, v187, v59, v31
	v_fma_f32 v30, v190, v64, v30
	v_fma_f32 v31, v191, v65, v31
	v_fma_f32 v208, v194, v62, v30
	v_fma_f32 v209, v195, v63, v31
	v_add_f32_e32 v30, v208, v209
	ds_bpermute_b32 v31, v238, v30
	s_waitcnt lgkmcnt(0)
	v_add_f32_e32 v30, v30, v31
	ds_bpermute_b32 v31, v239, v30
	s_waitcnt lgkmcnt(0)
	v_add_f32_e32 v30, v30, v31
	ds_bpermute_b32 v31, v240, v30
	s_waitcnt lgkmcnt(0)
	v_add_f32_e32 v30, v30, v31
	ds_bpermute_b32 v31, v241, v30
	s_waitcnt lgkmcnt(0)
	v_add_f32_e32 v30, v30, v31
	ds_bpermute_b32 v31, v242, v30
	s_waitcnt lgkmcnt(0)
	v_add_f32_e32 v30, v30, v31
	ds_bpermute_b32 v31, v243, v30
	s_and_saveexec_b64 s[0:1], s[2:3]
	s_cbranch_execz .LBB0_395
	s_add_i32 s4, s10, 0
	s_waitcnt lgkmcnt(0)
	v_add_f32_e32 v30, v30, v31
	v_mov_b32_e32 v31, s4
	ds_write_b32 v31, v30 offset:8
.LBB0_395:
	s_or_b64 exec, exec, s[0:1]
	s_waitcnt lgkmcnt(0)
	v_fma_f32 v30, v188, v32, v198
	v_fma_f32 v31, v189, v33, v199
	v_fma_f32 v30, v130, v20, v30
	v_fma_f32 v31, v131, v21, v31
	v_fma_f32 v30, v132, v28, v30
	v_fma_f32 v31, v133, v29, v31
	v_fma_f32 v30, v134, v14, v30
	v_fma_f32 v31, v135, v15, v31
	v_fma_f32 v30, v136, v18, v30
	v_fma_f32 v31, v137, v19, v31
	v_fma_f32 v30, v138, v8, v30
	v_fma_f32 v31, v139, v9, v31
	v_fma_f32 v30, v140, v22, v30
	v_fma_f32 v31, v141, v23, v31
	v_fma_f32 v30, v142, v12, v30
	v_fma_f32 v31, v143, v13, v31
	v_fma_f32 v30, v144, v16, v30
	v_fma_f32 v31, v145, v17, v31
	v_fma_f32 v30, v146, v6, v30
	v_fma_f32 v31, v147, v7, v31
	v_fma_f32 v30, v148, v10, v30
	v_fma_f32 v31, v149, v11, v31
	v_fma_f32 v30, v150, v0, v30
	v_fma_f32 v31, v151, v1, v31
	v_fma_f32 v30, v152, v4, v30
	v_fma_f32 v31, v153, v5, v31
	v_fma_f32 v30, v154, v2, v30
	v_fma_f32 v31, v155, v3, v31
	v_fma_f32 v30, v156, v26, v30
	v_fma_f32 v31, v157, v27, v31
	v_fma_f32 v30, v158, v24, v30
	v_fma_f32 v31, v159, v25, v31
	v_fma_f32 v30, v160, v36, v30
	v_fma_f32 v31, v161, v37, v31
	v_fma_f32 v30, v162, v34, v30
	v_fma_f32 v31, v163, v35, v31
	v_fma_f32 v30, v164, v42, v30
	v_fma_f32 v31, v165, v43, v31
	v_fma_f32 v30, v166, v40, v30
	v_fma_f32 v31, v167, v41, v31
	v_fma_f32 v30, v168, v48, v30
	v_fma_f32 v31, v169, v49, v31
	v_fma_f32 v30, v170, v46, v30
	v_fma_f32 v31, v171, v47, v31
	v_fma_f32 v30, v172, v52, v30
	v_fma_f32 v31, v173, v53, v31
	v_fma_f32 v30, v174, v50, v30
	v_fma_f32 v31, v175, v51, v31
	v_fma_f32 v30, v176, v56, v30
	v_fma_f32 v31, v177, v57, v31
	v_fma_f32 v30, v178, v54, v30
	v_fma_f32 v31, v179, v55, v31
	v_fma_f32 v30, v180, v60, v30
	v_fma_f32 v31, v181, v61, v31
	v_fma_f32 v30, v182, v58, v30
	v_fma_f32 v31, v183, v59, v31
	v_fma_f32 v30, v186, v64, v30
	v_fma_f32 v31, v187, v65, v31
	v_fma_f32 v30, v190, v62, v30
	v_fma_f32 v31, v191, v63, v31
	v_fma_f32 v210, v194, v68, v30
	v_fma_f32 v211, v195, v69, v31
	v_add_f32_e32 v30, v210, v211
	ds_bpermute_b32 v31, v238, v30
	s_waitcnt lgkmcnt(0)
	v_add_f32_e32 v30, v30, v31
	ds_bpermute_b32 v31, v239, v30
	s_waitcnt lgkmcnt(0)
	v_add_f32_e32 v30, v30, v31
	ds_bpermute_b32 v31, v240, v30
	s_waitcnt lgkmcnt(0)
	v_add_f32_e32 v30, v30, v31
	ds_bpermute_b32 v31, v241, v30
	s_waitcnt lgkmcnt(0)
	v_add_f32_e32 v30, v30, v31
	ds_bpermute_b32 v31, v242, v30
	s_waitcnt lgkmcnt(0)
	v_add_f32_e32 v30, v30, v31
	ds_bpermute_b32 v31, v243, v30
	s_and_saveexec_b64 s[0:1], s[2:3]
	s_cbranch_execz .LBB0_397
	s_add_i32 s4, s10, 0
	s_waitcnt lgkmcnt(0)
	v_add_f32_e32 v30, v30, v31
	v_mov_b32_e32 v31, s4
	ds_write_b32 v31, v30 offset:12
; template <int PH>
; __device__ __forceinline__ void run_phase(const Args& args, LAS unsigned char* lds) {
;     ...
;                         for (int k = 0; k < 8; ++k) { const int i = 8 * ch + k; if (i < 46) { const int q = p0 - 15 + i; float u0 = 0.f, u1 = 0.f;
;                             if (q >= 0 && q < L) { u0 = bflo(ca[k]) * __builtin_amdgcn_rcpf(1.0f + __expf(-bflo(cgt[k]))); u1 = bfhi(ca[k]) * __builtin_amdgcn_rcpf(1.0f + __expf(-bfhi(cgt[k]))); }
; #pragma unroll
;                             for (int o = 0; o < 16; ++o) { const int kk = i - o; if (kk >= 0 && kk <= 30) { a0[o] += w0[kk] * u0; a1[o] += w1[kk] * u1; } } } }
; #pragma unroll
;                         for (int k = 0; k < 8; ++k) { ca[k] = na[k]; cgt[k] = ng[k]; }
;                     }
;     ...
;                     float mean[16], rstd[16];
; #pragma unroll
;                     for (int o = 0; o < 16; ++o) { const float s = wave_sum(a0[o] + a1[o]); if (lane == 0) red[wave * 16 + o] = s; }
.LBB0_397:
	s_or_b64 exec, exec, s[0:1]
	v_fma_f32 v20, v188, v20, v198
	v_fma_f32 v21, v189, v21, v199
	v_fma_f32 v20, v130, v28, v20
	v_fma_f32 v21, v131, v29, v21
	v_fma_f32 v20, v132, v14, v20
	v_fma_f32 v21, v133, v15, v21
	v_fma_f32 v20, v134, v18, v20
	v_fma_f32 v21, v135, v19, v21
	v_fma_f32 v20, v136, v8, v20
	v_fma_f32 v21, v137, v9, v21
	v_fma_f32 v20, v138, v22, v20
	v_fma_f32 v21, v139, v23, v21
	v_fma_f32 v20, v140, v12, v20
	v_fma_f32 v21, v141, v13, v21
	v_fma_f32 v20, v142, v16, v20
	v_fma_f32 v21, v143, v17, v21
	v_fma_f32 v20, v144, v6, v20
	v_fma_f32 v21, v145, v7, v21
	v_fma_f32 v20, v146, v10, v20
	v_fma_f32 v21, v147, v11, v21
	v_fma_f32 v20, v148, v0, v20
	v_fma_f32 v21, v149, v1, v21
	v_fma_f32 v20, v150, v4, v20
	v_fma_f32 v21, v151, v5, v21
	v_fma_f32 v20, v152, v2, v20
	v_fma_f32 v21, v153, v3, v21
	v_fma_f32 v20, v154, v26, v20
	v_fma_f32 v21, v155, v27, v21
	v_fma_f32 v20, v156, v24, v20
	v_fma_f32 v21, v157, v25, v21
	v_fma_f32 v20, v158, v36, v20
	v_fma_f32 v21, v159, v37, v21
	v_fma_f32 v20, v160, v34, v20
	v_fma_f32 v21, v161, v35, v21
	v_fma_f32 v20, v162, v42, v20
	v_fma_f32 v21, v163, v43, v21
	v_fma_f32 v20, v164, v40, v20
	v_fma_f32 v21, v165, v41, v21
	v_fma_f32 v20, v166, v48, v20
	v_fma_f32 v21, v167, v49, v21
	v_fma_f32 v20, v168, v46, v20
	v_fma_f32 v21, v169, v47, v21
	v_fma_f32 v20, v170, v52, v20
	v_fma_f32 v21, v171, v53, v21
	v_fma_f32 v20, v172, v50, v20
	v_fma_f32 v21, v173, v51, v21
	v_fma_f32 v20, v174, v56, v20
	v_fma_f32 v21, v175, v57, v21
	v_fma_f32 v20, v176, v54, v20
	v_fma_f32 v21, v177, v55, v21
	v_fma_f32 v20, v178, v60, v20
	v_fma_f32 v21, v179, v61, v21
	v_fma_f32 v20, v180, v58, v20
	v_fma_f32 v21, v181, v59, v21
	v_fma_f32 v20, v182, v64, v20
	v_fma_f32 v21, v183, v65, v21
	v_fma_f32 v20, v186, v62, v20
	v_fma_f32 v21, v187, v63, v21
	v_fma_f32 v20, v190, v68, v20
	v_fma_f32 v21, v191, v69, v21
	v_fma_f32 v212, v194, v66, v20
	v_fma_f32 v213, v195, v67, v21
	v_add_f32_e32 v20, v212, v213
	ds_bpermute_b32 v21, v238, v20
	s_waitcnt lgkmcnt(0)
	v_add_f32_e32 v20, v20, v21
	ds_bpermute_b32 v21, v239, v20
	s_waitcnt lgkmcnt(0)
	v_add_f32_e32 v20, v20, v21
	ds_bpermute_b32 v21, v240, v20
	s_waitcnt lgkmcnt(0)
	v_add_f32_e32 v20, v20, v21
	ds_bpermute_b32 v21, v241, v20
	s_waitcnt lgkmcnt(0)
	v_add_f32_e32 v20, v20, v21
	ds_bpermute_b32 v21, v242, v20
	s_waitcnt lgkmcnt(0)
	v_add_f32_e32 v20, v20, v21
	ds_bpermute_b32 v21, v243, v20
	s_and_saveexec_b64 s[0:1], s[2:3]
	s_cbranch_execz .LBB0_399
	s_add_i32 s4, s10, 0
	s_waitcnt lgkmcnt(0)
	v_add_f32_e32 v20, v20, v21
	v_mov_b32_e32 v21, s4
	ds_write_b32 v21, v20 offset:16
.LBB0_399:
	s_or_b64 exec, exec, s[0:1]
	s_waitcnt lgkmcnt(0)
	v_fma_f32 v20, v188, v28, v198
	v_fma_f32 v21, v189, v29, v199
	v_fma_f32 v20, v130, v14, v20
	v_fma_f32 v21, v131, v15, v21
	v_fma_f32 v20, v132, v18, v20
	v_fma_f32 v21, v133, v19, v21
	v_fma_f32 v20, v134, v8, v20
	v_fma_f32 v21, v135, v9, v21
	v_fma_f32 v20, v136, v22, v20
	v_fma_f32 v21, v137, v23, v21
	v_fma_f32 v20, v138, v12, v20
	v_fma_f32 v21, v139, v13, v21
	v_fma_f32 v20, v140, v16, v20
	v_fma_f32 v21, v141, v17, v21
	v_fma_f32 v20, v142, v6, v20
	v_fma_f32 v21, v143, v7, v21
	v_fma_f32 v20, v144, v10, v20
	v_fma_f32 v21, v145, v11, v21
	v_fma_f32 v20, v146, v0, v20
	v_fma_f32 v21, v147, v1, v21
	v_fma_f32 v20, v148, v4, v20
	v_fma_f32 v21, v149, v5, v21
	v_fma_f32 v20, v150, v2, v20
	v_fma_f32 v21, v151, v3, v21
	v_fma_f32 v20, v152, v26, v20
	v_fma_f32 v21, v153, v27, v21
	v_fma_f32 v20, v154, v24, v20
	v_fma_f32 v21, v155, v25, v21
	v_fma_f32 v20, v156, v36, v20
	v_fma_f32 v21, v157, v37, v21
	v_fma_f32 v20, v158, v34, v20
	v_fma_f32 v21, v159, v35, v21
	v_fma_f32 v20, v160, v42, v20
	v_fma_f32 v21, v161, v43, v21
	v_fma_f32 v20, v162, v40, v20
	v_fma_f32 v21, v163, v41, v21
	v_fma_f32 v20, v164, v48, v20
	v_fma_f32 v21, v165, v49, v21
	v_fma_f32 v20, v166, v46, v20
	v_fma_f32 v21, v167, v47, v21
	v_fma_f32 v20, v168, v52, v20
	v_fma_f32 v21, v169, v53, v21
	v_fma_f32 v20, v170, v50, v20
	v_fma_f32 v21, v171, v51, v21
	v_fma_f32 v20, v172, v56, v20
	v_fma_f32 v21, v173, v57, v21
	v_fma_f32 v20, v174, v54, v20
	v_fma_f32 v21, v175, v55, v21
	v_fma_f32 v20, v176, v60, v20
	v_fma_f32 v21, v177, v61, v21
	v_fma_f32 v20, v178, v58, v20
	v_fma_f32 v21, v179, v59, v21
	v_fma_f32 v20, v180, v64, v20
	v_fma_f32 v21, v181, v65, v21
	v_fma_f32 v20, v182, v62, v20
	v_fma_f32 v21, v183, v63, v21
	v_fma_f32 v20, v186, v68, v20
	v_fma_f32 v21, v187, v69, v21
	v_fma_f32 v20, v190, v66, v20
	v_fma_f32 v21, v191, v67, v21
	v_fma_f32 v214, v194, v72, v20
	v_fma_f32 v215, v195, v73, v21
	v_add_f32_e32 v20, v214, v215
	ds_bpermute_b32 v21, v238, v20
	s_waitcnt lgkmcnt(0)
	v_add_f32_e32 v20, v20, v21
	ds_bpermute_b32 v21, v239, v20
	s_waitcnt lgkmcnt(0)
	v_add_f32_e32 v20, v20, v21
	ds_bpermute_b32 v21, v240, v20
	s_waitcnt lgkmcnt(0)
	v_add_f32_e32 v20, v20, v21
	ds_bpermute_b32 v21, v241, v20
	s_waitcnt lgkmcnt(0)
	v_add_f32_e32 v20, v20, v21
	ds_bpermute_b32 v21, v242, v20
	s_waitcnt lgkmcnt(0)
	v_add_f32_e32 v20, v20, v21
	ds_bpermute_b32 v21, v243, v20
	s_and_saveexec_b64 s[0:1], s[2:3]
	s_cbranch_execz .LBB0_401
	s_add_i32 s4, s10, 0
	s_waitcnt lgkmcnt(0)
	v_add_f32_e32 v20, v20, v21
	v_mov_b32_e32 v21, s4
	ds_write_b32 v21, v20 offset:20
; template <int PH>
; __device__ __forceinline__ void run_phase(const Args& args, LAS unsigned char* lds) {
;     ...
;                         for (int k = 0; k < 8; ++k) { const int i = 8 * ch + k; if (i < 46) { const int q = p0 - 15 + i; float u0 = 0.f, u1 = 0.f;
;                             if (q >= 0 && q < L) { u0 = bflo(ca[k]) * __builtin_amdgcn_rcpf(1.0f + __expf(-bflo(cgt[k]))); u1 = bfhi(ca[k]) * __builtin_amdgcn_rcpf(1.0f + __expf(-bfhi(cgt[k]))); }
; #pragma unroll
;                             for (int o = 0; o < 16; ++o) { const int kk = i - o; if (kk >= 0 && kk <= 30) { a0[o] += w0[kk] * u0; a1[o] += w1[kk] * u1; } } } }
; #pragma unroll
;                         for (int k = 0; k < 8; ++k) { ca[k] = na[k]; cgt[k] = ng[k]; }
;                     }
;     ...
;                     float mean[16], rstd[16];
; #pragma unroll
;                     for (int o = 0; o < 16; ++o) { const float s = wave_sum(a0[o] + a1[o]); if (lane == 0) red[wave * 16 + o] = s; }
.LBB0_401:
	s_or_b64 exec, exec, s[0:1]
	v_fma_f32 v14, v188, v14, v198
	v_fma_f32 v15, v189, v15, v199
	v_fma_f32 v14, v130, v18, v14
	v_fma_f32 v15, v131, v19, v15
	v_fma_f32 v14, v132, v8, v14
	v_fma_f32 v15, v133, v9, v15
	v_fma_f32 v14, v134, v22, v14
	v_fma_f32 v15, v135, v23, v15
	v_fma_f32 v14, v136, v12, v14
	v_fma_f32 v15, v137, v13, v15
	v_fma_f32 v14, v138, v16, v14
	v_fma_f32 v15, v139, v17, v15
	v_fma_f32 v14, v140, v6, v14
	v_fma_f32 v15, v141, v7, v15
	v_fma_f32 v14, v142, v10, v14
	v_fma_f32 v15, v143, v11, v15
	v_fma_f32 v14, v144, v0, v14
	v_fma_f32 v15, v145, v1, v15
	v_fma_f32 v14, v146, v4, v14
	v_fma_f32 v15, v147, v5, v15
	v_fma_f32 v14, v148, v2, v14
	v_fma_f32 v15, v149, v3, v15
	v_fma_f32 v14, v150, v26, v14
	v_fma_f32 v15, v151, v27, v15
	v_fma_f32 v14, v152, v24, v14
	v_fma_f32 v15, v153, v25, v15
	v_fma_f32 v14, v154, v36, v14
	v_fma_f32 v15, v155, v37, v15
	v_fma_f32 v14, v156, v34, v14
	v_fma_f32 v15, v157, v35, v15
	v_fma_f32 v14, v158, v42, v14
	v_fma_f32 v15, v159, v43, v15
	v_fma_f32 v14, v160, v40, v14
	v_fma_f32 v15, v161, v41, v15
	v_fma_f32 v14, v162, v48, v14
	v_fma_f32 v15, v163, v49, v15
	v_fma_f32 v14, v164, v46, v14
	v_fma_f32 v15, v165, v47, v15
	v_fma_f32 v14, v166, v52, v14
	v_fma_f32 v15, v167, v53, v15
	v_fma_f32 v14, v168, v50, v14
	v_fma_f32 v15, v169, v51, v15
	v_fma_f32 v14, v170, v56, v14
	v_fma_f32 v15, v171, v57, v15
	v_fma_f32 v14, v172, v54, v14
	v_fma_f32 v15, v173, v55, v15
	v_fma_f32 v14, v174, v60, v14
	v_fma_f32 v15, v175, v61, v15
	v_fma_f32 v14, v176, v58, v14
	v_fma_f32 v15, v177, v59, v15
	v_fma_f32 v14, v178, v64, v14
	v_fma_f32 v15, v179, v65, v15
	v_fma_f32 v14, v180, v62, v14
	v_fma_f32 v15, v181, v63, v15
	v_fma_f32 v14, v182, v68, v14
	v_fma_f32 v15, v183, v69, v15
	v_fma_f32 v14, v186, v66, v14
	v_fma_f32 v15, v187, v67, v15
	v_fma_f32 v14, v190, v72, v14
	v_fma_f32 v15, v191, v73, v15
	v_fma_f32 v216, v194, v70, v14
	v_fma_f32 v217, v195, v71, v15
	v_add_f32_e32 v14, v216, v217
	ds_bpermute_b32 v15, v238, v14
	s_waitcnt lgkmcnt(0)
	v_add_f32_e32 v14, v14, v15
	ds_bpermute_b32 v15, v239, v14
	s_waitcnt lgkmcnt(0)
	v_add_f32_e32 v14, v14, v15
	ds_bpermute_b32 v15, v240, v14
	s_waitcnt lgkmcnt(0)
	v_add_f32_e32 v14, v14, v15
	ds_bpermute_b32 v15, v241, v14
	s_waitcnt lgkmcnt(0)
	v_add_f32_e32 v14, v14, v15
	ds_bpermute_b32 v15, v242, v14
	s_waitcnt lgkmcnt(0)
	v_add_f32_e32 v14, v14, v15
	ds_bpermute_b32 v15, v243, v14
	s_and_saveexec_b64 s[0:1], s[2:3]
	s_cbranch_execz .LBB0_403
	s_add_i32 s4, s10, 0
	s_waitcnt lgkmcnt(0)
	v_add_f32_e32 v14, v14, v15
	v_mov_b32_e32 v15, s4
	ds_write_b32 v15, v14 offset:24
.LBB0_403:
	s_or_b64 exec, exec, s[0:1]
	s_waitcnt lgkmcnt(0)
	v_fma_f32 v14, v188, v18, v198
	v_fma_f32 v15, v189, v19, v199
	v_fma_f32 v14, v130, v8, v14
	v_fma_f32 v15, v131, v9, v15
	v_fma_f32 v14, v132, v22, v14
	v_fma_f32 v15, v133, v23, v15
	v_fma_f32 v14, v134, v12, v14
	v_fma_f32 v15, v135, v13, v15
	v_fma_f32 v14, v136, v16, v14
	v_fma_f32 v15, v137, v17, v15
	v_fma_f32 v14, v138, v6, v14
	v_fma_f32 v15, v139, v7, v15
	v_fma_f32 v14, v140, v10, v14
	v_fma_f32 v15, v141, v11, v15
	v_fma_f32 v14, v142, v0, v14
	v_fma_f32 v15, v143, v1, v15
	v_fma_f32 v14, v144, v4, v14
	v_fma_f32 v15, v145, v5, v15
	v_fma_f32 v14, v146, v2, v14
	v_fma_f32 v15, v147, v3, v15
	v_fma_f32 v14, v148, v26, v14
	v_fma_f32 v15, v149, v27, v15
	v_fma_f32 v14, v150, v24, v14
	v_fma_f32 v15, v151, v25, v15
	v_fma_f32 v14, v152, v36, v14
	v_fma_f32 v15, v153, v37, v15
	v_fma_f32 v14, v154, v34, v14
	v_fma_f32 v15, v155, v35, v15
	v_fma_f32 v14, v156, v42, v14
	v_fma_f32 v15, v157, v43, v15
	v_fma_f32 v14, v158, v40, v14
	v_fma_f32 v15, v159, v41, v15
	v_fma_f32 v14, v160, v48, v14
	v_fma_f32 v15, v161, v49, v15
	v_fma_f32 v14, v162, v46, v14
	v_fma_f32 v15, v163, v47, v15
	v_fma_f32 v14, v164, v52, v14
	v_fma_f32 v15, v165, v53, v15
	v_fma_f32 v14, v166, v50, v14
	v_fma_f32 v15, v167, v51, v15
	v_fma_f32 v14, v168, v56, v14
	v_fma_f32 v15, v169, v57, v15
	v_fma_f32 v14, v170, v54, v14
	v_fma_f32 v15, v171, v55, v15
	v_fma_f32 v14, v172, v60, v14
	v_fma_f32 v15, v173, v61, v15
	v_fma_f32 v14, v174, v58, v14
	v_fma_f32 v15, v175, v59, v15
	v_fma_f32 v14, v176, v64, v14
	v_fma_f32 v15, v177, v65, v15
	v_fma_f32 v14, v178, v62, v14
	v_fma_f32 v15, v179, v63, v15
	v_fma_f32 v14, v180, v68, v14
	v_fma_f32 v15, v181, v69, v15
	v_fma_f32 v14, v182, v66, v14
	v_fma_f32 v15, v183, v67, v15
	v_fma_f32 v14, v186, v72, v14
	v_fma_f32 v15, v187, v73, v15
	v_fma_f32 v14, v190, v70, v14
	v_fma_f32 v15, v191, v71, v15
	v_fma_f32 v218, v194, v76, v14
	v_fma_f32 v219, v195, v77, v15
	v_add_f32_e32 v14, v218, v219
	ds_bpermute_b32 v15, v238, v14
	s_waitcnt lgkmcnt(0)
	v_add_f32_e32 v14, v14, v15
	ds_bpermute_b32 v15, v239, v14
	s_waitcnt lgkmcnt(0)
	v_add_f32_e32 v14, v14, v15
	ds_bpermute_b32 v15, v240, v14
	s_waitcnt lgkmcnt(0)
	v_add_f32_e32 v14, v14, v15
	ds_bpermute_b32 v15, v241, v14
	s_waitcnt lgkmcnt(0)
	v_add_f32_e32 v14, v14, v15
	ds_bpermute_b32 v15, v242, v14
	s_waitcnt lgkmcnt(0)
	v_add_f32_e32 v14, v14, v15
	ds_bpermute_b32 v15, v243, v14
	s_and_saveexec_b64 s[0:1], s[2:3]
	s_cbranch_execz .LBB0_405
	s_add_i32 s4, s10, 0
	s_waitcnt lgkmcnt(0)
	v_add_f32_e32 v14, v14, v15
	v_mov_b32_e32 v15, s4
	ds_write_b32 v15, v14 offset:28
; template <int PH>
; __device__ __forceinline__ void run_phase(const Args& args, LAS unsigned char* lds) {
;     ...
;                         for (int k = 0; k < 8; ++k) { const int i = 8 * ch + k; if (i < 46) { const int q = p0 - 15 + i; float u0 = 0.f, u1 = 0.f;
;                             if (q >= 0 && q < L) { u0 = bflo(ca[k]) * __builtin_amdgcn_rcpf(1.0f + __expf(-bflo(cgt[k]))); u1 = bfhi(ca[k]) * __builtin_amdgcn_rcpf(1.0f + __expf(-bfhi(cgt[k]))); }
; #pragma unroll
;                             for (int o = 0; o < 16; ++o) { const int kk = i - o; if (kk >= 0 && kk <= 30) { a0[o] += w0[kk] * u0; a1[o] += w1[kk] * u1; } } } }
; #pragma unroll
;                         for (int k = 0; k < 8; ++k) { ca[k] = na[k]; cgt[k] = ng[k]; }
;                     }
;     ...
;                     float mean[16], rstd[16];
; #pragma unroll
;                     for (int o = 0; o < 16; ++o) { const float s = wave_sum(a0[o] + a1[o]); if (lane == 0) red[wave * 16 + o] = s; }
.LBB0_405:
	s_or_b64 exec, exec, s[0:1]
	v_fma_f32 v8, v188, v8, v198
	v_fma_f32 v9, v189, v9, v199
	v_fma_f32 v8, v130, v22, v8
	v_fma_f32 v9, v131, v23, v9
	v_fma_f32 v8, v132, v12, v8
	v_fma_f32 v9, v133, v13, v9
	v_fma_f32 v8, v134, v16, v8
	v_fma_f32 v9, v135, v17, v9
	v_fma_f32 v8, v136, v6, v8
	v_fma_f32 v9, v137, v7, v9
	v_fma_f32 v8, v138, v10, v8
	v_fma_f32 v9, v139, v11, v9
	v_fma_f32 v8, v140, v0, v8
	v_fma_f32 v9, v141, v1, v9
	v_fma_f32 v8, v142, v4, v8
	v_fma_f32 v9, v143, v5, v9
	v_fma_f32 v8, v144, v2, v8
	v_fma_f32 v9, v145, v3, v9
	v_fma_f32 v8, v146, v26, v8
	v_fma_f32 v9, v147, v27, v9
	v_fma_f32 v8, v148, v24, v8
	v_fma_f32 v9, v149, v25, v9
	v_fma_f32 v8, v150, v36, v8
	v_fma_f32 v9, v151, v37, v9
	v_fma_f32 v8, v152, v34, v8
	v_fma_f32 v9, v153, v35, v9
	v_fma_f32 v8, v154, v42, v8
	v_fma_f32 v9, v155, v43, v9
	v_fma_f32 v8, v156, v40, v8
	v_fma_f32 v9, v157, v41, v9
	v_fma_f32 v8, v158, v48, v8
	v_fma_f32 v9, v159, v49, v9
	v_fma_f32 v8, v160, v46, v8
	v_fma_f32 v9, v161, v47, v9
	v_fma_f32 v8, v162, v52, v8
	v_fma_f32 v9, v163, v53, v9
	v_fma_f32 v8, v164, v50, v8
	v_fma_f32 v9, v165, v51, v9
	v_fma_f32 v8, v166, v56, v8
	v_fma_f32 v9, v167, v57, v9
	v_fma_f32 v8, v168, v54, v8
	v_fma_f32 v9, v169, v55, v9
	v_fma_f32 v8, v170, v60, v8
	v_fma_f32 v9, v171, v61, v9
	v_fma_f32 v8, v172, v58, v8
	v_fma_f32 v9, v173, v59, v9
	v_fma_f32 v8, v174, v64, v8
	v_fma_f32 v9, v175, v65, v9
	v_fma_f32 v8, v176, v62, v8
	v_fma_f32 v9, v177, v63, v9
	v_fma_f32 v8, v178, v68, v8
	v_fma_f32 v9, v179, v69, v9
	v_fma_f32 v8, v180, v66, v8
	v_fma_f32 v9, v181, v67, v9
	v_fma_f32 v8, v182, v72, v8
	v_fma_f32 v9, v183, v73, v9
	v_fma_f32 v8, v186, v70, v8
	v_fma_f32 v9, v187, v71, v9
	v_fma_f32 v8, v190, v76, v8
	v_fma_f32 v9, v191, v77, v9
	v_fma_f32 v220, v194, v74, v8
	v_fma_f32 v221, v195, v75, v9
	v_add_f32_e32 v8, v220, v221
	ds_bpermute_b32 v9, v238, v8
	s_waitcnt lgkmcnt(0)
	v_add_f32_e32 v8, v8, v9
	ds_bpermute_b32 v9, v239, v8
	s_waitcnt lgkmcnt(0)
	v_add_f32_e32 v8, v8, v9
	ds_bpermute_b32 v9, v240, v8
	s_waitcnt lgkmcnt(0)
	v_add_f32_e32 v8, v8, v9
	ds_bpermute_b32 v9, v241, v8
	s_waitcnt lgkmcnt(0)
	v_add_f32_e32 v8, v8, v9
	ds_bpermute_b32 v9, v242, v8
	s_waitcnt lgkmcnt(0)
	v_add_f32_e32 v8, v8, v9
	ds_bpermute_b32 v9, v243, v8
	s_and_saveexec_b64 s[0:1], s[2:3]
	s_cbranch_execz .LBB0_407
	s_add_i32 s4, s10, 0
	s_waitcnt lgkmcnt(0)
	v_add_f32_e32 v8, v8, v9
	v_mov_b32_e32 v9, s4
	ds_write_b32 v9, v8 offset:32
.LBB0_407:
	s_or_b64 exec, exec, s[0:1]
	s_waitcnt lgkmcnt(0)
	v_fma_f32 v8, v188, v22, v198
	v_fma_f32 v9, v189, v23, v199
	v_fma_f32 v8, v130, v12, v8
	v_fma_f32 v9, v131, v13, v9
	v_fma_f32 v8, v132, v16, v8
	v_fma_f32 v9, v133, v17, v9
	v_fma_f32 v8, v134, v6, v8
	v_fma_f32 v9, v135, v7, v9
	v_fma_f32 v8, v136, v10, v8
	v_fma_f32 v9, v137, v11, v9
	v_fma_f32 v8, v138, v0, v8
	v_fma_f32 v9, v139, v1, v9
	v_fma_f32 v8, v140, v4, v8
	v_fma_f32 v9, v141, v5, v9
	v_fma_f32 v8, v142, v2, v8
	v_fma_f32 v9, v143, v3, v9
	v_fma_f32 v8, v144, v26, v8
	v_fma_f32 v9, v145, v27, v9
	v_fma_f32 v8, v146, v24, v8
	v_fma_f32 v9, v147, v25, v9
	v_fma_f32 v8, v148, v36, v8
	v_fma_f32 v9, v149, v37, v9
	v_fma_f32 v8, v150, v34, v8
	v_fma_f32 v9, v151, v35, v9
	v_fma_f32 v8, v152, v42, v8
	v_fma_f32 v9, v153, v43, v9
	v_fma_f32 v8, v154, v40, v8
	v_fma_f32 v9, v155, v41, v9
	v_fma_f32 v8, v156, v48, v8
	v_fma_f32 v9, v157, v49, v9
	v_fma_f32 v8, v158, v46, v8
	v_fma_f32 v9, v159, v47, v9
	v_fma_f32 v8, v160, v52, v8
	v_fma_f32 v9, v161, v53, v9
	v_fma_f32 v8, v162, v50, v8
	v_fma_f32 v9, v163, v51, v9
	v_fma_f32 v8, v164, v56, v8
	v_fma_f32 v9, v165, v57, v9
	v_fma_f32 v8, v166, v54, v8
	v_fma_f32 v9, v167, v55, v9
	v_fma_f32 v8, v168, v60, v8
	v_fma_f32 v9, v169, v61, v9
	v_fma_f32 v8, v170, v58, v8
	v_fma_f32 v9, v171, v59, v9
	v_fma_f32 v8, v172, v64, v8
	v_fma_f32 v9, v173, v65, v9
	v_fma_f32 v8, v174, v62, v8
	v_fma_f32 v9, v175, v63, v9
	v_fma_f32 v8, v176, v68, v8
	v_fma_f32 v9, v177, v69, v9
	v_fma_f32 v8, v178, v66, v8
	v_fma_f32 v9, v179, v67, v9
	v_fma_f32 v8, v180, v72, v8
	v_fma_f32 v9, v181, v73, v9
	v_fma_f32 v8, v182, v70, v8
	v_fma_f32 v9, v183, v71, v9
	v_fma_f32 v8, v186, v76, v8
	v_fma_f32 v9, v187, v77, v9
	v_fma_f32 v8, v190, v74, v8
	v_fma_f32 v9, v191, v75, v9
	v_fma_f32 v222, v194, v80, v8
	v_fma_f32 v223, v195, v81, v9
	v_add_f32_e32 v8, v222, v223
	ds_bpermute_b32 v9, v238, v8
	s_waitcnt lgkmcnt(0)
	v_add_f32_e32 v8, v8, v9
	ds_bpermute_b32 v9, v239, v8
	s_waitcnt lgkmcnt(0)
	v_add_f32_e32 v8, v8, v9
	ds_bpermute_b32 v9, v240, v8
	s_waitcnt lgkmcnt(0)
	v_add_f32_e32 v8, v8, v9
	ds_bpermute_b32 v9, v241, v8
	s_waitcnt lgkmcnt(0)
	v_add_f32_e32 v8, v8, v9
	ds_bpermute_b32 v9, v242, v8
	s_waitcnt lgkmcnt(0)
	v_add_f32_e32 v8, v8, v9
	ds_bpermute_b32 v9, v243, v8
	s_and_saveexec_b64 s[0:1], s[2:3]
	s_cbranch_execz .LBB0_409
	s_add_i32 s4, s10, 0
	s_waitcnt lgkmcnt(0)
	v_add_f32_e32 v8, v8, v9
	v_mov_b32_e32 v9, s4
	ds_write_b32 v9, v8 offset:36
; template <int PH>
; __device__ __forceinline__ void run_phase(const Args& args, LAS unsigned char* lds) {
;     ...
;                         for (int k = 0; k < 8; ++k) { const int i = 8 * ch + k; if (i < 46) { const int q = p0 - 15 + i; float u0 = 0.f, u1 = 0.f;
;                             if (q >= 0 && q < L) { u0 = bflo(ca[k]) * __builtin_amdgcn_rcpf(1.0f + __expf(-bflo(cgt[k]))); u1 = bfhi(ca[k]) * __builtin_amdgcn_rcpf(1.0f + __expf(-bfhi(cgt[k]))); }
; #pragma unroll
;                             for (int o = 0; o < 16; ++o) { const int kk = i - o; if (kk >= 0 && kk <= 30) { a0[o] += w0[kk] * u0; a1[o] += w1[kk] * u1; } } } }
; #pragma unroll
;                         for (int k = 0; k < 8; ++k) { ca[k] = na[k]; cgt[k] = ng[k]; }
;                     }
;     ...
;                     float mean[16], rstd[16];
; #pragma unroll
;                     for (int o = 0; o < 16; ++o) { const float s = wave_sum(a0[o] + a1[o]); if (lane == 0) red[wave * 16 + o] = s; }
.LBB0_409:
	s_or_b64 exec, exec, s[0:1]
	s_waitcnt lgkmcnt(0)
	v_fma_f32 v8, v188, v12, v198
	v_fma_f32 v9, v189, v13, v199
	v_fma_f32 v8, v130, v16, v8
	v_fma_f32 v9, v131, v17, v9
	v_fma_f32 v8, v132, v6, v8
	v_fma_f32 v9, v133, v7, v9
	v_fma_f32 v8, v134, v10, v8
	v_fma_f32 v9, v135, v11, v9
	v_fma_f32 v8, v136, v0, v8
	v_fma_f32 v9, v137, v1, v9
	v_fma_f32 v8, v138, v4, v8
	v_fma_f32 v9, v139, v5, v9
	v_fma_f32 v8, v140, v2, v8
	v_fma_f32 v9, v141, v3, v9
	v_fma_f32 v8, v142, v26, v8
	v_fma_f32 v9, v143, v27, v9
	v_fma_f32 v8, v144, v24, v8
	v_fma_f32 v9, v145, v25, v9
	v_fma_f32 v8, v146, v36, v8
	v_fma_f32 v9, v147, v37, v9
	v_fma_f32 v8, v148, v34, v8
	v_fma_f32 v9, v149, v35, v9
	v_fma_f32 v8, v150, v42, v8
	v_fma_f32 v9, v151, v43, v9
	v_fma_f32 v8, v152, v40, v8
	v_fma_f32 v9, v153, v41, v9
	v_fma_f32 v8, v154, v48, v8
	v_fma_f32 v9, v155, v49, v9
	v_fma_f32 v8, v156, v46, v8
	v_fma_f32 v9, v157, v47, v9
	v_fma_f32 v8, v158, v52, v8
	v_fma_f32 v9, v159, v53, v9
	v_fma_f32 v8, v160, v50, v8
	v_fma_f32 v9, v161, v51, v9
	v_fma_f32 v8, v162, v56, v8
	v_fma_f32 v9, v163, v57, v9
	v_fma_f32 v8, v164, v54, v8
	v_fma_f32 v9, v165, v55, v9
	v_fma_f32 v8, v166, v60, v8
	v_fma_f32 v9, v167, v61, v9
	v_fma_f32 v8, v168, v58, v8
	v_fma_f32 v9, v169, v59, v9
	v_fma_f32 v8, v170, v64, v8
	v_fma_f32 v9, v171, v65, v9
	v_fma_f32 v8, v172, v62, v8
	v_fma_f32 v9, v173, v63, v9
	v_fma_f32 v8, v174, v68, v8
	v_fma_f32 v9, v175, v69, v9
	v_fma_f32 v8, v176, v66, v8
	v_fma_f32 v9, v177, v67, v9
	v_fma_f32 v8, v178, v72, v8
	v_fma_f32 v9, v179, v73, v9
	v_fma_f32 v8, v180, v70, v8
	v_fma_f32 v9, v181, v71, v9
	v_fma_f32 v8, v182, v76, v8
	v_fma_f32 v9, v183, v77, v9
	v_fma_f32 v8, v186, v74, v8
	v_fma_f32 v9, v187, v75, v9
	v_fma_f32 v8, v190, v80, v8
	v_fma_f32 v9, v191, v81, v9
	v_fma_f32 v224, v194, v78, v8
	v_fma_f32 v225, v195, v79, v9
	v_add_f32_e32 v8, v224, v225
	ds_bpermute_b32 v9, v238, v8
	s_waitcnt lgkmcnt(0)
	v_add_f32_e32 v8, v8, v9
	ds_bpermute_b32 v9, v239, v8
	s_waitcnt lgkmcnt(0)
	v_add_f32_e32 v8, v8, v9
	ds_bpermute_b32 v9, v240, v8
	s_waitcnt lgkmcnt(0)
	v_add_f32_e32 v8, v8, v9
	ds_bpermute_b32 v9, v241, v8
	s_waitcnt lgkmcnt(0)
	v_add_f32_e32 v8, v8, v9
	ds_bpermute_b32 v9, v242, v8
	s_waitcnt lgkmcnt(0)
	v_add_f32_e32 v8, v8, v9
	ds_bpermute_b32 v9, v243, v8
	s_and_saveexec_b64 s[0:1], s[2:3]
	s_cbranch_execz .LBB0_411
	s_add_i32 s4, s10, 0
	s_waitcnt lgkmcnt(0)
	v_add_f32_e32 v8, v8, v9
	v_mov_b32_e32 v9, s4
	ds_write_b32 v9, v8 offset:40
.LBB0_411:
	s_or_b64 exec, exec, s[0:1]
	s_waitcnt lgkmcnt(0)
	v_fma_f32 v8, v188, v16, v198
	v_fma_f32 v9, v189, v17, v199
	v_fma_f32 v8, v130, v6, v8
	v_fma_f32 v9, v131, v7, v9
	v_fma_f32 v8, v132, v10, v8
	v_fma_f32 v9, v133, v11, v9
	v_fma_f32 v8, v134, v0, v8
	v_fma_f32 v9, v135, v1, v9
	v_fma_f32 v8, v136, v4, v8
	v_fma_f32 v9, v137, v5, v9
	v_fma_f32 v8, v138, v2, v8
	v_fma_f32 v9, v139, v3, v9
	v_fma_f32 v8, v140, v26, v8
	v_fma_f32 v9, v141, v27, v9
	v_fma_f32 v8, v142, v24, v8
	v_fma_f32 v9, v143, v25, v9
	v_fma_f32 v8, v144, v36, v8
	v_fma_f32 v9, v145, v37, v9
	v_fma_f32 v8, v146, v34, v8
	v_fma_f32 v9, v147, v35, v9
	v_fma_f32 v8, v148, v42, v8
	v_fma_f32 v9, v149, v43, v9
	v_fma_f32 v8, v150, v40, v8
	v_fma_f32 v9, v151, v41, v9
	v_fma_f32 v8, v152, v48, v8
	v_fma_f32 v9, v153, v49, v9
	v_fma_f32 v8, v154, v46, v8
	v_fma_f32 v9, v155, v47, v9
	v_fma_f32 v8, v156, v52, v8
	v_fma_f32 v9, v157, v53, v9
	v_fma_f32 v8, v158, v50, v8
	v_fma_f32 v9, v159, v51, v9
	v_fma_f32 v8, v160, v56, v8
	v_fma_f32 v9, v161, v57, v9
	v_fma_f32 v8, v162, v54, v8
	v_fma_f32 v9, v163, v55, v9
	v_fma_f32 v8, v164, v60, v8
	v_fma_f32 v9, v165, v61, v9
	v_fma_f32 v8, v166, v58, v8
	v_fma_f32 v9, v167, v59, v9
	v_fma_f32 v8, v168, v64, v8
	v_fma_f32 v9, v169, v65, v9
	v_fma_f32 v8, v170, v62, v8
	v_fma_f32 v9, v171, v63, v9
	v_fma_f32 v8, v172, v68, v8
	v_fma_f32 v9, v173, v69, v9
	v_fma_f32 v8, v174, v66, v8
	v_fma_f32 v9, v175, v67, v9
	v_fma_f32 v8, v176, v72, v8
	v_fma_f32 v9, v177, v73, v9
	v_fma_f32 v8, v178, v70, v8
	v_fma_f32 v9, v179, v71, v9
	v_fma_f32 v8, v180, v76, v8
	v_fma_f32 v9, v181, v77, v9
	v_fma_f32 v8, v182, v74, v8
	v_fma_f32 v9, v183, v75, v9
	v_fma_f32 v8, v186, v80, v8
	v_fma_f32 v9, v187, v81, v9
	v_fma_f32 v8, v190, v78, v8
	v_fma_f32 v9, v191, v79, v9
	v_fma_f32 v226, v194, v84, v8
	v_fma_f32 v227, v195, v85, v9
	v_add_f32_e32 v8, v226, v227
	ds_bpermute_b32 v9, v238, v8
	s_waitcnt lgkmcnt(0)
	v_add_f32_e32 v8, v8, v9
	ds_bpermute_b32 v9, v239, v8
	s_waitcnt lgkmcnt(0)
	v_add_f32_e32 v8, v8, v9
	ds_bpermute_b32 v9, v240, v8
	s_waitcnt lgkmcnt(0)
	v_add_f32_e32 v8, v8, v9
	ds_bpermute_b32 v9, v241, v8
	s_waitcnt lgkmcnt(0)
	v_add_f32_e32 v8, v8, v9
	ds_bpermute_b32 v9, v242, v8
	s_waitcnt lgkmcnt(0)
	v_add_f32_e32 v8, v8, v9
	ds_bpermute_b32 v9, v243, v8
	s_and_saveexec_b64 s[0:1], s[2:3]
	s_cbranch_execz .LBB0_413
	s_add_i32 s4, s10, 0
	s_waitcnt lgkmcnt(0)
	v_add_f32_e32 v8, v8, v9
	v_mov_b32_e32 v9, s4
	ds_write_b32 v9, v8 offset:44
; template <int PH>
; __device__ __forceinline__ void run_phase(const Args& args, LAS unsigned char* lds) {
;     ...
;                         for (int k = 0; k < 8; ++k) { const int i = 8 * ch + k; if (i < 46) { const int q = p0 - 15 + i; float u0 = 0.f, u1 = 0.f;
;                             if (q >= 0 && q < L) { u0 = bflo(ca[k]) * __builtin_amdgcn_rcpf(1.0f + __expf(-bflo(cgt[k]))); u1 = bfhi(ca[k]) * __builtin_amdgcn_rcpf(1.0f + __expf(-bfhi(cgt[k]))); }
; #pragma unroll
;                             for (int o = 0; o < 16; ++o) { const int kk = i - o; if (kk >= 0 && kk <= 30) { a0[o] += w0[kk] * u0; a1[o] += w1[kk] * u1; } } } }
; #pragma unroll
;                         for (int k = 0; k < 8; ++k) { ca[k] = na[k]; cgt[k] = ng[k]; }
;                     }
;     ...
;                     float mean[16], rstd[16];
; #pragma unroll
;                     for (int o = 0; o < 16; ++o) { const float s = wave_sum(a0[o] + a1[o]); if (lane == 0) red[wave * 16 + o] = s; }
.LBB0_413:
	s_or_b64 exec, exec, s[0:1]
	v_fma_f32 v6, v188, v6, v198
	v_fma_f32 v7, v189, v7, v199
	v_fma_f32 v6, v130, v10, v6
	v_fma_f32 v7, v131, v11, v7
	v_fma_f32 v6, v132, v0, v6
	v_fma_f32 v7, v133, v1, v7
	v_fma_f32 v6, v134, v4, v6
	v_fma_f32 v7, v135, v5, v7
	v_fma_f32 v6, v136, v2, v6
	v_fma_f32 v7, v137, v3, v7
	v_fma_f32 v6, v138, v26, v6
	v_fma_f32 v7, v139, v27, v7
	v_fma_f32 v6, v140, v24, v6
	v_fma_f32 v7, v141, v25, v7
	v_fma_f32 v6, v142, v36, v6
	v_fma_f32 v7, v143, v37, v7
	v_fma_f32 v6, v144, v34, v6
	v_fma_f32 v7, v145, v35, v7
	v_fma_f32 v6, v146, v42, v6
	v_fma_f32 v7, v147, v43, v7
	v_fma_f32 v6, v148, v40, v6
	v_fma_f32 v7, v149, v41, v7
	v_fma_f32 v6, v150, v48, v6
	v_fma_f32 v7, v151, v49, v7
	v_fma_f32 v6, v152, v46, v6
	v_fma_f32 v7, v153, v47, v7
	v_fma_f32 v6, v154, v52, v6
	v_fma_f32 v7, v155, v53, v7
	v_fma_f32 v6, v156, v50, v6
	v_fma_f32 v7, v157, v51, v7
	v_fma_f32 v6, v158, v56, v6
	v_fma_f32 v7, v159, v57, v7
	v_fma_f32 v6, v160, v54, v6
	v_fma_f32 v7, v161, v55, v7
	v_fma_f32 v6, v162, v60, v6
	v_fma_f32 v7, v163, v61, v7
	v_fma_f32 v6, v164, v58, v6
	v_fma_f32 v7, v165, v59, v7
	v_fma_f32 v6, v166, v64, v6
	v_fma_f32 v7, v167, v65, v7
	v_fma_f32 v6, v168, v62, v6
	v_fma_f32 v7, v169, v63, v7
	v_fma_f32 v6, v170, v68, v6
	v_fma_f32 v7, v171, v69, v7
	v_fma_f32 v6, v172, v66, v6
	v_fma_f32 v7, v173, v67, v7
	v_fma_f32 v6, v174, v72, v6
	v_fma_f32 v7, v175, v73, v7
	v_fma_f32 v6, v176, v70, v6
	v_fma_f32 v7, v177, v71, v7
	v_fma_f32 v6, v178, v76, v6
	v_fma_f32 v7, v179, v77, v7
	v_fma_f32 v6, v180, v74, v6
	v_fma_f32 v7, v181, v75, v7
	v_fma_f32 v6, v182, v80, v6
	v_fma_f32 v7, v183, v81, v7
	v_fma_f32 v6, v186, v78, v6
	v_fma_f32 v7, v187, v79, v7
	v_fma_f32 v6, v190, v84, v6
	v_fma_f32 v7, v191, v85, v7
	v_fma_f32 v228, v194, v82, v6
	v_fma_f32 v229, v195, v83, v7
	v_add_f32_e32 v6, v228, v229
	ds_bpermute_b32 v7, v238, v6
	s_waitcnt lgkmcnt(0)
	v_add_f32_e32 v6, v6, v7
	ds_bpermute_b32 v7, v239, v6
	s_waitcnt lgkmcnt(0)
	v_add_f32_e32 v6, v6, v7
	ds_bpermute_b32 v7, v240, v6
	s_waitcnt lgkmcnt(0)
	v_add_f32_e32 v6, v6, v7
	ds_bpermute_b32 v7, v241, v6
	s_waitcnt lgkmcnt(0)
	v_add_f32_e32 v6, v6, v7
	ds_bpermute_b32 v7, v242, v6
	s_waitcnt lgkmcnt(0)
	v_add_f32_e32 v6, v6, v7
	ds_bpermute_b32 v7, v243, v6
	s_and_saveexec_b64 s[0:1], s[2:3]
	s_cbranch_execz .LBB0_415
	s_add_i32 s4, s10, 0
	s_waitcnt lgkmcnt(0)
	v_add_f32_e32 v6, v6, v7
	v_mov_b32_e32 v7, s4
	ds_write_b32 v7, v6 offset:48
.LBB0_415:
	s_or_b64 exec, exec, s[0:1]
	s_waitcnt lgkmcnt(0)
	v_fma_f32 v6, v188, v10, v198
	v_fma_f32 v7, v189, v11, v199
	v_fma_f32 v6, v130, v0, v6
	v_fma_f32 v7, v131, v1, v7
	v_fma_f32 v6, v132, v4, v6
	v_fma_f32 v7, v133, v5, v7
	v_fma_f32 v6, v134, v2, v6
	v_fma_f32 v7, v135, v3, v7
	v_fma_f32 v6, v136, v26, v6
	v_fma_f32 v7, v137, v27, v7
	v_fma_f32 v6, v138, v24, v6
	v_fma_f32 v7, v139, v25, v7
	v_fma_f32 v6, v140, v36, v6
	v_fma_f32 v7, v141, v37, v7
	v_fma_f32 v6, v142, v34, v6
	v_fma_f32 v7, v143, v35, v7
	v_fma_f32 v6, v144, v42, v6
	v_fma_f32 v7, v145, v43, v7
	v_fma_f32 v6, v146, v40, v6
	v_fma_f32 v7, v147, v41, v7
	v_fma_f32 v6, v148, v48, v6
	v_fma_f32 v7, v149, v49, v7
	v_fma_f32 v6, v150, v46, v6
	v_fma_f32 v7, v151, v47, v7
	v_fma_f32 v6, v152, v52, v6
	v_fma_f32 v7, v153, v53, v7
	v_fma_f32 v6, v154, v50, v6
	v_fma_f32 v7, v155, v51, v7
	v_fma_f32 v6, v156, v56, v6
	v_fma_f32 v7, v157, v57, v7
	v_fma_f32 v6, v158, v54, v6
	v_fma_f32 v7, v159, v55, v7
	v_fma_f32 v6, v160, v60, v6
	v_fma_f32 v7, v161, v61, v7
	v_fma_f32 v6, v162, v58, v6
	v_fma_f32 v7, v163, v59, v7
	v_fma_f32 v6, v164, v64, v6
	v_fma_f32 v7, v165, v65, v7
	v_fma_f32 v6, v166, v62, v6
	v_fma_f32 v7, v167, v63, v7
	v_fma_f32 v6, v168, v68, v6
	v_fma_f32 v7, v169, v69, v7
	v_fma_f32 v6, v170, v66, v6
	v_fma_f32 v7, v171, v67, v7
	v_fma_f32 v6, v172, v72, v6
	v_fma_f32 v7, v173, v73, v7
	v_fma_f32 v6, v174, v70, v6
	v_fma_f32 v7, v175, v71, v7
	v_fma_f32 v6, v176, v76, v6
	v_fma_f32 v7, v177, v77, v7
	v_fma_f32 v6, v178, v74, v6
	v_fma_f32 v7, v179, v75, v7
	v_fma_f32 v6, v180, v80, v6
	v_fma_f32 v7, v181, v81, v7
	v_fma_f32 v6, v182, v78, v6
	v_fma_f32 v7, v183, v79, v7
	v_fma_f32 v6, v186, v84, v6
	v_fma_f32 v7, v187, v85, v7
	v_fma_f32 v6, v190, v82, v6
	v_fma_f32 v7, v191, v83, v7
	v_fma_f32 v230, v194, v88, v6
	v_fma_f32 v231, v195, v89, v7
	v_add_f32_e32 v6, v230, v231
	ds_bpermute_b32 v7, v238, v6
	s_waitcnt lgkmcnt(0)
	v_add_f32_e32 v6, v6, v7
	ds_bpermute_b32 v7, v239, v6
	s_waitcnt lgkmcnt(0)
	v_add_f32_e32 v6, v6, v7
	ds_bpermute_b32 v7, v240, v6
	s_waitcnt lgkmcnt(0)
	v_add_f32_e32 v6, v6, v7
	ds_bpermute_b32 v7, v241, v6
	s_waitcnt lgkmcnt(0)
	v_add_f32_e32 v6, v6, v7
	ds_bpermute_b32 v7, v242, v6
	s_waitcnt lgkmcnt(0)
	v_add_f32_e32 v6, v6, v7
	ds_bpermute_b32 v7, v243, v6
	s_and_saveexec_b64 s[0:1], s[2:3]
	s_cbranch_execz .LBB0_417
	s_add_i32 s4, s10, 0
	s_waitcnt lgkmcnt(0)
	v_add_f32_e32 v6, v6, v7
	v_mov_b32_e32 v7, s4
	ds_write_b32 v7, v6 offset:52
; template <int PH>
; __device__ __forceinline__ void run_phase(const Args& args, LAS unsigned char* lds) {
;     ...
;                         for (int k = 0; k < 8; ++k) { const int i = 8 * ch + k; if (i < 46) { const int q = p0 - 15 + i; float u0 = 0.f, u1 = 0.f;
;                             if (q >= 0 && q < L) { u0 = bflo(ca[k]) * __builtin_amdgcn_rcpf(1.0f + __expf(-bflo(cgt[k]))); u1 = bfhi(ca[k]) * __builtin_amdgcn_rcpf(1.0f + __expf(-bfhi(cgt[k]))); }
; #pragma unroll
;                             for (int o = 0; o < 16; ++o) { const int kk = i - o; if (kk >= 0 && kk <= 30) { a0[o] += w0[kk] * u0; a1[o] += w1[kk] * u1; } } } }
; #pragma unroll
;                         for (int k = 0; k < 8; ++k) { ca[k] = na[k]; cgt[k] = ng[k]; }
;                     }
;     ...
;                     float mean[16], rstd[16];
; #pragma unroll
;                     for (int o = 0; o < 16; ++o) { const float s = wave_sum(a0[o] + a1[o]); if (lane == 0) red[wave * 16 + o] = s; }
.LBB0_417:
	s_or_b64 exec, exec, s[0:1]
	v_fma_f32 v0, v188, v0, v198
	v_fma_f32 v1, v189, v1, v199
	v_fma_f32 v0, v130, v4, v0
	v_fma_f32 v1, v131, v5, v1
	v_fma_f32 v0, v132, v2, v0
	v_fma_f32 v1, v133, v3, v1
	v_fma_f32 v0, v134, v26, v0
	v_fma_f32 v1, v135, v27, v1
	v_fma_f32 v0, v136, v24, v0
	v_fma_f32 v1, v137, v25, v1
	v_fma_f32 v0, v138, v36, v0
	v_fma_f32 v1, v139, v37, v1
	v_fma_f32 v0, v140, v34, v0
	v_fma_f32 v1, v141, v35, v1
	v_fma_f32 v0, v142, v42, v0
	v_fma_f32 v1, v143, v43, v1
	v_fma_f32 v0, v144, v40, v0
	v_fma_f32 v1, v145, v41, v1
	v_fma_f32 v0, v146, v48, v0
	v_fma_f32 v1, v147, v49, v1
	v_fma_f32 v0, v148, v46, v0
	v_fma_f32 v1, v149, v47, v1
	v_fma_f32 v0, v150, v52, v0
	v_fma_f32 v1, v151, v53, v1
	v_fma_f32 v0, v152, v50, v0
	v_fma_f32 v1, v153, v51, v1
	v_fma_f32 v0, v154, v56, v0
	v_fma_f32 v1, v155, v57, v1
	v_fma_f32 v0, v156, v54, v0
	v_fma_f32 v1, v157, v55, v1
	v_fma_f32 v0, v158, v60, v0
	v_fma_f32 v1, v159, v61, v1
	v_fma_f32 v0, v160, v58, v0
	v_fma_f32 v1, v161, v59, v1
	v_fma_f32 v0, v162, v64, v0
	v_fma_f32 v1, v163, v65, v1
	v_fma_f32 v0, v164, v62, v0
	v_fma_f32 v1, v165, v63, v1
	v_fma_f32 v0, v166, v68, v0
	v_fma_f32 v1, v167, v69, v1
	v_fma_f32 v0, v168, v66, v0
	v_fma_f32 v1, v169, v67, v1
	v_fma_f32 v0, v170, v72, v0
	v_fma_f32 v1, v171, v73, v1
	v_fma_f32 v0, v172, v70, v0
	v_fma_f32 v1, v173, v71, v1
	v_fma_f32 v0, v174, v76, v0
	v_fma_f32 v1, v175, v77, v1
	v_fma_f32 v0, v176, v74, v0
	v_fma_f32 v1, v177, v75, v1
	v_fma_f32 v0, v178, v80, v0
	v_fma_f32 v1, v179, v81, v1
	v_fma_f32 v0, v180, v78, v0
	v_fma_f32 v1, v181, v79, v1
	v_fma_f32 v0, v182, v84, v0
	v_fma_f32 v1, v183, v85, v1
	v_fma_f32 v0, v186, v82, v0
	v_fma_f32 v1, v187, v83, v1
	v_fma_f32 v0, v190, v88, v0
	v_fma_f32 v1, v191, v89, v1
	v_fma_f32 v232, v194, v86, v0
	v_fma_f32 v233, v195, v87, v1
	v_add_f32_e32 v0, v232, v233
	ds_bpermute_b32 v1, v238, v0
	s_waitcnt lgkmcnt(0)
	v_add_f32_e32 v0, v0, v1
	ds_bpermute_b32 v1, v239, v0
	s_waitcnt lgkmcnt(0)
	v_add_f32_e32 v0, v0, v1
	ds_bpermute_b32 v1, v240, v0
	s_waitcnt lgkmcnt(0)
	v_add_f32_e32 v0, v0, v1
	ds_bpermute_b32 v1, v241, v0
	s_waitcnt lgkmcnt(0)
	v_add_f32_e32 v0, v0, v1
	ds_bpermute_b32 v1, v242, v0
	s_waitcnt lgkmcnt(0)
	v_add_f32_e32 v0, v0, v1
	ds_bpermute_b32 v1, v243, v0
	s_and_saveexec_b64 s[0:1], s[2:3]
	s_cbranch_execz .LBB0_419
	s_add_i32 s4, s10, 0
	s_waitcnt lgkmcnt(0)
	v_add_f32_e32 v0, v0, v1
	v_mov_b32_e32 v1, s4
	ds_write_b32 v1, v0 offset:56
.LBB0_419:
	s_or_b64 exec, exec, s[0:1]
	s_waitcnt lgkmcnt(0)
	v_fma_f32 v0, v188, v4, v198
	v_fma_f32 v1, v189, v5, v199
	v_fma_f32 v0, v130, v2, v0
	v_fma_f32 v1, v131, v3, v1
	v_fma_f32 v0, v132, v26, v0
	v_fma_f32 v1, v133, v27, v1
	v_fma_f32 v0, v134, v24, v0
	v_fma_f32 v1, v135, v25, v1
	v_fma_f32 v0, v136, v36, v0
	v_fma_f32 v1, v137, v37, v1
	v_fma_f32 v0, v138, v34, v0
	v_fma_f32 v1, v139, v35, v1
	v_fma_f32 v0, v140, v42, v0
	v_fma_f32 v1, v141, v43, v1
	v_fma_f32 v0, v142, v40, v0
	v_fma_f32 v1, v143, v41, v1
	v_fma_f32 v0, v144, v48, v0
	v_fma_f32 v1, v145, v49, v1
	v_fma_f32 v0, v146, v46, v0
	v_fma_f32 v1, v147, v47, v1
	v_fma_f32 v0, v148, v52, v0
	v_fma_f32 v1, v149, v53, v1
	v_fma_f32 v0, v150, v50, v0
	v_fma_f32 v1, v151, v51, v1
	v_fma_f32 v0, v152, v56, v0
	v_fma_f32 v1, v153, v57, v1
	v_fma_f32 v0, v154, v54, v0
	v_fma_f32 v1, v155, v55, v1
	v_fma_f32 v0, v156, v60, v0
	v_fma_f32 v1, v157, v61, v1
	v_fma_f32 v0, v158, v58, v0
	v_fma_f32 v1, v159, v59, v1
	v_fma_f32 v0, v160, v64, v0
	v_fma_f32 v1, v161, v65, v1
	v_fma_f32 v0, v162, v62, v0
	v_fma_f32 v1, v163, v63, v1
	v_fma_f32 v0, v164, v68, v0
	v_fma_f32 v1, v165, v69, v1
	v_fma_f32 v0, v166, v66, v0
	v_fma_f32 v1, v167, v67, v1
	v_fma_f32 v0, v168, v72, v0
	v_fma_f32 v1, v169, v73, v1
	v_fma_f32 v0, v170, v70, v0
	v_fma_f32 v1, v171, v71, v1
	v_fma_f32 v0, v172, v76, v0
	v_fma_f32 v1, v173, v77, v1
	v_fma_f32 v0, v174, v74, v0
	v_fma_f32 v1, v175, v75, v1
	v_fma_f32 v0, v176, v80, v0
	v_fma_f32 v1, v177, v81, v1
	v_fma_f32 v0, v178, v78, v0
	v_fma_f32 v1, v179, v79, v1
	v_fma_f32 v0, v180, v84, v0
	v_fma_f32 v1, v181, v85, v1
	v_fma_f32 v0, v182, v82, v0
	v_fma_f32 v1, v183, v83, v1
	v_fma_f32 v0, v186, v88, v0
	v_fma_f32 v1, v187, v89, v1
	v_fma_f32 v0, v190, v86, v0
	v_fma_f32 v1, v191, v87, v1
	v_fma_f32 v234, v194, v90, v0
	v_fma_f32 v235, v195, v91, v1
	v_add_f32_e32 v0, v234, v235
	ds_bpermute_b32 v1, v238, v0
	s_waitcnt lgkmcnt(0)
	v_add_f32_e32 v0, v0, v1
	ds_bpermute_b32 v1, v239, v0
	s_waitcnt lgkmcnt(0)
	v_add_f32_e32 v0, v0, v1
	ds_bpermute_b32 v1, v240, v0
	s_waitcnt lgkmcnt(0)
	v_add_f32_e32 v0, v0, v1
	ds_bpermute_b32 v1, v241, v0
	s_waitcnt lgkmcnt(0)
	v_add_f32_e32 v0, v0, v1
	ds_bpermute_b32 v1, v242, v0
	s_waitcnt lgkmcnt(0)
	v_add_f32_e32 v0, v0, v1
	ds_bpermute_b32 v1, v243, v0
	s_and_saveexec_b64 s[0:1], s[2:3]
	s_cbranch_execz .LBB0_421
	s_add_i32 s4, s10, 0
	s_waitcnt lgkmcnt(0)
	v_add_f32_e32 v0, v0, v1
	v_mov_b32_e32 v1, s4
	ds_write_b32 v1, v0 offset:60

; template <int PH>
; __device__ __forceinline__ void run_phase(const Args& args, LAS unsigned char* lds) {
;     ...
;                         for (int k = 0; k < 8; ++k) { const int i = 8 * ch + k; if (i < 46) { const int q = p0 - 15 + i; float u0 = 0.f, u1 = 0.f;
;                             if (q >= 0 && q < L) { u0 = bflo(ca[k]) * __builtin_amdgcn_rcpf(1.0f + __expf(-bflo(cgt[k]))); u1 = bfhi(ca[k]) * __builtin_amdgcn_rcpf(1.0f + __expf(-bfhi(cgt[k]))); }
.LBB0_454:
	s_waitcnt vmcnt(2)
	v_lshlrev_b32_e32 v86, 16, v91
	v_and_b32_e32 v87, 0xffff0000, v91
	v_mul_f32_e32 v86, 0xbfb8aa3b, v86
	v_mul_f32_e32 v87, 0xbfb8aa3b, v87
	v_exp_f32_e32 v86, v86
	v_exp_f32_e32 v87, v87
	v_lshlrev_b32_e32 v94, 16, v90
	v_and_b32_e32 v95, 0xffff0000, v90
	v_add_f32_e32 v86, 1.0, v86
	v_add_f32_e32 v87, 1.0, v87
	v_rcp_f32_e32 v86, v86
	v_rcp_f32_e32 v87, v87
	s_nop 0
	v_mul_f32_e32 v86, v86, v94
	v_mul_f32_e32 v87, v87, v95
	v_mov_b32_e32 v90, 0
	s_cmp_ge_u32 s1, s4
	v_mov_b32_e32 v91, 0
	s_cbranch_scc0 .LBB0_388
	s_branch .LBB0_389
